# GEMM DMA split 4,4 (instead of 5,3) with the static priority raise
# baseline (speedup 1.0000x reference)
.Lg24_np:
	s_add_u32 m0, s14, 0x8020
	s_add_u32 s12, s1, s4
	s_addc_u32 s13, s3, s5
	global_load_lds_dwordx4 v155, s[12:13]
	s_add_u32 m0, s14, 0xa020
	s_add_u32 s12, s12, 0x40000
	s_addc_u32 s13, s13, 0
	global_load_lds_dwordx4 v155, s[12:13]
	s_add_u32 m0, s14, 0xc020
	s_add_u32 s12, s12, 0x40000
	s_addc_u32 s13, s13, 0
	global_load_lds_dwordx4 v155, s[12:13]
	s_add_u32 m0, s14, 0xe020
	s_add_u32 s12, s12, 0x40000
	s_addc_u32 s13, s13, 0
	global_load_lds_dwordx4 v155, s[12:13]
	ds_read_b128 v[130:133], v177 offset:0
	ds_read_b128 v[164:167], v207 offset:0
	ds_read_b128 v[168:171], v207 offset:4096
	ds_read_b128 v[134:137], v177 offset:4096
	ds_read_b128 v[156:159], v177 offset:8192
	ds_read_b128 v[160:163], v177 offset:12288
.Lg24_loop:
	s_waitcnt lgkmcnt(4)
	v_mfma_f32_32x32x16_bf16 v[114:129], v[130:133], v[164:167], v[114:129]
	ds_read_b128 v[172:175], v204 offset:0
	s_waitcnt lgkmcnt(4)
	v_mfma_f32_32x32x16_bf16 v[98:113], v[130:133], v[168:171], v[98:113]
	ds_read_b128 v[192:195], v208 offset:0
	s_add_u32 m0, s14, 0x18020
	s_add_u32 s12, s9, s4
	s_addc_u32 s13, s10, s5
	global_load_lds_dwordx4 v155, s[12:13]
	s_waitcnt lgkmcnt(4)
	v_mfma_f32_32x32x16_bf16 v[82:97], v[134:137], v[164:167], v[82:97]
	ds_read_b128 v[200:203], v208 offset:4096
	v_mfma_f32_32x32x16_bf16 v[66:81], v[134:137], v[168:171], v[66:81]
	ds_read_b128 v[180:183], v204 offset:4096
	s_add_u32 m0, s14, 0x1a020
	s_add_u32 s12, s12, 0x40000
	s_addc_u32 s13, s13, 0
	global_load_lds_dwordx4 v155, s[12:13]
	s_waitcnt lgkmcnt(5)
	v_mfma_f32_32x32x16_bf16 v[50:65], v[156:159], v[164:167], v[50:65]
	ds_read_b128 v[184:187], v204 offset:8192
	v_mfma_f32_32x32x16_bf16 v[34:49], v[156:159], v[168:171], v[34:49]
	ds_read_b128 v[188:191], v204 offset:12288
	s_add_u32 m0, s14, 0x1c020
	s_add_u32 s12, s12, 0x40000
	s_addc_u32 s13, s13, 0
	global_load_lds_dwordx4 v155, s[12:13]
	s_waitcnt lgkmcnt(6)
	v_mfma_f32_32x32x16_bf16 v[18:33], v[160:163], v[164:167], v[18:33]
	v_mfma_f32_32x32x16_bf16 v[2:17], v[160:163], v[168:171], v[2:17]
	s_add_u32 m0, s14, 0x1e020
	s_add_u32 s12, s12, 0x40000
	s_addc_u32 s13, s13, 0
	global_load_lds_dwordx4 v155, s[12:13]
	s_add_u32 s4, s4, 0x80
	s_addc_u32 s5, s5, 0
	s_waitcnt lgkmcnt(4)
	v_mfma_f32_32x32x16_bf16 v[114:129], v[172:175], v[192:195], v[114:129]
	ds_read_b128 v[130:133], v205 offset:0
	s_waitcnt lgkmcnt(4)
	v_mfma_f32_32x32x16_bf16 v[98:113], v[172:175], v[200:203], v[98:113]
	ds_read_b128 v[164:167], v209 offset:0
	s_waitcnt lgkmcnt(4)
	v_mfma_f32_32x32x16_bf16 v[82:97], v[180:183], v[192:195], v[82:97]
	ds_read_b128 v[168:171], v209 offset:4096
	v_mfma_f32_32x32x16_bf16 v[66:81], v[180:183], v[200:203], v[66:81]
	ds_read_b128 v[134:137], v205 offset:4096
	s_waitcnt lgkmcnt(5)
	v_mfma_f32_32x32x16_bf16 v[50:65], v[184:187], v[192:195], v[50:65]
	ds_read_b128 v[156:159], v205 offset:8192
	v_mfma_f32_32x32x16_bf16 v[34:49], v[184:187], v[200:203], v[34:49]
	ds_read_b128 v[160:163], v205 offset:12288
	s_waitcnt lgkmcnt(6)
	v_mfma_f32_32x32x16_bf16 v[18:33], v[188:191], v[192:195], v[18:33]
	v_mfma_f32_32x32x16_bf16 v[2:17], v[188:191], v[200:203], v[2:17]
	s_waitcnt lgkmcnt(4)
	v_mfma_f32_32x32x16_bf16 v[114:129], v[130:133], v[164:167], v[114:129]
	ds_read_b128 v[172:175], v206 offset:0
	ds_read_b128 v[192:195], v210 offset:0
	s_waitcnt lgkmcnt(5)
	v_mfma_f32_32x32x16_bf16 v[98:113], v[130:133], v[168:171], v[98:113]
	ds_read_b128 v[200:203], v210 offset:4096
	ds_read_b128 v[180:183], v206 offset:4096
	s_waitcnt lgkmcnt(6)
	v_mfma_f32_32x32x16_bf16 v[82:97], v[134:137], v[164:167], v[82:97]
	ds_read_b128 v[184:187], v206 offset:8192
	ds_read_b128 v[188:191], v206 offset:12288
	v_mfma_f32_32x32x16_bf16 v[66:81], v[134:137], v[168:171], v[66:81]
	s_waitcnt lgkmcnt(7)
	v_mfma_f32_32x32x16_bf16 v[50:65], v[156:159], v[164:167], v[50:65]
	v_mfma_f32_32x32x16_bf16 v[34:49], v[156:159], v[168:171], v[34:49]
	s_waitcnt lgkmcnt(6)
	v_mfma_f32_32x32x16_bf16 v[18:33], v[160:163], v[164:167], v[18:33]
	v_mfma_f32_32x32x16_bf16 v[2:17], v[160:163], v[168:171], v[2:17]
	s_waitcnt vmcnt(0) lgkmcnt(0)
	s_barrier
	v_mfma_f32_32x32x16_bf16 v[114:129], v[172:175], v[192:195], v[114:129]
	ds_read_b128 v[130:133], v177 offset:32768
	v_mfma_f32_32x32x16_bf16 v[98:113], v[172:175], v[200:203], v[98:113]
	ds_read_b128 v[164:167], v207 offset:32768
	s_add_u32 m0, s14, 0x20
	s_add_u32 s12, s1, s4
	s_addc_u32 s13, s3, s5
	global_load_lds_dwordx4 v155, s[12:13]
	v_mfma_f32_32x32x16_bf16 v[82:97], v[180:183], v[192:195], v[82:97]
	ds_read_b128 v[168:171], v207 offset:36864
	v_mfma_f32_32x32x16_bf16 v[66:81], v[180:183], v[200:203], v[66:81]
	ds_read_b128 v[134:137], v177 offset:36864
	s_add_u32 m0, s14, 0x2020
	s_add_u32 s12, s12, 0x40000
	s_addc_u32 s13, s13, 0
	global_load_lds_dwordx4 v155, s[12:13]
	v_mfma_f32_32x32x16_bf16 v[50:65], v[184:187], v[192:195], v[50:65]
	ds_read_b128 v[156:159], v177 offset:40960
	v_mfma_f32_32x32x16_bf16 v[34:49], v[184:187], v[200:203], v[34:49]
	ds_read_b128 v[160:163], v177 offset:45056
	s_add_u32 m0, s14, 0x4020
	s_add_u32 s12, s12, 0x40000
	s_addc_u32 s13, s13, 0
	global_load_lds_dwordx4 v155, s[12:13]
	v_mfma_f32_32x32x16_bf16 v[18:33], v[188:191], v[192:195], v[18:33]
	v_mfma_f32_32x32x16_bf16 v[2:17], v[188:191], v[200:203], v[2:17]
	s_add_u32 m0, s14, 0x6020
	s_add_u32 s12, s12, 0x40000
	s_addc_u32 s13, s13, 0
	global_load_lds_dwordx4 v155, s[12:13]
	s_waitcnt lgkmcnt(4)
	v_mfma_f32_32x32x16_bf16 v[114:129], v[130:133], v[164:167], v[114:129]
	ds_read_b128 v[172:175], v204 offset:32768
	s_waitcnt lgkmcnt(4)
	v_mfma_f32_32x32x16_bf16 v[98:113], v[130:133], v[168:171], v[98:113]
	ds_read_b128 v[192:195], v208 offset:32768
	s_add_u32 m0, s14, 0x10020
	s_add_u32 s12, s9, s4
	s_addc_u32 s13, s10, s5
	global_load_lds_dwordx4 v155, s[12:13]
	s_waitcnt lgkmcnt(4)
	v_mfma_f32_32x32x16_bf16 v[82:97], v[134:137], v[164:167], v[82:97]
	ds_read_b128 v[200:203], v208 offset:36864
	v_mfma_f32_32x32x16_bf16 v[66:81], v[134:137], v[168:171], v[66:81]
	ds_read_b128 v[180:183], v204 offset:36864
	s_add_u32 m0, s14, 0x12020
	s_add_u32 s12, s12, 0x40000
	s_addc_u32 s13, s13, 0
	global_load_lds_dwordx4 v155, s[12:13]
	s_waitcnt lgkmcnt(5)
	v_mfma_f32_32x32x16_bf16 v[50:65], v[156:159], v[164:167], v[50:65]
	ds_read_b128 v[184:187], v204 offset:40960
	v_mfma_f32_32x32x16_bf16 v[34:49], v[156:159], v[168:171], v[34:49]
	ds_read_b128 v[188:191], v204 offset:45056
	s_add_u32 m0, s14, 0x14020
	s_add_u32 s12, s12, 0x40000
	s_addc_u32 s13, s13, 0
	global_load_lds_dwordx4 v155, s[12:13]
	s_waitcnt lgkmcnt(6)
	v_mfma_f32_32x32x16_bf16 v[18:33], v[160:163], v[164:167], v[18:33]
	v_mfma_f32_32x32x16_bf16 v[2:17], v[160:163], v[168:171], v[2:17]
	s_add_u32 m0, s14, 0x16020
	s_add_u32 s12, s12, 0x40000
	s_addc_u32 s13, s13, 0
	global_load_lds_dwordx4 v155, s[12:13]
	s_add_u32 s4, s4, 0x80
	s_addc_u32 s5, s5, 0
	s_waitcnt lgkmcnt(4)
	v_mfma_f32_32x32x16_bf16 v[114:129], v[172:175], v[192:195], v[114:129]
	ds_read_b128 v[130:133], v205 offset:32768
	s_waitcnt lgkmcnt(4)
	v_mfma_f32_32x32x16_bf16 v[98:113], v[172:175], v[200:203], v[98:113]
	ds_read_b128 v[164:167], v209 offset:32768
	s_waitcnt lgkmcnt(4)
	v_mfma_f32_32x32x16_bf16 v[82:97], v[180:183], v[192:195], v[82:97]
	ds_read_b128 v[168:171], v209 offset:36864
	v_mfma_f32_32x32x16_bf16 v[66:81], v[180:183], v[200:203], v[66:81]
	ds_read_b128 v[134:137], v205 offset:36864
	s_waitcnt lgkmcnt(5)
	v_mfma_f32_32x32x16_bf16 v[50:65], v[184:187], v[192:195], v[50:65]
	ds_read_b128 v[156:159], v205 offset:40960
	v_mfma_f32_32x32x16_bf16 v[34:49], v[184:187], v[200:203], v[34:49]
	ds_read_b128 v[160:163], v205 offset:45056
	s_waitcnt lgkmcnt(6)
	v_mfma_f32_32x32x16_bf16 v[18:33], v[188:191], v[192:195], v[18:33]
	v_mfma_f32_32x32x16_bf16 v[2:17], v[188:191], v[200:203], v[2:17]
	s_waitcnt lgkmcnt(4)
	v_mfma_f32_32x32x16_bf16 v[114:129], v[130:133], v[164:167], v[114:129]
	ds_read_b128 v[172:175], v206 offset:32768
	ds_read_b128 v[192:195], v210 offset:32768
	s_waitcnt lgkmcnt(5)
	v_mfma_f32_32x32x16_bf16 v[98:113], v[130:133], v[168:171], v[98:113]
	ds_read_b128 v[200:203], v210 offset:36864
	ds_read_b128 v[180:183], v206 offset:36864
	s_waitcnt lgkmcnt(6)
	v_mfma_f32_32x32x16_bf16 v[82:97], v[134:137], v[164:167], v[82:97]
	ds_read_b128 v[184:187], v206 offset:40960
	ds_read_b128 v[188:191], v206 offset:45056
	v_mfma_f32_32x32x16_bf16 v[66:81], v[134:137], v[168:171], v[66:81]
	s_waitcnt lgkmcnt(7)
	v_mfma_f32_32x32x16_bf16 v[50:65], v[156:159], v[164:167], v[50:65]
	v_mfma_f32_32x32x16_bf16 v[34:49], v[156:159], v[168:171], v[34:49]
	s_waitcnt lgkmcnt(6)
	v_mfma_f32_32x32x16_bf16 v[18:33], v[160:163], v[164:167], v[18:33]
	v_mfma_f32_32x32x16_bf16 v[2:17], v[160:163], v[168:171], v[2:17]
	s_waitcnt vmcnt(0) lgkmcnt(0)
	s_barrier
	v_mfma_f32_32x32x16_bf16 v[114:129], v[172:175], v[192:195], v[114:129]
	ds_read_b128 v[130:133], v177 offset:0
	v_mfma_f32_32x32x16_bf16 v[98:113], v[172:175], v[200:203], v[98:113]
	ds_read_b128 v[164:167], v207 offset:0
	s_add_u32 m0, s14, 0x8020
	s_add_u32 s12, s1, s4
	s_addc_u32 s13, s3, s5
	global_load_lds_dwordx4 v155, s[12:13]
	v_mfma_f32_32x32x16_bf16 v[82:97], v[180:183], v[192:195], v[82:97]
	ds_read_b128 v[168:171], v207 offset:4096
	v_mfma_f32_32x32x16_bf16 v[66:81], v[180:183], v[200:203], v[66:81]
	ds_read_b128 v[134:137], v177 offset:4096
	s_add_u32 m0, s14, 0xa020
	s_add_u32 s12, s12, 0x40000
	s_addc_u32 s13, s13, 0
	global_load_lds_dwordx4 v155, s[12:13]
	v_mfma_f32_32x32x16_bf16 v[50:65], v[184:187], v[192:195], v[50:65]
	ds_read_b128 v[156:159], v177 offset:8192
	v_mfma_f32_32x32x16_bf16 v[34:49], v[184:187], v[200:203], v[34:49]
	ds_read_b128 v[160:163], v177 offset:12288
	s_add_u32 m0, s14, 0xc020
	s_add_u32 s12, s12, 0x40000
	s_addc_u32 s13, s13, 0
	global_load_lds_dwordx4 v155, s[12:13]
	v_mfma_f32_32x32x16_bf16 v[18:33], v[188:191], v[192:195], v[18:33]
	v_mfma_f32_32x32x16_bf16 v[2:17], v[188:191], v[200:203], v[2:17]
	s_add_u32 m0, s14, 0xe020
	s_add_u32 s12, s12, 0x40000
	s_addc_u32 s13, s13, 0
	global_load_lds_dwordx4 v155, s[12:13]
	s_sub_u32 s11, s11, 1
	s_cmp_lg_u32 s11, 0
	s_cbranch_scc1 .Lg24_loop
	s_waitcnt lgkmcnt(4)
	v_mfma_f32_32x32x16_bf16 v[114:129], v[130:133], v[164:167], v[114:129]
	ds_read_b128 v[172:175], v204 offset:0
	s_waitcnt lgkmcnt(4)
	v_mfma_f32_32x32x16_bf16 v[98:113], v[130:133], v[168:171], v[98:113]
	ds_read_b128 v[192:195], v208 offset:0
	s_add_u32 m0, s14, 0x18020
	s_add_u32 s12, s9, s4
	s_addc_u32 s13, s10, s5
	global_load_lds_dwordx4 v155, s[12:13]
	s_waitcnt lgkmcnt(4)
	v_mfma_f32_32x32x16_bf16 v[82:97], v[134:137], v[164:167], v[82:97]
	ds_read_b128 v[200:203], v208 offset:4096
	v_mfma_f32_32x32x16_bf16 v[66:81], v[134:137], v[168:171], v[66:81]
	ds_read_b128 v[180:183], v204 offset:4096
	s_add_u32 m0, s14, 0x1a020
	s_add_u32 s12, s12, 0x40000
	s_addc_u32 s13, s13, 0
	global_load_lds_dwordx4 v155, s[12:13]
	s_waitcnt lgkmcnt(5)
	v_mfma_f32_32x32x16_bf16 v[50:65], v[156:159], v[164:167], v[50:65]
	ds_read_b128 v[184:187], v204 offset:8192
	v_mfma_f32_32x32x16_bf16 v[34:49], v[156:159], v[168:171], v[34:49]
	ds_read_b128 v[188:191], v204 offset:12288
	s_add_u32 m0, s14, 0x1c020
	s_add_u32 s12, s12, 0x40000
	s_addc_u32 s13, s13, 0
	global_load_lds_dwordx4 v155, s[12:13]
	s_waitcnt lgkmcnt(6)
	v_mfma_f32_32x32x16_bf16 v[18:33], v[160:163], v[164:167], v[18:33]
	v_mfma_f32_32x32x16_bf16 v[2:17], v[160:163], v[168:171], v[2:17]
	s_add_u32 m0, s14, 0x1e020
	s_add_u32 s12, s12, 0x40000
	s_addc_u32 s13, s13, 0
	global_load_lds_dwordx4 v155, s[12:13]
	s_add_u32 s4, s4, 0x80
	s_addc_u32 s5, s5, 0
	s_waitcnt lgkmcnt(4)
	v_mfma_f32_32x32x16_bf16 v[114:129], v[172:175], v[192:195], v[114:129]
	ds_read_b128 v[130:133], v205 offset:0
	s_waitcnt lgkmcnt(4)
	v_mfma_f32_32x32x16_bf16 v[98:113], v[172:175], v[200:203], v[98:113]
	ds_read_b128 v[164:167], v209 offset:0
	s_waitcnt lgkmcnt(4)
	v_mfma_f32_32x32x16_bf16 v[82:97], v[180:183], v[192:195], v[82:97]
	ds_read_b128 v[168:171], v209 offset:4096
	v_mfma_f32_32x32x16_bf16 v[66:81], v[180:183], v[200:203], v[66:81]
	ds_read_b128 v[134:137], v205 offset:4096
	s_waitcnt lgkmcnt(5)
	v_mfma_f32_32x32x16_bf16 v[50:65], v[184:187], v[192:195], v[50:65]
	ds_read_b128 v[156:159], v205 offset:8192
	v_mfma_f32_32x32x16_bf16 v[34:49], v[184:187], v[200:203], v[34:49]
	ds_read_b128 v[160:163], v205 offset:12288
	s_waitcnt lgkmcnt(6)
	v_mfma_f32_32x32x16_bf16 v[18:33], v[188:191], v[192:195], v[18:33]
	v_mfma_f32_32x32x16_bf16 v[2:17], v[188:191], v[200:203], v[2:17]
	s_waitcnt lgkmcnt(4)
	v_mfma_f32_32x32x16_bf16 v[114:129], v[130:133], v[164:167], v[114:129]
	ds_read_b128 v[172:175], v206 offset:0
	ds_read_b128 v[192:195], v210 offset:0
	s_waitcnt lgkmcnt(5)
	v_mfma_f32_32x32x16_bf16 v[98:113], v[130:133], v[168:171], v[98:113]
	ds_read_b128 v[200:203], v210 offset:4096
	ds_read_b128 v[180:183], v206 offset:4096
	s_waitcnt lgkmcnt(6)
	v_mfma_f32_32x32x16_bf16 v[82:97], v[134:137], v[164:167], v[82:97]
	ds_read_b128 v[184:187], v206 offset:8192
	ds_read_b128 v[188:191], v206 offset:12288
	v_mfma_f32_32x32x16_bf16 v[66:81], v[134:137], v[168:171], v[66:81]
	s_waitcnt lgkmcnt(7)
	v_mfma_f32_32x32x16_bf16 v[50:65], v[156:159], v[164:167], v[50:65]
	v_mfma_f32_32x32x16_bf16 v[34:49], v[156:159], v[168:171], v[34:49]
	s_waitcnt lgkmcnt(6)
	v_mfma_f32_32x32x16_bf16 v[18:33], v[160:163], v[164:167], v[18:33]
	v_mfma_f32_32x32x16_bf16 v[2:17], v[160:163], v[168:171], v[2:17]
	s_waitcnt vmcnt(0) lgkmcnt(0)
	s_barrier
	v_mfma_f32_32x32x16_bf16 v[114:129], v[172:175], v[192:195], v[114:129]
	ds_read_b128 v[130:133], v177 offset:32768
	v_mfma_f32_32x32x16_bf16 v[98:113], v[172:175], v[200:203], v[98:113]
	ds_read_b128 v[164:167], v207 offset:32768
	v_mfma_f32_32x32x16_bf16 v[82:97], v[180:183], v[192:195], v[82:97]
	ds_read_b128 v[168:171], v207 offset:36864
	v_mfma_f32_32x32x16_bf16 v[66:81], v[180:183], v[200:203], v[66:81]
	ds_read_b128 v[134:137], v177 offset:36864
	v_mfma_f32_32x32x16_bf16 v[50:65], v[184:187], v[192:195], v[50:65]
	ds_read_b128 v[156:159], v177 offset:40960
	v_mfma_f32_32x32x16_bf16 v[34:49], v[184:187], v[200:203], v[34:49]
	ds_read_b128 v[160:163], v177 offset:45056
	v_mfma_f32_32x32x16_bf16 v[18:33], v[188:191], v[192:195], v[18:33]
	v_mfma_f32_32x32x16_bf16 v[2:17], v[188:191], v[200:203], v[2:17]
	s_waitcnt lgkmcnt(4)
	v_mfma_f32_32x32x16_bf16 v[114:129], v[130:133], v[164:167], v[114:129]
	ds_read_b128 v[172:175], v204 offset:32768
	s_waitcnt lgkmcnt(4)
	v_mfma_f32_32x32x16_bf16 v[98:113], v[130:133], v[168:171], v[98:113]
	ds_read_b128 v[192:195], v208 offset:32768
	s_waitcnt lgkmcnt(4)
	v_mfma_f32_32x32x16_bf16 v[82:97], v[134:137], v[164:167], v[82:97]
	ds_read_b128 v[200:203], v208 offset:36864
	v_mfma_f32_32x32x16_bf16 v[66:81], v[134:137], v[168:171], v[66:81]
	ds_read_b128 v[180:183], v204 offset:36864
	s_waitcnt lgkmcnt(5)
	v_mfma_f32_32x32x16_bf16 v[50:65], v[156:159], v[164:167], v[50:65]
	ds_read_b128 v[184:187], v204 offset:40960
	v_mfma_f32_32x32x16_bf16 v[34:49], v[156:159], v[168:171], v[34:49]
	ds_read_b128 v[188:191], v204 offset:45056
	s_waitcnt lgkmcnt(6)
	v_mfma_f32_32x32x16_bf16 v[18:33], v[160:163], v[164:167], v[18:33]
	v_mfma_f32_32x32x16_bf16 v[2:17], v[160:163], v[168:171], v[2:17]
	s_waitcnt lgkmcnt(4)
	v_mfma_f32_32x32x16_bf16 v[114:129], v[172:175], v[192:195], v[114:129]
	ds_read_b128 v[130:133], v205 offset:32768
	s_waitcnt lgkmcnt(4)
	v_mfma_f32_32x32x16_bf16 v[98:113], v[172:175], v[200:203], v[98:113]
	ds_read_b128 v[164:167], v209 offset:32768
	s_waitcnt lgkmcnt(4)
	v_mfma_f32_32x32x16_bf16 v[82:97], v[180:183], v[192:195], v[82:97]
	ds_read_b128 v[168:171], v209 offset:36864
	v_mfma_f32_32x32x16_bf16 v[66:81], v[180:183], v[200:203], v[66:81]
	ds_read_b128 v[134:137], v205 offset:36864
	s_waitcnt lgkmcnt(5)
	v_mfma_f32_32x32x16_bf16 v[50:65], v[184:187], v[192:195], v[50:65]
	ds_read_b128 v[156:159], v205 offset:40960
	v_mfma_f32_32x32x16_bf16 v[34:49], v[184:187], v[200:203], v[34:49]
	ds_read_b128 v[160:163], v205 offset:45056
	s_waitcnt lgkmcnt(6)
	v_mfma_f32_32x32x16_bf16 v[18:33], v[188:191], v[192:195], v[18:33]
	v_mfma_f32_32x32x16_bf16 v[2:17], v[188:191], v[200:203], v[2:17]
	s_waitcnt lgkmcnt(4)
	v_mfma_f32_32x32x16_bf16 v[114:129], v[130:133], v[164:167], v[114:129]
	ds_read_b128 v[172:175], v206 offset:32768
	ds_read_b128 v[192:195], v210 offset:32768
	s_waitcnt lgkmcnt(5)
	v_mfma_f32_32x32x16_bf16 v[98:113], v[130:133], v[168:171], v[98:113]
	ds_read_b128 v[200:203], v210 offset:36864
	ds_read_b128 v[180:183], v206 offset:36864
	s_waitcnt lgkmcnt(6)
	v_mfma_f32_32x32x16_bf16 v[82:97], v[134:137], v[164:167], v[82:97]
	ds_read_b128 v[184:187], v206 offset:40960
	ds_read_b128 v[188:191], v206 offset:45056
	v_mfma_f32_32x32x16_bf16 v[66:81], v[134:137], v[168:171], v[66:81]
	s_waitcnt lgkmcnt(7)
	v_mfma_f32_32x32x16_bf16 v[50:65], v[156:159], v[164:167], v[50:65]
	v_mfma_f32_32x32x16_bf16 v[34:49], v[156:159], v[168:171], v[34:49]
	s_waitcnt lgkmcnt(6)
	v_mfma_f32_32x32x16_bf16 v[18:33], v[160:163], v[164:167], v[18:33]
	v_mfma_f32_32x32x16_bf16 v[2:17], v[160:163], v[168:171], v[2:17]
	s_waitcnt vmcnt(0) lgkmcnt(0)
	s_barrier
	v_mfma_f32_32x32x16_bf16 v[114:129], v[172:175], v[192:195], v[114:129]
	v_mfma_f32_32x32x16_bf16 v[98:113], v[172:175], v[200:203], v[98:113]
	v_mfma_f32_32x32x16_bf16 v[82:97], v[180:183], v[192:195], v[82:97]
	v_mfma_f32_32x32x16_bf16 v[66:81], v[180:183], v[200:203], v[66:81]
	v_mfma_f32_32x32x16_bf16 v[50:65], v[184:187], v[192:195], v[50:65]
	v_mfma_f32_32x32x16_bf16 v[34:49], v[184:187], v[200:203], v[34:49]
	v_mfma_f32_32x32x16_bf16 v[18:33], v[188:191], v[192:195], v[18:33]
	v_mfma_f32_32x32x16_bf16 v[2:17], v[188:191], v[200:203], v[2:17]
	s_setprio 0
	v_add_u32_e32 v130, s0, v149
	v_ashrrev_i32_e32 v131, 31, v130
	v_lshrrev_b32_e32 v155, 18, v131
	v_add_u32_e32 v0, v130, v155
	v_ashrrev_i32_e32 v0, 14, v0
	v_mul_i32_i24_e32 v133, 0x4000, v0
	v_sub_u32_e32 v133, v130, v133
	v_add_u32_e32 v156, 0x100, v133
	v_mul_hi_i32_i24_e32 v137, 0x4100, v0
	v_mul_i32_i24_e32 v136, 0x4100, v0
	v_ashrrev_i32_e32 v157, 31, v156
	v_lshl_add_u64 v[136:137], v[136:137], 0, v[156:157]
	v_mov_b32_e32 v156, v179
	s_waitcnt vmcnt(0)
	s_barrier
	v_mul_i32_i24_e32 v134, 0xc00, v0
	v_readlane_b32 s40, v251, 2
	v_and_b32_e32 v0, 31, v156
	v_bfe_u32 v133, v156, 5, 1
	v_mul_u32_u24_e32 v133, 0x240, v133
	v_lshlrev_b32_e32 v0, 2, v0
	v_add3_u32 v0, v151, v133, v0
	ds_write2_b32 v0, v114, v115 offset1:36
	ds_write2_b32 v0, v116, v117 offset0:72 offset1:108
	v_add_u32_e32 v114, 0x400, v0
	v_or_b32_e32 v132, s2, v150
	ds_write2_b32 v114, v118, v119 offset0:32 offset1:68
	ds_write2_b32 v114, v120, v121 offset0:104 offset1:140
	v_add_u32_e32 v114, 0x800, v0
	v_add_u32_e32 v0, 0xc00, v0
	v_readlane_b32 s41, v251, 3
	v_readlane_b32 s42, v251, 4
	v_readlane_b32 s43, v251, 5
	v_readlane_b32 s44, v251, 6
	v_readlane_b32 s45, v251, 7
	v_readlane_b32 s46, v251, 8
	v_readlane_b32 s47, v251, 9
	v_readlane_b32 s48, v251, 10
	v_readlane_b32 s49, v251, 11
	v_readlane_b32 s50, v251, 12
	v_readlane_b32 s51, v251, 13
	v_readlane_b32 s0, v251, 26
	v_ashrrev_i32_e32 v135, 31, v134
	v_lshlrev_b64 v[136:137], 11, v[136:137]
	ds_write2_b32 v114, v122, v123 offset0:64 offset1:100
	ds_write2_b32 v114, v124, v125 offset0:136 offset1:172
	ds_write2_b32 v0, v126, v127 offset0:96 offset1:132
	ds_write2_b32 v0, v128, v129 offset0:168 offset1:204
	v_readlane_b32 s54, v251, 16
	v_readlane_b32 s55, v251, 17
	v_ashrrev_i32_e32 v133, 31, v132
	v_readlane_b32 s1, v251, 27
	v_readlane_b32 s36, v253, 47
	v_lshlrev_b32_e32 v0, 2, v156
	v_readlane_b32 s52, v251, 14
	v_readlane_b32 s53, v251, 15
	v_lshl_add_u64 v[114:115], v[134:135], 2, s[54:55]
	s_mov_b64 s[2:3], 0x1b0b000
	v_lshl_add_u64 v[118:119], s[0:1], 0, v[136:137]
	v_lshlrev_b64 v[116:117], 1, v[132:133]
	v_lshlrev_b64 v[122:123], 12, v[130:131]
	v_readlane_b32 s37, v253, 48
	v_and_b32_e32 v128, 28, v0
	v_lshl_add_u64 v[120:121], v[114:115], 0, s[2:3]
	v_lshlrev_b64 v[114:115], 2, v[132:133]
	v_lshl_add_u64 v[118:119], v[118:119], 0, v[116:117]
	v_lshl_add_u64 v[124:125], s[36:37], 0, v[122:123]
	v_lshl_add_u64 v[122:123], s[52:53], 0, v[122:123]
	v_lshlrev_b32_e32 v0, 2, v128
	v_lshlrev_b32_e32 v128, 1, v128
	v_mov_b32_e32 v129, v1
	v_bfe_u32 v133, v156, 3, 3
	v_lshl_add_u64 v[126:127], v[120:121], 0, v[114:115]
	v_lshl_add_u64 v[124:125], v[124:125], 0, v[114:115]
	v_lshl_add_u64 v[122:123], v[122:123], 0, v[114:115]
	v_lshl_add_u64 v[134:135], v[118:119], 0, v[128:129]
	v_mul_u32_u24_e32 v131, 0x90, v133
	v_lshlrev_b32_e32 v156, 11, v133
	v_mov_b32_e32 v157, v1
	s_waitcnt lgkmcnt(0)
	v_lshl_add_u64 v[126:127], v[126:127], 0, v[0:1]
	v_lshl_add_u64 v[136:137], v[124:125], 0, v[0:1]
	v_lshl_add_u64 v[128:129], v[122:123], 0, v[0:1]
	v_add3_u32 v131, v151, v0, v131
	v_lshlrev_b32_e32 v0, 12, v133
	v_lshl_add_u64 v[156:157], v[134:135], 0, v[156:157]
	v_lshl_add_u64 v[164:165], v[136:137], 0, v[0:1]
	global_load_dwordx4 v[180:183], v[126:127], off
	v_mov_b32_e32 v212, v133
	v_lshlrev_b32_e32 v184, 11, v212
	v_mov_b32_e32 v185, v1
	v_lshl_add_u64 v[184:185], v[134:135], 0, v[184:185]
	global_load_dwordx2 v[184:185], v[184:185], off
	v_lshlrev_b32_e32 v192, 12, v212
	v_mov_b32_e32 v193, v1
	v_lshl_add_u64 v[192:193], v[136:137], 0, v[192:193]
	global_load_dwordx4 v[192:195], v[192:193], off
	v_or_b32_e32 v212, 8, v133
	v_lshlrev_b32_e32 v186, 11, v212
	v_mov_b32_e32 v187, v1
	v_lshl_add_u64 v[186:187], v[134:135], 0, v[186:187]
	global_load_dwordx2 v[186:187], v[186:187], off
	v_lshlrev_b32_e32 v200, 12, v212
	v_mov_b32_e32 v201, v1
	v_lshl_add_u64 v[200:201], v[136:137], 0, v[200:201]
	global_load_dwordx4 v[200:203], v[200:201], off
	v_or_b32_e32 v212, 16, v133
	v_lshlrev_b32_e32 v188, 11, v212
	v_mov_b32_e32 v189, v1
	v_lshl_add_u64 v[188:189], v[134:135], 0, v[188:189]
	global_load_dwordx2 v[188:189], v[188:189], off
	v_lshlrev_b32_e32 v204, 12, v212
	v_mov_b32_e32 v205, v1
	v_lshl_add_u64 v[204:205], v[136:137], 0, v[204:205]
	global_load_dwordx4 v[204:207], v[204:205], off
	v_or_b32_e32 v212, 24, v133
	v_lshlrev_b32_e32 v190, 11, v212
	v_mov_b32_e32 v191, v1
	v_lshl_add_u64 v[190:191], v[134:135], 0, v[190:191]
	global_load_dwordx2 v[190:191], v[190:191], off
	v_lshlrev_b32_e32 v208, 12, v212
	v_mov_b32_e32 v209, v1
	v_lshl_add_u64 v[208:209], v[136:137], 0, v[208:209]
	global_load_dwordx4 v[208:211], v[208:209], off
	s_waitcnt vmcnt(6)
	v_mov_b32_e32 v168, v184
	v_mov_b32_e32 v169, v185
	ds_read_b128 v[156:159], v131
	v_mov_b32_e32 v160, v180
	v_mov_b32_e32 v161, v181
	v_mov_b32_e32 v162, v182
	v_mov_b32_e32 v163, v183
	s_nop 0
	v_mov_b32_e32 v164, v192
	v_mov_b32_e32 v165, v193
	v_mov_b32_e32 v166, v194
	v_mov_b32_e32 v167, v195
	v_lshl_add_u64 v[170:171], v[128:129], 0, v[0:1]
	v_readlane_b32 s38, v253, 49
	v_readlane_b32 s39, v253, 50
	v_readlane_b32 s42, v253, 53
	v_readlane_b32 s43, v253, 54
	v_readlane_b32 s44, v253, 55
	v_readlane_b32 s45, v253, 56
	v_readlane_b32 s46, v253, 57
	v_readlane_b32 s47, v253, 58
	v_readlane_b32 s48, v253, 59
	v_readlane_b32 s49, v253, 60
	v_readlane_b32 s51, v253, 62
	v_readlane_b32 s40, v253, 51
	v_readlane_b32 s41, v253, 52
	v_readlane_b32 s50, v253, 61
	v_and_b32_e32 v173, 0xffff0000, v168
	v_lshlrev_b32_e32 v172, 16, v168
	v_pk_add_f32 v[164:165], v[164:165], v[172:173]
	s_waitcnt lgkmcnt(0)
	v_pk_fma_f32 v[156:157], v[156:157], v[160:161], v[164:165]
	v_and_b32_e32 v161, 0xffff0000, v169
	v_lshlrev_b32_e32 v160, 16, v169
	v_pk_add_f32 v[160:161], v[166:167], v[160:161]
	s_nop 0
	v_pk_fma_f32 v[158:159], v[158:159], v[162:163], v[160:161]
	global_store_dwordx4 v[170:171], v[156:159], off
	s_nop 1
	v_or_b32_e32 v156, 8, v133
	v_lshlrev_b32_e32 v0, 12, v156
	v_lshlrev_b32_e32 v156, 11, v156
	v_mov_b32_e32 v157, v1
	v_lshl_add_u64 v[156:157], v[134:135], 0, v[156:157]
	v_lshl_add_u64 v[164:165], v[136:137], 0, v[0:1]
	s_waitcnt vmcnt(5)
	v_mov_b32_e32 v168, v186
	v_mov_b32_e32 v169, v187
	ds_read_b128 v[156:159], v131 offset:1152
	v_mov_b32_e32 v160, v180
	v_mov_b32_e32 v161, v181
	v_mov_b32_e32 v162, v182
	v_mov_b32_e32 v163, v183
	s_nop 0
	v_mov_b32_e32 v164, v200
	v_mov_b32_e32 v165, v201
	v_mov_b32_e32 v166, v202
	v_mov_b32_e32 v167, v203
	v_lshl_add_u64 v[170:171], v[128:129], 0, v[0:1]
	v_or_b32_e32 v0, 16, v133
	v_and_b32_e32 v173, 0xffff0000, v168
	v_lshlrev_b32_e32 v172, 16, v168
	v_pk_add_f32 v[164:165], v[164:165], v[172:173]
	s_waitcnt lgkmcnt(0)
	v_pk_fma_f32 v[156:157], v[156:157], v[160:161], v[164:165]
	v_and_b32_e32 v161, 0xffff0000, v169
	v_lshlrev_b32_e32 v160, 16, v169
	v_pk_add_f32 v[160:161], v[166:167], v[160:161]
	s_nop 0
	v_pk_fma_f32 v[158:159], v[158:159], v[162:163], v[160:161]
	global_store_dwordx4 v[170:171], v[156:159], off
	s_nop 1
	v_lshlrev_b32_e32 v158, 11, v0
	v_mov_b32_e32 v159, v1
	v_lshlrev_b32_e32 v156, 12, v0
	v_mov_b32_e32 v157, v1
	v_lshl_add_u64 v[158:159], v[134:135], 0, v[158:159]
	v_lshl_add_u64 v[164:165], v[136:137], 0, v[156:157]
	s_waitcnt vmcnt(4)
	v_mov_b32_e32 v168, v188
	v_mov_b32_e32 v169, v189
	v_lshl_add_u64 v[170:171], v[128:129], 0, v[156:157]
	ds_read_b128 v[156:159], v131 offset:2304
	v_mov_b32_e32 v160, v180
	v_mov_b32_e32 v161, v181
	v_mov_b32_e32 v162, v182
	v_mov_b32_e32 v163, v183
	s_nop 0
	v_mov_b32_e32 v164, v204
	v_mov_b32_e32 v165, v205
	v_mov_b32_e32 v166, v206
	v_mov_b32_e32 v167, v207
	v_or_b32_e32 v0, 24, v133
	v_and_b32_e32 v173, 0xffff0000, v168
	v_lshlrev_b32_e32 v172, 16, v168
	v_pk_add_f32 v[164:165], v[164:165], v[172:173]
	s_waitcnt lgkmcnt(0)
	v_pk_fma_f32 v[156:157], v[156:157], v[160:161], v[164:165]
	v_and_b32_e32 v161, 0xffff0000, v169
	v_lshlrev_b32_e32 v160, 16, v169
	v_pk_add_f32 v[160:161], v[166:167], v[160:161]
	s_nop 0
	v_pk_fma_f32 v[158:159], v[158:159], v[162:163], v[160:161]
	global_store_dwordx4 v[170:171], v[156:159], off
	s_nop 1
	v_lshlrev_b32_e32 v156, 12, v0
	v_mov_b32_e32 v157, v1
	v_lshl_add_u64 v[158:159], v[136:137], 0, v[156:157]
	v_lshlrev_b32_e32 v136, 11, v0
	v_mov_b32_e32 v137, v1
	v_lshl_add_u64 v[134:135], v[134:135], 0, v[136:137]
	s_waitcnt vmcnt(3)
	v_mov_b32_e32 v160, v190
	v_mov_b32_e32 v161, v191
	v_lshl_add_u64 v[162:163], v[128:129], 0, v[156:157]
	ds_read_b128 v[134:137], v131 offset:3456
	v_mov_b32_e32 v126, v180
	v_mov_b32_e32 v127, v181
	v_mov_b32_e32 v128, v182
	v_mov_b32_e32 v129, v183
	s_nop 0
	v_mov_b32_e32 v156, v208
	v_mov_b32_e32 v157, v209
	v_mov_b32_e32 v158, v210
	v_mov_b32_e32 v159, v211
	v_and_b32_e32 v165, 0xffff0000, v160
	v_lshlrev_b32_e32 v164, 16, v160
	v_pk_add_f32 v[156:157], v[156:157], v[164:165]
	s_waitcnt lgkmcnt(0)
	v_pk_fma_f32 v[126:127], v[134:135], v[126:127], v[156:157]
	v_and_b32_e32 v135, 0xffff0000, v161
	v_lshlrev_b32_e32 v134, 16, v161
	v_pk_add_f32 v[134:135], v[158:159], v[134:135]
	s_nop 0
	v_pk_fma_f32 v[128:129], v[136:137], v[128:129], v[134:135]
	global_store_dwordx4 v[162:163], v[126:129], off
	v_mov_b32_e32 v0, v179
	s_nop 0
	v_or_b32_e32 v126, 32, v132
	v_and_b32_e32 v127, 31, v0
	v_bfe_u32 v128, v0, 5, 1
	v_mul_u32_u24_e32 v128, 0x240, v128
	v_lshlrev_b32_e32 v127, 2, v127
	v_add3_u32 v127, v151, v128, v127
	ds_write2_b32 v127, v98, v99 offset1:36
	ds_write2_b32 v127, v100, v101 offset0:72 offset1:108
	v_add_u32_e32 v98, 0x400, v127
	ds_write2_b32 v98, v102, v103 offset0:32 offset1:68
	ds_write2_b32 v98, v104, v105 offset0:104 offset1:140
	v_add_u32_e32 v98, 0x800, v127
	ds_write2_b32 v98, v106, v107 offset0:64 offset1:100
	ds_write2_b32 v98, v108, v109 offset0:136 offset1:172
	v_add_u32_e32 v98, 0xc00, v127
	ds_write2_b32 v98, v110, v111 offset0:96 offset1:132
	ds_write2_b32 v98, v112, v113 offset0:168 offset1:204
	v_lshlrev_b32_e32 v98, 2, v0
	v_and_b32_e32 v102, 28, v98
	v_lshlrev_b32_e32 v108, 2, v102
	v_lshlrev_b32_e32 v102, 1, v102
	v_mov_b32_e32 v103, v1
	v_bfe_u32 v131, v0, 3, 3
	v_ashrrev_i32_e32 v127, 31, v126
	v_mov_b32_e32 v109, v1
	v_lshl_add_u64 v[104:105], v[118:119], 0, v[102:103]
	v_lshlrev_b32_e32 v110, 11, v131
	v_mov_b32_e32 v111, v1
	s_waitcnt lgkmcnt(0)
	v_lshl_add_u64 v[100:101], v[120:121], 0, v[108:109]
	v_lshlrev_b64 v[98:99], 2, v[126:127]
	v_mul_u32_u24_e32 v0, 0x90, v131
	v_lshl_add_u64 v[110:111], v[104:105], 0, v[110:111]
	v_lshl_add_u64 v[100:101], v[100:101], 0, v[98:99]
	v_lshl_add_u64 v[106:107], v[124:125], 0, v[108:109]
	v_lshl_add_u64 v[102:103], v[122:123], 0, v[108:109]
	v_add3_u32 v0, v151, v108, v0
	v_lshlrev_b32_e32 v108, 12, v131
	global_load_dwordx4 v[180:183], v[100:101], off
	v_mov_b32_e32 v212, v131
	v_lshlrev_b32_e32 v184, 11, v212
	v_mov_b32_e32 v185, v1
	v_lshl_add_u64 v[184:185], v[104:105], 0, v[184:185]
	global_load_dwordx2 v[184:185], v[184:185], off offset:64
	v_lshlrev_b32_e32 v192, 12, v212
	v_mov_b32_e32 v193, v1
	v_lshl_add_u64 v[192:193], v[106:107], 0, v[192:193]
	global_load_dwordx4 v[192:195], v[192:193], off offset:128
	v_or_b32_e32 v212, 8, v131
	v_lshlrev_b32_e32 v186, 11, v212
	v_mov_b32_e32 v187, v1
	v_lshl_add_u64 v[186:187], v[104:105], 0, v[186:187]
	global_load_dwordx2 v[186:187], v[186:187], off offset:64
	v_lshlrev_b32_e32 v200, 12, v212
	v_mov_b32_e32 v201, v1
	v_lshl_add_u64 v[200:201], v[106:107], 0, v[200:201]
	global_load_dwordx4 v[200:203], v[200:201], off offset:128
	v_or_b32_e32 v212, 16, v131
	v_lshlrev_b32_e32 v188, 11, v212
	v_mov_b32_e32 v189, v1
	v_lshl_add_u64 v[188:189], v[104:105], 0, v[188:189]
	global_load_dwordx2 v[188:189], v[188:189], off offset:64
	v_lshlrev_b32_e32 v204, 12, v212
	v_mov_b32_e32 v205, v1
	v_lshl_add_u64 v[204:205], v[106:107], 0, v[204:205]
	global_load_dwordx4 v[204:207], v[204:205], off offset:128
	v_or_b32_e32 v212, 24, v131
	v_lshlrev_b32_e32 v190, 11, v212
	v_mov_b32_e32 v191, v1
	v_lshl_add_u64 v[190:191], v[104:105], 0, v[190:191]
	global_load_dwordx2 v[190:191], v[190:191], off offset:64
	v_lshlrev_b32_e32 v208, 12, v212
	v_mov_b32_e32 v209, v1
	v_lshl_add_u64 v[208:209], v[106:107], 0, v[208:209]
	global_load_dwordx4 v[208:211], v[208:209], off offset:128
	s_waitcnt vmcnt(6)
	v_mov_b32_e32 v126, v184
	v_mov_b32_e32 v127, v185
	v_lshl_add_u64 v[112:113], v[106:107], 0, v[108:109]
	v_lshl_add_u64 v[128:129], v[102:103], 0, v[108:109]
	ds_read_b128 v[108:111], v0
	v_mov_b32_e32 v118, v180
	v_mov_b32_e32 v119, v181
	v_mov_b32_e32 v120, v182
	v_mov_b32_e32 v121, v183
	v_mov_b32_e32 v122, v192
	v_mov_b32_e32 v123, v193
	v_mov_b32_e32 v124, v194
	v_mov_b32_e32 v125, v195
	v_and_b32_e32 v113, 0xffff0000, v126
	v_lshlrev_b32_e32 v112, 16, v126
	v_pk_add_f32 v[112:113], v[122:123], v[112:113]
	s_waitcnt lgkmcnt(0)
	v_pk_fma_f32 v[108:109], v[108:109], v[118:119], v[112:113]
	v_and_b32_e32 v113, 0xffff0000, v127
	v_lshlrev_b32_e32 v112, 16, v127
	v_pk_add_f32 v[112:113], v[124:125], v[112:113]
	s_nop 0
	v_pk_fma_f32 v[110:111], v[110:111], v[120:121], v[112:113]
	global_store_dwordx4 v[128:129], v[108:111], off offset:128
	s_nop 1
	v_or_b32_e32 v110, 8, v131
	v_lshlrev_b32_e32 v108, 12, v110
	v_lshlrev_b32_e32 v110, 11, v110
	v_mov_b32_e32 v111, v1
	v_lshl_add_u64 v[110:111], v[104:105], 0, v[110:111]
	v_mov_b32_e32 v109, v1
	s_waitcnt vmcnt(5)
	v_mov_b32_e32 v126, v186
	v_mov_b32_e32 v127, v187
	v_lshl_add_u64 v[112:113], v[106:107], 0, v[108:109]
	v_lshl_add_u64 v[128:129], v[102:103], 0, v[108:109]
	ds_read_b128 v[108:111], v0 offset:1152
	v_mov_b32_e32 v118, v180
	v_mov_b32_e32 v119, v181
	v_mov_b32_e32 v120, v182
	v_mov_b32_e32 v121, v183
	v_mov_b32_e32 v122, v200
	v_mov_b32_e32 v123, v201
	v_mov_b32_e32 v124, v202
	v_mov_b32_e32 v125, v203
	v_and_b32_e32 v113, 0xffff0000, v126
	v_lshlrev_b32_e32 v112, 16, v126
	v_pk_add_f32 v[112:113], v[122:123], v[112:113]
	s_waitcnt lgkmcnt(0)
	v_pk_fma_f32 v[108:109], v[108:109], v[118:119], v[112:113]
	v_and_b32_e32 v113, 0xffff0000, v127
	v_lshlrev_b32_e32 v112, 16, v127
	v_pk_add_f32 v[112:113], v[124:125], v[112:113]
	s_nop 0
	v_pk_fma_f32 v[110:111], v[110:111], v[120:121], v[112:113]
	global_store_dwordx4 v[128:129], v[108:111], off offset:128
	s_nop 1
	v_or_b32_e32 v110, 16, v131
	v_lshlrev_b32_e32 v108, 12, v110
	v_lshlrev_b32_e32 v110, 11, v110
	v_mov_b32_e32 v111, v1
	v_lshl_add_u64 v[110:111], v[104:105], 0, v[110:111]
	v_mov_b32_e32 v109, v1
	s_waitcnt vmcnt(4)
	v_mov_b32_e32 v126, v188
	v_mov_b32_e32 v127, v189
	v_lshl_add_u64 v[112:113], v[106:107], 0, v[108:109]
	v_lshl_add_u64 v[128:129], v[102:103], 0, v[108:109]
	ds_read_b128 v[108:111], v0 offset:2304
	v_mov_b32_e32 v118, v180
	v_mov_b32_e32 v119, v181
	v_mov_b32_e32 v120, v182
	v_mov_b32_e32 v121, v183
	v_mov_b32_e32 v122, v204
	v_mov_b32_e32 v123, v205
	v_mov_b32_e32 v124, v206
	v_mov_b32_e32 v125, v207
	v_and_b32_e32 v113, 0xffff0000, v126
	v_lshlrev_b32_e32 v112, 16, v126
	v_pk_add_f32 v[112:113], v[122:123], v[112:113]
	s_waitcnt lgkmcnt(0)
	v_pk_fma_f32 v[108:109], v[108:109], v[118:119], v[112:113]
	v_and_b32_e32 v113, 0xffff0000, v127
	v_lshlrev_b32_e32 v112, 16, v127
	v_pk_add_f32 v[112:113], v[124:125], v[112:113]
	s_nop 0
	v_pk_fma_f32 v[110:111], v[110:111], v[120:121], v[112:113]
	v_or_b32_e32 v112, 24, v131
	global_store_dwordx4 v[128:129], v[108:111], off offset:128
	s_nop 1
	v_lshlrev_b32_e32 v108, 12, v112
	v_mov_b32_e32 v109, v1
	v_lshl_add_u64 v[110:111], v[106:107], 0, v[108:109]
	v_lshlrev_b32_e32 v106, 11, v112
	v_mov_b32_e32 v107, v1
	v_lshl_add_u64 v[104:105], v[104:105], 0, v[106:107]
	s_waitcnt vmcnt(3)
	v_mov_b32_e32 v118, v190
	v_mov_b32_e32 v119, v191
	v_lshl_add_u64 v[120:121], v[102:103], 0, v[108:109]
	ds_read_b128 v[102:105], v0 offset:3456
	v_mov_b32_e32 v106, v180
	v_mov_b32_e32 v107, v181
	v_mov_b32_e32 v108, v182
	v_mov_b32_e32 v109, v183
	s_nop 0
	v_mov_b32_e32 v110, v208
	v_mov_b32_e32 v111, v209
	v_mov_b32_e32 v112, v210
	v_mov_b32_e32 v113, v211
	v_and_b32_e32 v101, 0xffff0000, v118
	v_lshlrev_b32_e32 v100, 16, v118
	v_pk_add_f32 v[100:101], v[110:111], v[100:101]
	s_waitcnt lgkmcnt(0)
	v_pk_fma_f32 v[100:101], v[102:103], v[106:107], v[100:101]
	v_and_b32_e32 v103, 0xffff0000, v119
	v_lshlrev_b32_e32 v102, 16, v119
	v_pk_add_f32 v[102:103], v[112:113], v[102:103]
	s_nop 0
	v_pk_fma_f32 v[102:103], v[104:105], v[108:109], v[102:103]
	global_store_dwordx4 v[120:121], v[100:103], off offset:128
	s_nop 1
	v_or_b32_e32 v100, 32, v130
	v_add_u32_e32 v0, v100, v155
	v_ashrrev_i32_e32 v0, 14, v0
	v_mul_i32_i24_e32 v101, 0x4000, v0
	v_sub_u32_e32 v101, v100, v101
	v_add_u32_e32 v106, 0x100, v101
	v_mul_i32_i24_e32 v102, 0xc00, v0
	v_mul_hi_i32_i24_e32 v105, 0x4100, v0
	v_mul_i32_i24_e32 v104, 0x4100, v0
	v_ashrrev_i32_e32 v107, 31, v106
	v_mov_b32_e32 v0, v179
	v_lshl_add_u64 v[104:105], v[104:105], 0, v[106:107]
	v_ashrrev_i32_e32 v103, 31, v102
	v_and_b32_e32 v106, 31, v0
	v_bfe_u32 v107, v0, 5, 1
	v_mul_u32_u24_e32 v107, 0x240, v107
	v_lshlrev_b32_e32 v106, 2, v106
	v_add3_u32 v106, v151, v107, v106
	ds_write2_b32 v106, v82, v83 offset1:36
	ds_write2_b32 v106, v84, v85 offset0:72 offset1:108
	v_add_u32_e32 v82, 0x400, v106
	ds_write2_b32 v82, v86, v87 offset0:32 offset1:68
	ds_write2_b32 v82, v88, v89 offset0:104 offset1:140
	v_add_u32_e32 v82, 0x800, v106
	ds_write2_b32 v82, v90, v91 offset0:64 offset1:100
	ds_write2_b32 v82, v92, v93 offset0:136 offset1:172
	v_add_u32_e32 v82, 0xc00, v106
	v_lshlrev_b64 v[104:105], 11, v[104:105]
	v_ashrrev_i32_e32 v101, 31, v100
	ds_write2_b32 v82, v94, v95 offset0:96 offset1:132
	ds_write2_b32 v82, v96, v97 offset0:168 offset1:204
	v_lshl_add_u64 v[82:83], v[102:103], 2, s[54:55]
	v_lshlrev_b32_e32 v92, 2, v0
	v_lshl_add_u64 v[86:87], v[82:83], 0, s[2:3]
	v_lshl_add_u64 v[82:83], s[0:1], 0, v[104:105]
	v_lshlrev_b64 v[84:85], 12, v[100:101]
	v_and_b32_e32 v92, 28, v92
	v_lshl_add_u64 v[82:83], v[82:83], 0, v[116:117]
	v_lshl_add_u64 v[88:89], s[36:37], 0, v[84:85]
	v_lshl_add_u64 v[84:85], s[52:53], 0, v[84:85]
	v_lshlrev_b32_e32 v100, 2, v92
	v_lshlrev_b32_e32 v92, 1, v92
	v_mov_b32_e32 v93, v1
	v_bfe_u32 v122, v0, 3, 3
	v_lshl_add_u64 v[90:91], v[86:87], 0, v[114:115]
	v_lshl_add_u64 v[88:89], v[88:89], 0, v[114:115]
	v_lshl_add_u64 v[84:85], v[84:85], 0, v[114:115]
	v_mov_b32_e32 v101, v1
	v_lshl_add_u64 v[94:95], v[82:83], 0, v[92:93]
	v_mul_u32_u24_e32 v0, 0x90, v122
	v_lshlrev_b32_e32 v102, 11, v122
	v_mov_b32_e32 v103, v1
	s_waitcnt lgkmcnt(0)
	v_lshl_add_u64 v[90:91], v[90:91], 0, v[100:101]
	v_lshl_add_u64 v[96:97], v[88:89], 0, v[100:101]
	v_lshl_add_u64 v[92:93], v[84:85], 0, v[100:101]
	v_add3_u32 v0, v151, v100, v0
	v_lshlrev_b32_e32 v100, 12, v122
	v_lshl_add_u64 v[102:103], v[94:95], 0, v[102:103]
	v_lshl_add_u64 v[108:109], v[96:97], 0, v[100:101]
	global_load_dwordx4 v[180:183], v[90:91], off
	v_mov_b32_e32 v212, v122
	v_lshlrev_b32_e32 v184, 11, v212
	v_mov_b32_e32 v185, v1
	v_lshl_add_u64 v[184:185], v[94:95], 0, v[184:185]
	global_load_dwordx2 v[184:185], v[184:185], off
	v_lshlrev_b32_e32 v192, 12, v212
	v_mov_b32_e32 v193, v1
	v_lshl_add_u64 v[192:193], v[96:97], 0, v[192:193]
	global_load_dwordx4 v[192:195], v[192:193], off
	v_or_b32_e32 v212, 8, v122
	v_lshlrev_b32_e32 v186, 11, v212
	v_mov_b32_e32 v187, v1
	v_lshl_add_u64 v[186:187], v[94:95], 0, v[186:187]
	global_load_dwordx2 v[186:187], v[186:187], off
	v_lshlrev_b32_e32 v200, 12, v212
	v_mov_b32_e32 v201, v1
	v_lshl_add_u64 v[200:201], v[96:97], 0, v[200:201]
	global_load_dwordx4 v[200:203], v[200:201], off
	v_or_b32_e32 v212, 16, v122
	v_lshlrev_b32_e32 v188, 11, v212
	v_mov_b32_e32 v189, v1
	v_lshl_add_u64 v[188:189], v[94:95], 0, v[188:189]
	global_load_dwordx2 v[188:189], v[188:189], off
	v_lshlrev_b32_e32 v204, 12, v212
	v_mov_b32_e32 v205, v1
	v_lshl_add_u64 v[204:205], v[96:97], 0, v[204:205]
	global_load_dwordx4 v[204:207], v[204:205], off
	v_or_b32_e32 v212, 24, v122
	v_lshlrev_b32_e32 v190, 11, v212
	v_mov_b32_e32 v191, v1
	v_lshl_add_u64 v[190:191], v[94:95], 0, v[190:191]
	global_load_dwordx2 v[190:191], v[190:191], off
	v_lshlrev_b32_e32 v208, 12, v212
	v_mov_b32_e32 v209, v1
	v_lshl_add_u64 v[208:209], v[96:97], 0, v[208:209]
	global_load_dwordx4 v[208:211], v[208:209], off
	s_waitcnt vmcnt(6)
	v_mov_b32_e32 v112, v184
	v_mov_b32_e32 v113, v185
	v_lshl_add_u64 v[118:119], v[92:93], 0, v[100:101]
	ds_read_b128 v[100:103], v0
	v_mov_b32_e32 v104, v180
	v_mov_b32_e32 v105, v181
	v_mov_b32_e32 v106, v182
	v_mov_b32_e32 v107, v183
	s_nop 0
	v_mov_b32_e32 v108, v192
	v_mov_b32_e32 v109, v193
	v_mov_b32_e32 v110, v194
	v_mov_b32_e32 v111, v195
	v_and_b32_e32 v121, 0xffff0000, v112
	v_lshlrev_b32_e32 v120, 16, v112
	v_pk_add_f32 v[108:109], v[108:109], v[120:121]
	s_waitcnt lgkmcnt(0)
	v_pk_fma_f32 v[100:101], v[100:101], v[104:105], v[108:109]
	v_and_b32_e32 v105, 0xffff0000, v113
	v_lshlrev_b32_e32 v104, 16, v113
	v_pk_add_f32 v[104:105], v[110:111], v[104:105]
	s_nop 0
	v_pk_fma_f32 v[102:103], v[102:103], v[106:107], v[104:105]
	global_store_dwordx4 v[118:119], v[100:103], off
	s_nop 1
	v_or_b32_e32 v102, 8, v122
	v_lshlrev_b32_e32 v100, 12, v102
	v_lshlrev_b32_e32 v102, 11, v102
	v_mov_b32_e32 v103, v1
	v_mov_b32_e32 v101, v1
	v_lshl_add_u64 v[102:103], v[94:95], 0, v[102:103]
	v_lshl_add_u64 v[108:109], v[96:97], 0, v[100:101]
	s_waitcnt vmcnt(5)
	v_mov_b32_e32 v112, v186
	v_mov_b32_e32 v113, v187
	v_lshl_add_u64 v[118:119], v[92:93], 0, v[100:101]
	ds_read_b128 v[100:103], v0 offset:1152
	v_mov_b32_e32 v104, v180
	v_mov_b32_e32 v105, v181
	v_mov_b32_e32 v106, v182
	v_mov_b32_e32 v107, v183
	s_nop 0
	v_mov_b32_e32 v108, v200
	v_mov_b32_e32 v109, v201
	v_mov_b32_e32 v110, v202
	v_mov_b32_e32 v111, v203
	v_and_b32_e32 v121, 0xffff0000, v112
	v_lshlrev_b32_e32 v120, 16, v112
	v_pk_add_f32 v[108:109], v[108:109], v[120:121]
	s_waitcnt lgkmcnt(0)
	v_pk_fma_f32 v[100:101], v[100:101], v[104:105], v[108:109]
	v_and_b32_e32 v105, 0xffff0000, v113
	v_lshlrev_b32_e32 v104, 16, v113
	v_pk_add_f32 v[104:105], v[110:111], v[104:105]
	s_nop 0
	v_pk_fma_f32 v[102:103], v[102:103], v[106:107], v[104:105]
	global_store_dwordx4 v[118:119], v[100:103], off
	s_nop 1
	v_or_b32_e32 v102, 16, v122
	v_lshlrev_b32_e32 v100, 12, v102
	v_lshlrev_b32_e32 v102, 11, v102
	v_mov_b32_e32 v103, v1
	v_mov_b32_e32 v101, v1
	v_lshl_add_u64 v[102:103], v[94:95], 0, v[102:103]
	v_lshl_add_u64 v[108:109], v[96:97], 0, v[100:101]
	s_waitcnt vmcnt(4)
	v_mov_b32_e32 v112, v188
	v_mov_b32_e32 v113, v189
	v_lshl_add_u64 v[118:119], v[92:93], 0, v[100:101]
	ds_read_b128 v[100:103], v0 offset:2304
	v_mov_b32_e32 v104, v180
	v_mov_b32_e32 v105, v181
	v_mov_b32_e32 v106, v182
	v_mov_b32_e32 v107, v183
	s_nop 0
	v_mov_b32_e32 v108, v204
	v_mov_b32_e32 v109, v205
	v_mov_b32_e32 v110, v206
	v_mov_b32_e32 v111, v207
	v_and_b32_e32 v121, 0xffff0000, v112
	v_lshlrev_b32_e32 v120, 16, v112
	v_pk_add_f32 v[108:109], v[108:109], v[120:121]
	s_waitcnt lgkmcnt(0)
	v_pk_fma_f32 v[100:101], v[100:101], v[104:105], v[108:109]
	v_and_b32_e32 v105, 0xffff0000, v113
	v_lshlrev_b32_e32 v104, 16, v113
	v_pk_add_f32 v[104:105], v[110:111], v[104:105]
	s_nop 0
	v_pk_fma_f32 v[102:103], v[102:103], v[106:107], v[104:105]
	global_store_dwordx4 v[118:119], v[100:103], off
	s_nop 1
	v_or_b32_e32 v102, 24, v122
	v_lshlrev_b32_e32 v100, 12, v102
	v_lshlrev_b32_e32 v102, 11, v102
	v_mov_b32_e32 v103, v1
	v_lshl_add_u64 v[94:95], v[94:95], 0, v[102:103]
	v_mov_b32_e32 v101, v1
	s_waitcnt vmcnt(3)
	v_mov_b32_e32 v108, v190
	v_mov_b32_e32 v109, v191
	v_lshl_add_u64 v[96:97], v[96:97], 0, v[100:101]
	v_lshl_add_u64 v[110:111], v[92:93], 0, v[100:101]
	ds_read_b128 v[92:95], v0 offset:3456
	v_mov_b32_e32 v100, v180
	v_mov_b32_e32 v101, v181
	v_mov_b32_e32 v102, v182
	v_mov_b32_e32 v103, v183
	v_mov_b32_e32 v104, v208
	v_mov_b32_e32 v105, v209
	v_mov_b32_e32 v106, v210
	v_mov_b32_e32 v107, v211
	v_and_b32_e32 v91, 0xffff0000, v108
	v_lshlrev_b32_e32 v90, 16, v108
	v_pk_add_f32 v[90:91], v[104:105], v[90:91]
	s_waitcnt lgkmcnt(0)
	v_pk_fma_f32 v[90:91], v[92:93], v[100:101], v[90:91]
	v_and_b32_e32 v93, 0xffff0000, v109
	v_lshlrev_b32_e32 v92, 16, v109
	v_pk_add_f32 v[92:93], v[106:107], v[92:93]
	s_nop 0
	v_pk_fma_f32 v[92:93], v[94:95], v[102:103], v[92:93]
	global_store_dwordx4 v[110:111], v[90:93], off
	v_mov_b32_e32 v0, v179
	s_nop 0
	v_and_b32_e32 v90, 31, v0
	v_bfe_u32 v91, v0, 5, 1
	v_mul_u32_u24_e32 v91, 0x240, v91
	v_lshlrev_b32_e32 v90, 2, v90
	v_add3_u32 v90, v151, v91, v90
	ds_write2_b32 v90, v66, v67 offset1:36
	ds_write2_b32 v90, v68, v69 offset0:72 offset1:108
	v_add_u32_e32 v66, 0x400, v90
	ds_write2_b32 v66, v70, v71 offset0:32 offset1:68
	ds_write2_b32 v66, v72, v73 offset0:104 offset1:140
	v_add_u32_e32 v66, 0x800, v90
	ds_write2_b32 v66, v74, v75 offset0:64 offset1:100
	ds_write2_b32 v66, v76, v77 offset0:136 offset1:172
	v_add_u32_e32 v66, 0xc00, v90
	ds_write2_b32 v66, v78, v79 offset0:96 offset1:132
	ds_write2_b32 v66, v80, v81 offset0:168 offset1:204
	v_lshlrev_b32_e32 v66, 2, v0
	v_and_b32_e32 v68, 28, v66
	v_lshlrev_b32_e32 v74, 2, v68
	v_lshlrev_b32_e32 v68, 1, v68
	v_mov_b32_e32 v69, v1
	v_bfe_u32 v92, v0, 3, 3
	v_mov_b32_e32 v75, v1
	v_lshl_add_u64 v[70:71], v[82:83], 0, v[68:69]
	v_mul_u32_u24_e32 v0, 0x90, v92
	v_lshlrev_b32_e32 v76, 11, v92
	v_mov_b32_e32 v77, v1
	s_waitcnt lgkmcnt(0)
	v_lshl_add_u64 v[66:67], v[86:87], 0, v[74:75]
	v_lshl_add_u64 v[72:73], v[88:89], 0, v[74:75]
	v_lshl_add_u64 v[68:69], v[84:85], 0, v[74:75]
	v_add3_u32 v0, v151, v74, v0
	v_lshlrev_b32_e32 v74, 12, v92
	v_lshl_add_u64 v[76:77], v[70:71], 0, v[76:77]
	v_lshl_add_u64 v[66:67], v[66:67], 0, v[98:99]
	v_lshl_add_u64 v[82:83], v[72:73], 0, v[74:75]
	global_load_dwordx4 v[180:183], v[66:67], off
	v_mov_b32_e32 v212, v92
	v_lshlrev_b32_e32 v184, 11, v212
	v_mov_b32_e32 v185, v1
	v_lshl_add_u64 v[184:185], v[70:71], 0, v[184:185]
	global_load_dwordx2 v[184:185], v[184:185], off offset:64
	v_lshlrev_b32_e32 v192, 12, v212
	v_mov_b32_e32 v193, v1
	v_lshl_add_u64 v[192:193], v[72:73], 0, v[192:193]
	global_load_dwordx4 v[192:195], v[192:193], off offset:128
	v_or_b32_e32 v212, 8, v92
	v_lshlrev_b32_e32 v186, 11, v212
	v_mov_b32_e32 v187, v1
	v_lshl_add_u64 v[186:187], v[70:71], 0, v[186:187]
	global_load_dwordx2 v[186:187], v[186:187], off offset:64
	v_lshlrev_b32_e32 v200, 12, v212
	v_mov_b32_e32 v201, v1
	v_lshl_add_u64 v[200:201], v[72:73], 0, v[200:201]
	global_load_dwordx4 v[200:203], v[200:201], off offset:128
	v_or_b32_e32 v212, 16, v92
	v_lshlrev_b32_e32 v188, 11, v212
	v_mov_b32_e32 v189, v1
	v_lshl_add_u64 v[188:189], v[70:71], 0, v[188:189]
	global_load_dwordx2 v[188:189], v[188:189], off offset:64
	v_lshlrev_b32_e32 v204, 12, v212
	v_mov_b32_e32 v205, v1
	v_lshl_add_u64 v[204:205], v[72:73], 0, v[204:205]
	global_load_dwordx4 v[204:207], v[204:205], off offset:128
	v_or_b32_e32 v212, 24, v92
	v_lshlrev_b32_e32 v190, 11, v212
	v_mov_b32_e32 v191, v1
	v_lshl_add_u64 v[190:191], v[70:71], 0, v[190:191]
	global_load_dwordx2 v[190:191], v[190:191], off offset:64
	v_lshlrev_b32_e32 v208, 12, v212
	v_mov_b32_e32 v209, v1
	v_lshl_add_u64 v[208:209], v[72:73], 0, v[208:209]
	global_load_dwordx4 v[208:211], v[208:209], off offset:128
	s_waitcnt vmcnt(6)
	v_mov_b32_e32 v86, v184
	v_mov_b32_e32 v87, v185
	v_lshl_add_u64 v[88:89], v[68:69], 0, v[74:75]
	ds_read_b128 v[74:77], v0
	v_mov_b32_e32 v78, v180
	v_mov_b32_e32 v79, v181
	v_mov_b32_e32 v80, v182
	v_mov_b32_e32 v81, v183
	s_nop 0
	v_mov_b32_e32 v82, v192
	v_mov_b32_e32 v83, v193
	v_mov_b32_e32 v84, v194
	v_mov_b32_e32 v85, v195
	v_and_b32_e32 v91, 0xffff0000, v86
	v_lshlrev_b32_e32 v90, 16, v86
	v_pk_add_f32 v[82:83], v[82:83], v[90:91]
	s_waitcnt lgkmcnt(0)
	v_pk_fma_f32 v[74:75], v[74:75], v[78:79], v[82:83]
	v_and_b32_e32 v79, 0xffff0000, v87
	v_lshlrev_b32_e32 v78, 16, v87
	v_pk_add_f32 v[78:79], v[84:85], v[78:79]
	s_nop 0
	v_pk_fma_f32 v[76:77], v[76:77], v[80:81], v[78:79]
	global_store_dwordx4 v[88:89], v[74:77], off offset:128
	s_nop 1
	v_or_b32_e32 v76, 8, v92
	v_lshlrev_b32_e32 v74, 12, v76
	v_lshlrev_b32_e32 v76, 11, v76
	v_mov_b32_e32 v77, v1
	v_mov_b32_e32 v75, v1
	v_lshl_add_u64 v[76:77], v[70:71], 0, v[76:77]
	v_lshl_add_u64 v[82:83], v[72:73], 0, v[74:75]
	s_waitcnt vmcnt(5)
	v_mov_b32_e32 v86, v186
	v_mov_b32_e32 v87, v187
	v_lshl_add_u64 v[88:89], v[68:69], 0, v[74:75]
	ds_read_b128 v[74:77], v0 offset:1152
	v_mov_b32_e32 v78, v180
	v_mov_b32_e32 v79, v181
	v_mov_b32_e32 v80, v182
	v_mov_b32_e32 v81, v183
	s_nop 0
	v_mov_b32_e32 v82, v200
	v_mov_b32_e32 v83, v201
	v_mov_b32_e32 v84, v202
	v_mov_b32_e32 v85, v203
	v_and_b32_e32 v91, 0xffff0000, v86
	v_lshlrev_b32_e32 v90, 16, v86
	v_pk_add_f32 v[82:83], v[82:83], v[90:91]
	s_waitcnt lgkmcnt(0)
	v_pk_fma_f32 v[74:75], v[74:75], v[78:79], v[82:83]
	v_and_b32_e32 v79, 0xffff0000, v87
	v_lshlrev_b32_e32 v78, 16, v87
	v_pk_add_f32 v[78:79], v[84:85], v[78:79]
	s_nop 0
	v_pk_fma_f32 v[76:77], v[76:77], v[80:81], v[78:79]
	global_store_dwordx4 v[88:89], v[74:77], off offset:128
	s_nop 1
	v_or_b32_e32 v76, 16, v92
	v_lshlrev_b32_e32 v74, 12, v76
	v_lshlrev_b32_e32 v76, 11, v76
	v_mov_b32_e32 v77, v1
	v_mov_b32_e32 v75, v1
	v_lshl_add_u64 v[76:77], v[70:71], 0, v[76:77]
	v_lshl_add_u64 v[82:83], v[72:73], 0, v[74:75]
	s_waitcnt vmcnt(4)
	v_mov_b32_e32 v86, v188
	v_mov_b32_e32 v87, v189
	v_lshl_add_u64 v[88:89], v[68:69], 0, v[74:75]
	ds_read_b128 v[74:77], v0 offset:2304
	v_mov_b32_e32 v78, v180
	v_mov_b32_e32 v79, v181
	v_mov_b32_e32 v80, v182
	v_mov_b32_e32 v81, v183
	s_nop 0
	v_mov_b32_e32 v82, v204
	v_mov_b32_e32 v83, v205
	v_mov_b32_e32 v84, v206
	v_mov_b32_e32 v85, v207
	v_and_b32_e32 v91, 0xffff0000, v86
	v_lshlrev_b32_e32 v90, 16, v86
	v_pk_add_f32 v[82:83], v[82:83], v[90:91]
	s_waitcnt lgkmcnt(0)
	v_pk_fma_f32 v[74:75], v[74:75], v[78:79], v[82:83]
	v_and_b32_e32 v79, 0xffff0000, v87
	v_lshlrev_b32_e32 v78, 16, v87
	v_pk_add_f32 v[78:79], v[84:85], v[78:79]
	s_nop 0
	v_pk_fma_f32 v[76:77], v[76:77], v[80:81], v[78:79]
	v_or_b32_e32 v78, 24, v92
	global_store_dwordx4 v[88:89], v[74:77], off offset:128
	s_nop 1
	v_lshlrev_b32_e32 v74, 12, v78
	v_mov_b32_e32 v75, v1
	v_lshl_add_u64 v[76:77], v[72:73], 0, v[74:75]
	v_lshlrev_b32_e32 v72, 11, v78
	v_mov_b32_e32 v73, v1
	v_lshl_add_u64 v[70:71], v[70:71], 0, v[72:73]
	s_waitcnt vmcnt(3)
	v_mov_b32_e32 v80, v190
	v_mov_b32_e32 v81, v191
	v_lshl_add_u64 v[82:83], v[68:69], 0, v[74:75]
	ds_read_b128 v[68:71], v0 offset:3456
	v_mov_b32_e32 v72, v180
	v_mov_b32_e32 v73, v181
	v_mov_b32_e32 v74, v182
	v_mov_b32_e32 v75, v183
	s_nop 0
	v_mov_b32_e32 v76, v208
	v_mov_b32_e32 v77, v209
	v_mov_b32_e32 v78, v210
	v_mov_b32_e32 v79, v211
	v_and_b32_e32 v67, 0xffff0000, v80
	v_lshlrev_b32_e32 v66, 16, v80
	v_pk_add_f32 v[66:67], v[76:77], v[66:67]
	s_waitcnt lgkmcnt(0)
	v_pk_fma_f32 v[66:67], v[68:69], v[72:73], v[66:67]
	v_and_b32_e32 v69, 0xffff0000, v81
	v_lshlrev_b32_e32 v68, 16, v81
	v_pk_add_f32 v[68:69], v[78:79], v[68:69]
	s_nop 0
	v_pk_fma_f32 v[68:69], v[70:71], v[74:75], v[68:69]
	global_store_dwordx4 v[82:83], v[66:69], off offset:128
	s_nop 1
	v_or_b32_e32 v66, 64, v130
	v_add_u32_e32 v0, v66, v155
	v_ashrrev_i32_e32 v0, 14, v0
	v_mul_i32_i24_e32 v67, 0x4000, v0
	v_sub_u32_e32 v67, v66, v67
	v_add_u32_e32 v72, 0x100, v67
	v_mul_i32_i24_e32 v68, 0xc00, v0
	v_mul_hi_i32_i24_e32 v71, 0x4100, v0
	v_mul_i32_i24_e32 v70, 0x4100, v0
	v_ashrrev_i32_e32 v73, 31, v72
	v_mov_b32_e32 v0, v179
	v_lshl_add_u64 v[70:71], v[70:71], 0, v[72:73]
	v_ashrrev_i32_e32 v69, 31, v68
	v_and_b32_e32 v72, 31, v0
	v_bfe_u32 v73, v0, 5, 1
	v_mul_u32_u24_e32 v73, 0x240, v73
	v_lshlrev_b32_e32 v72, 2, v72
	v_add3_u32 v72, v151, v73, v72
	ds_write2_b32 v72, v50, v51 offset1:36
	ds_write2_b32 v72, v52, v53 offset0:72 offset1:108
	v_add_u32_e32 v50, 0x400, v72
	ds_write2_b32 v50, v54, v55 offset0:32 offset1:68
	ds_write2_b32 v50, v56, v57 offset0:104 offset1:140
	v_add_u32_e32 v50, 0x800, v72
	ds_write2_b32 v50, v58, v59 offset0:64 offset1:100
	ds_write2_b32 v50, v60, v61 offset0:136 offset1:172
	v_add_u32_e32 v50, 0xc00, v72
	v_lshlrev_b64 v[70:71], 11, v[70:71]
	v_ashrrev_i32_e32 v67, 31, v66
	ds_write2_b32 v50, v62, v63 offset0:96 offset1:132
	ds_write2_b32 v50, v64, v65 offset0:168 offset1:204
	v_lshl_add_u64 v[50:51], v[68:69], 2, s[54:55]
	v_lshlrev_b32_e32 v60, 2, v0
	v_lshl_add_u64 v[54:55], v[50:51], 0, s[2:3]
	v_lshl_add_u64 v[50:51], s[0:1], 0, v[70:71]
	v_lshlrev_b64 v[52:53], 12, v[66:67]
	v_and_b32_e32 v60, 28, v60
	v_lshl_add_u64 v[50:51], v[50:51], 0, v[116:117]
	v_lshl_add_u64 v[56:57], s[36:37], 0, v[52:53]
	v_lshl_add_u64 v[52:53], s[52:53], 0, v[52:53]
	v_lshlrev_b32_e32 v66, 2, v60
	v_lshlrev_b32_e32 v60, 1, v60
	v_mov_b32_e32 v61, v1
	v_bfe_u32 v84, v0, 3, 3
	v_lshl_add_u64 v[58:59], v[54:55], 0, v[114:115]
	v_lshl_add_u64 v[56:57], v[56:57], 0, v[114:115]
	v_lshl_add_u64 v[52:53], v[52:53], 0, v[114:115]
	v_mov_b32_e32 v67, v1
	v_lshl_add_u64 v[62:63], v[50:51], 0, v[60:61]
	v_mul_u32_u24_e32 v0, 0x90, v84
	v_lshlrev_b32_e32 v68, 11, v84
	v_mov_b32_e32 v69, v1
	s_waitcnt lgkmcnt(0)
	v_lshl_add_u64 v[58:59], v[58:59], 0, v[66:67]
	v_lshl_add_u64 v[64:65], v[56:57], 0, v[66:67]
	v_lshl_add_u64 v[60:61], v[52:53], 0, v[66:67]
	v_add3_u32 v0, v151, v66, v0
	v_lshlrev_b32_e32 v66, 12, v84
	v_lshl_add_u64 v[68:69], v[62:63], 0, v[68:69]
	v_lshl_add_u64 v[74:75], v[64:65], 0, v[66:67]
	global_load_dwordx4 v[180:183], v[58:59], off
	v_mov_b32_e32 v212, v84
	v_lshlrev_b32_e32 v184, 11, v212
	v_mov_b32_e32 v185, v1
	v_lshl_add_u64 v[184:185], v[62:63], 0, v[184:185]
	global_load_dwordx2 v[184:185], v[184:185], off
	v_lshlrev_b32_e32 v192, 12, v212
	v_mov_b32_e32 v193, v1
	v_lshl_add_u64 v[192:193], v[64:65], 0, v[192:193]
	global_load_dwordx4 v[192:195], v[192:193], off
	v_or_b32_e32 v212, 8, v84
	v_lshlrev_b32_e32 v186, 11, v212
	v_mov_b32_e32 v187, v1
	v_lshl_add_u64 v[186:187], v[62:63], 0, v[186:187]
	global_load_dwordx2 v[186:187], v[186:187], off
	v_lshlrev_b32_e32 v200, 12, v212
	v_mov_b32_e32 v201, v1
	v_lshl_add_u64 v[200:201], v[64:65], 0, v[200:201]
	global_load_dwordx4 v[200:203], v[200:201], off
	v_or_b32_e32 v212, 16, v84
	v_lshlrev_b32_e32 v188, 11, v212
	v_mov_b32_e32 v189, v1
	v_lshl_add_u64 v[188:189], v[62:63], 0, v[188:189]
	global_load_dwordx2 v[188:189], v[188:189], off
	v_lshlrev_b32_e32 v204, 12, v212
	v_mov_b32_e32 v205, v1
	v_lshl_add_u64 v[204:205], v[64:65], 0, v[204:205]
	global_load_dwordx4 v[204:207], v[204:205], off
	v_or_b32_e32 v212, 24, v84
	v_lshlrev_b32_e32 v190, 11, v212
	v_mov_b32_e32 v191, v1
	v_lshl_add_u64 v[190:191], v[62:63], 0, v[190:191]
	global_load_dwordx2 v[190:191], v[190:191], off
	v_lshlrev_b32_e32 v208, 12, v212
	v_mov_b32_e32 v209, v1
	v_lshl_add_u64 v[208:209], v[64:65], 0, v[208:209]
	global_load_dwordx4 v[208:211], v[208:209], off
	s_waitcnt vmcnt(6)
	v_mov_b32_e32 v78, v184
	v_mov_b32_e32 v79, v185
	v_lshl_add_u64 v[80:81], v[60:61], 0, v[66:67]
	ds_read_b128 v[66:69], v0
	v_mov_b32_e32 v70, v180
	v_mov_b32_e32 v71, v181
	v_mov_b32_e32 v72, v182
	v_mov_b32_e32 v73, v183
	s_nop 0
	v_mov_b32_e32 v74, v192
	v_mov_b32_e32 v75, v193
	v_mov_b32_e32 v76, v194
	v_mov_b32_e32 v77, v195
	v_and_b32_e32 v83, 0xffff0000, v78
	v_lshlrev_b32_e32 v82, 16, v78
	v_pk_add_f32 v[74:75], v[74:75], v[82:83]
	s_waitcnt lgkmcnt(0)
	v_pk_fma_f32 v[66:67], v[66:67], v[70:71], v[74:75]
	v_and_b32_e32 v71, 0xffff0000, v79
	v_lshlrev_b32_e32 v70, 16, v79
	v_pk_add_f32 v[70:71], v[76:77], v[70:71]
	s_nop 0
	v_pk_fma_f32 v[68:69], v[68:69], v[72:73], v[70:71]
	global_store_dwordx4 v[80:81], v[66:69], off
	s_nop 1
	v_or_b32_e32 v68, 8, v84
	v_lshlrev_b32_e32 v66, 12, v68
	v_lshlrev_b32_e32 v68, 11, v68
	v_mov_b32_e32 v69, v1
	v_mov_b32_e32 v67, v1
	v_lshl_add_u64 v[68:69], v[62:63], 0, v[68:69]
	v_lshl_add_u64 v[74:75], v[64:65], 0, v[66:67]
	s_waitcnt vmcnt(5)
	v_mov_b32_e32 v78, v186
	v_mov_b32_e32 v79, v187
	v_lshl_add_u64 v[80:81], v[60:61], 0, v[66:67]
	ds_read_b128 v[66:69], v0 offset:1152
	v_mov_b32_e32 v70, v180
	v_mov_b32_e32 v71, v181
	v_mov_b32_e32 v72, v182
	v_mov_b32_e32 v73, v183
	s_nop 0
	v_mov_b32_e32 v74, v200
	v_mov_b32_e32 v75, v201
	v_mov_b32_e32 v76, v202
	v_mov_b32_e32 v77, v203
	v_and_b32_e32 v83, 0xffff0000, v78
	v_lshlrev_b32_e32 v82, 16, v78
	v_pk_add_f32 v[74:75], v[74:75], v[82:83]
	s_waitcnt lgkmcnt(0)
	v_pk_fma_f32 v[66:67], v[66:67], v[70:71], v[74:75]
	v_and_b32_e32 v71, 0xffff0000, v79
	v_lshlrev_b32_e32 v70, 16, v79
	v_pk_add_f32 v[70:71], v[76:77], v[70:71]
	s_nop 0
	v_pk_fma_f32 v[68:69], v[68:69], v[72:73], v[70:71]
	global_store_dwordx4 v[80:81], v[66:69], off
	s_nop 1
	v_or_b32_e32 v68, 16, v84
	v_lshlrev_b32_e32 v66, 12, v68
	v_lshlrev_b32_e32 v68, 11, v68
	v_mov_b32_e32 v69, v1
	v_mov_b32_e32 v67, v1
	v_lshl_add_u64 v[68:69], v[62:63], 0, v[68:69]
	v_lshl_add_u64 v[74:75], v[64:65], 0, v[66:67]
	s_waitcnt vmcnt(4)
	v_mov_b32_e32 v78, v188
	v_mov_b32_e32 v79, v189
	v_lshl_add_u64 v[80:81], v[60:61], 0, v[66:67]
	ds_read_b128 v[66:69], v0 offset:2304
	v_mov_b32_e32 v70, v180
	v_mov_b32_e32 v71, v181
	v_mov_b32_e32 v72, v182
	v_mov_b32_e32 v73, v183
	s_nop 0
	v_mov_b32_e32 v74, v204
	v_mov_b32_e32 v75, v205
	v_mov_b32_e32 v76, v206
	v_mov_b32_e32 v77, v207
	v_and_b32_e32 v83, 0xffff0000, v78
	v_lshlrev_b32_e32 v82, 16, v78
	v_pk_add_f32 v[74:75], v[74:75], v[82:83]
	s_waitcnt lgkmcnt(0)
	v_pk_fma_f32 v[66:67], v[66:67], v[70:71], v[74:75]
	v_and_b32_e32 v71, 0xffff0000, v79
	v_lshlrev_b32_e32 v70, 16, v79
	v_pk_add_f32 v[70:71], v[76:77], v[70:71]
	s_nop 0
	v_pk_fma_f32 v[68:69], v[68:69], v[72:73], v[70:71]
	v_or_b32_e32 v70, 24, v84
	global_store_dwordx4 v[80:81], v[66:69], off
	s_nop 1
	v_lshlrev_b32_e32 v66, 12, v70
	v_mov_b32_e32 v67, v1
	v_lshl_add_u64 v[68:69], v[64:65], 0, v[66:67]
	v_lshlrev_b32_e32 v64, 11, v70
	v_mov_b32_e32 v65, v1
	v_lshl_add_u64 v[62:63], v[62:63], 0, v[64:65]
	s_waitcnt vmcnt(3)
	v_mov_b32_e32 v72, v190
	v_mov_b32_e32 v73, v191
	v_lshl_add_u64 v[74:75], v[60:61], 0, v[66:67]
	ds_read_b128 v[60:63], v0 offset:3456
	v_mov_b32_e32 v64, v180
	v_mov_b32_e32 v65, v181
	v_mov_b32_e32 v66, v182
	v_mov_b32_e32 v67, v183
	s_nop 0
	v_mov_b32_e32 v68, v208
	v_mov_b32_e32 v69, v209
	v_mov_b32_e32 v70, v210
	v_mov_b32_e32 v71, v211
	v_and_b32_e32 v59, 0xffff0000, v72
	v_lshlrev_b32_e32 v58, 16, v72
	v_pk_add_f32 v[58:59], v[68:69], v[58:59]
	s_waitcnt lgkmcnt(0)
	v_pk_fma_f32 v[58:59], v[60:61], v[64:65], v[58:59]
	v_and_b32_e32 v61, 0xffff0000, v73
	v_lshlrev_b32_e32 v60, 16, v73
	v_pk_add_f32 v[60:61], v[70:71], v[60:61]
	s_nop 0
	v_pk_fma_f32 v[60:61], v[62:63], v[66:67], v[60:61]
	global_store_dwordx4 v[74:75], v[58:61], off
	v_mov_b32_e32 v0, v179
	s_nop 0
	v_and_b32_e32 v58, 31, v0
	v_bfe_u32 v59, v0, 5, 1
	v_mul_u32_u24_e32 v59, 0x240, v59
	v_lshlrev_b32_e32 v58, 2, v58
	v_add3_u32 v58, v151, v59, v58
	ds_write2_b32 v58, v34, v35 offset1:36
	ds_write2_b32 v58, v36, v37 offset0:72 offset1:108
	v_add_u32_e32 v34, 0x400, v58
	ds_write2_b32 v34, v38, v39 offset0:32 offset1:68
	ds_write2_b32 v34, v40, v41 offset0:104 offset1:140
	v_add_u32_e32 v34, 0x800, v58
	ds_write2_b32 v34, v42, v43 offset0:64 offset1:100
	ds_write2_b32 v34, v44, v45 offset0:136 offset1:172
	v_add_u32_e32 v34, 0xc00, v58
	ds_write2_b32 v34, v46, v47 offset0:96 offset1:132
	ds_write2_b32 v34, v48, v49 offset0:168 offset1:204
	v_lshlrev_b32_e32 v34, 2, v0
	v_and_b32_e32 v36, 28, v34
	v_lshlrev_b32_e32 v42, 2, v36
	v_lshlrev_b32_e32 v36, 1, v36
	v_mov_b32_e32 v37, v1
	v_bfe_u32 v60, v0, 3, 3
	v_mov_b32_e32 v43, v1
	v_lshl_add_u64 v[38:39], v[50:51], 0, v[36:37]
	v_mul_u32_u24_e32 v0, 0x90, v60
	v_lshlrev_b32_e32 v44, 11, v60
	v_mov_b32_e32 v45, v1
	s_waitcnt lgkmcnt(0)
	v_lshl_add_u64 v[34:35], v[54:55], 0, v[42:43]
	v_lshl_add_u64 v[40:41], v[56:57], 0, v[42:43]
	v_lshl_add_u64 v[36:37], v[52:53], 0, v[42:43]
	v_add3_u32 v0, v151, v42, v0
	v_lshlrev_b32_e32 v42, 12, v60
	v_lshl_add_u64 v[44:45], v[38:39], 0, v[44:45]
	v_lshl_add_u64 v[34:35], v[34:35], 0, v[98:99]
	v_lshl_add_u64 v[50:51], v[40:41], 0, v[42:43]
	global_load_dwordx4 v[180:183], v[34:35], off
	v_mov_b32_e32 v212, v60
	v_lshlrev_b32_e32 v184, 11, v212
	v_mov_b32_e32 v185, v1
	v_lshl_add_u64 v[184:185], v[38:39], 0, v[184:185]
	global_load_dwordx2 v[184:185], v[184:185], off offset:64
	v_lshlrev_b32_e32 v192, 12, v212
	v_mov_b32_e32 v193, v1
	v_lshl_add_u64 v[192:193], v[40:41], 0, v[192:193]
	global_load_dwordx4 v[192:195], v[192:193], off offset:128
	v_or_b32_e32 v212, 8, v60
	v_lshlrev_b32_e32 v186, 11, v212
	v_mov_b32_e32 v187, v1
	v_lshl_add_u64 v[186:187], v[38:39], 0, v[186:187]
	global_load_dwordx2 v[186:187], v[186:187], off offset:64
	v_lshlrev_b32_e32 v200, 12, v212
	v_mov_b32_e32 v201, v1
	v_lshl_add_u64 v[200:201], v[40:41], 0, v[200:201]
	global_load_dwordx4 v[200:203], v[200:201], off offset:128
	v_or_b32_e32 v212, 16, v60
	v_lshlrev_b32_e32 v188, 11, v212
	v_mov_b32_e32 v189, v1
	v_lshl_add_u64 v[188:189], v[38:39], 0, v[188:189]
	global_load_dwordx2 v[188:189], v[188:189], off offset:64
	v_lshlrev_b32_e32 v204, 12, v212
	v_mov_b32_e32 v205, v1
	v_lshl_add_u64 v[204:205], v[40:41], 0, v[204:205]
	global_load_dwordx4 v[204:207], v[204:205], off offset:128
	v_or_b32_e32 v212, 24, v60
	v_lshlrev_b32_e32 v190, 11, v212
	v_mov_b32_e32 v191, v1
	v_lshl_add_u64 v[190:191], v[38:39], 0, v[190:191]
	global_load_dwordx2 v[190:191], v[190:191], off offset:64
	v_lshlrev_b32_e32 v208, 12, v212
	v_mov_b32_e32 v209, v1
	v_lshl_add_u64 v[208:209], v[40:41], 0, v[208:209]
	global_load_dwordx4 v[208:211], v[208:209], off offset:128
	s_waitcnt vmcnt(6)
	v_mov_b32_e32 v54, v184
	v_mov_b32_e32 v55, v185
	v_lshl_add_u64 v[56:57], v[36:37], 0, v[42:43]
	ds_read_b128 v[42:45], v0
	v_mov_b32_e32 v46, v180
	v_mov_b32_e32 v47, v181
	v_mov_b32_e32 v48, v182
	v_mov_b32_e32 v49, v183
	s_nop 0
	v_mov_b32_e32 v50, v192
	v_mov_b32_e32 v51, v193
	v_mov_b32_e32 v52, v194
	v_mov_b32_e32 v53, v195
	v_and_b32_e32 v59, 0xffff0000, v54
	v_lshlrev_b32_e32 v58, 16, v54
	v_pk_add_f32 v[50:51], v[50:51], v[58:59]
	s_waitcnt lgkmcnt(0)
	v_pk_fma_f32 v[42:43], v[42:43], v[46:47], v[50:51]
	v_and_b32_e32 v47, 0xffff0000, v55
	v_lshlrev_b32_e32 v46, 16, v55
	v_pk_add_f32 v[46:47], v[52:53], v[46:47]
	s_nop 0
	v_pk_fma_f32 v[44:45], v[44:45], v[48:49], v[46:47]
	global_store_dwordx4 v[56:57], v[42:45], off offset:128
	s_nop 1
	v_or_b32_e32 v44, 8, v60
	v_lshlrev_b32_e32 v42, 12, v44
	v_lshlrev_b32_e32 v44, 11, v44
	v_mov_b32_e32 v45, v1
	v_mov_b32_e32 v43, v1
	v_lshl_add_u64 v[44:45], v[38:39], 0, v[44:45]
	v_lshl_add_u64 v[50:51], v[40:41], 0, v[42:43]
	s_waitcnt vmcnt(5)
	v_mov_b32_e32 v54, v186
	v_mov_b32_e32 v55, v187
	v_lshl_add_u64 v[56:57], v[36:37], 0, v[42:43]
	ds_read_b128 v[42:45], v0 offset:1152
	v_mov_b32_e32 v46, v180
	v_mov_b32_e32 v47, v181
	v_mov_b32_e32 v48, v182
	v_mov_b32_e32 v49, v183
	s_nop 0
	v_mov_b32_e32 v50, v200
	v_mov_b32_e32 v51, v201
	v_mov_b32_e32 v52, v202
	v_mov_b32_e32 v53, v203
	v_and_b32_e32 v59, 0xffff0000, v54
	v_lshlrev_b32_e32 v58, 16, v54
	v_pk_add_f32 v[50:51], v[50:51], v[58:59]
	s_waitcnt lgkmcnt(0)
	v_pk_fma_f32 v[42:43], v[42:43], v[46:47], v[50:51]
	v_and_b32_e32 v47, 0xffff0000, v55
	v_lshlrev_b32_e32 v46, 16, v55
	v_pk_add_f32 v[46:47], v[52:53], v[46:47]
	s_nop 0
	v_pk_fma_f32 v[44:45], v[44:45], v[48:49], v[46:47]
	global_store_dwordx4 v[56:57], v[42:45], off offset:128
	s_nop 1
	v_or_b32_e32 v44, 16, v60
	v_lshlrev_b32_e32 v42, 12, v44
	v_lshlrev_b32_e32 v44, 11, v44
	v_mov_b32_e32 v45, v1
	v_mov_b32_e32 v43, v1
	v_lshl_add_u64 v[44:45], v[38:39], 0, v[44:45]
	v_lshl_add_u64 v[50:51], v[40:41], 0, v[42:43]
	s_waitcnt vmcnt(4)
	v_mov_b32_e32 v54, v188
	v_mov_b32_e32 v55, v189
	v_lshl_add_u64 v[56:57], v[36:37], 0, v[42:43]
	ds_read_b128 v[42:45], v0 offset:2304
	v_mov_b32_e32 v46, v180
	v_mov_b32_e32 v47, v181
	v_mov_b32_e32 v48, v182
	v_mov_b32_e32 v49, v183
	s_nop 0
	v_mov_b32_e32 v50, v204
	v_mov_b32_e32 v51, v205
	v_mov_b32_e32 v52, v206
	v_mov_b32_e32 v53, v207
	v_and_b32_e32 v59, 0xffff0000, v54
	v_lshlrev_b32_e32 v58, 16, v54
	v_pk_add_f32 v[50:51], v[50:51], v[58:59]
	s_waitcnt lgkmcnt(0)
	v_pk_fma_f32 v[42:43], v[42:43], v[46:47], v[50:51]
	v_and_b32_e32 v47, 0xffff0000, v55
	v_lshlrev_b32_e32 v46, 16, v55
	v_pk_add_f32 v[46:47], v[52:53], v[46:47]
	s_nop 0
	v_pk_fma_f32 v[44:45], v[44:45], v[48:49], v[46:47]
	v_or_b32_e32 v46, 24, v60
	global_store_dwordx4 v[56:57], v[42:45], off offset:128
	s_nop 1
	v_lshlrev_b32_e32 v42, 12, v46
	v_mov_b32_e32 v43, v1
	v_lshl_add_u64 v[44:45], v[40:41], 0, v[42:43]
	v_lshlrev_b32_e32 v40, 11, v46
	v_mov_b32_e32 v41, v1
	v_lshl_add_u64 v[38:39], v[38:39], 0, v[40:41]
	s_waitcnt vmcnt(3)
	v_mov_b32_e32 v48, v190
	v_mov_b32_e32 v49, v191
	v_lshl_add_u64 v[50:51], v[36:37], 0, v[42:43]
	ds_read_b128 v[36:39], v0 offset:3456
	v_mov_b32_e32 v40, v180
	v_mov_b32_e32 v41, v181
	v_mov_b32_e32 v42, v182
	v_mov_b32_e32 v43, v183
	s_nop 0
	v_mov_b32_e32 v44, v208
	v_mov_b32_e32 v45, v209
	v_mov_b32_e32 v46, v210
	v_mov_b32_e32 v47, v211
	v_and_b32_e32 v35, 0xffff0000, v48
	v_lshlrev_b32_e32 v34, 16, v48
	v_pk_add_f32 v[34:35], v[44:45], v[34:35]
	s_waitcnt lgkmcnt(0)
	v_pk_fma_f32 v[34:35], v[36:37], v[40:41], v[34:35]
	v_and_b32_e32 v37, 0xffff0000, v49
	v_lshlrev_b32_e32 v36, 16, v49
	v_pk_add_f32 v[36:37], v[46:47], v[36:37]
	s_nop 0
	v_pk_fma_f32 v[36:37], v[38:39], v[42:43], v[36:37]
	global_store_dwordx4 v[50:51], v[34:37], off offset:128
	s_nop 1
	v_or_b32_e32 v34, 0x60, v130
	v_add_u32_e32 v0, v34, v155
	v_ashrrev_i32_e32 v0, 14, v0
	v_mul_i32_i24_e32 v35, 0x4000, v0
	v_sub_u32_e32 v35, v34, v35
	v_add_u32_e32 v40, 0x100, v35
	v_mul_i32_i24_e32 v36, 0xc00, v0
	v_mul_hi_i32_i24_e32 v39, 0x4100, v0
	v_mul_i32_i24_e32 v38, 0x4100, v0
	v_ashrrev_i32_e32 v41, 31, v40
	v_mov_b32_e32 v0, v179
	v_lshl_add_u64 v[38:39], v[38:39], 0, v[40:41]
	v_ashrrev_i32_e32 v37, 31, v36
	v_and_b32_e32 v40, 31, v0
	v_bfe_u32 v41, v0, 5, 1
	v_mul_u32_u24_e32 v41, 0x240, v41
	v_lshlrev_b32_e32 v40, 2, v40
	v_add3_u32 v40, v151, v41, v40
	ds_write2_b32 v40, v18, v19 offset1:36
	ds_write2_b32 v40, v20, v21 offset0:72 offset1:108
	v_add_u32_e32 v18, 0x400, v40
	ds_write2_b32 v18, v22, v23 offset0:32 offset1:68
	ds_write2_b32 v18, v24, v25 offset0:104 offset1:140
	v_add_u32_e32 v18, 0x800, v40
	ds_write2_b32 v18, v26, v27 offset0:64 offset1:100
	ds_write2_b32 v18, v28, v29 offset0:136 offset1:172
	v_add_u32_e32 v18, 0xc00, v40
	v_lshlrev_b64 v[38:39], 11, v[38:39]
	v_ashrrev_i32_e32 v35, 31, v34
	ds_write2_b32 v18, v30, v31 offset0:96 offset1:132
	ds_write2_b32 v18, v32, v33 offset0:168 offset1:204
	v_lshl_add_u64 v[18:19], v[36:37], 2, s[54:55]
	v_lshlrev_b32_e32 v28, 2, v0
	v_lshl_add_u64 v[20:21], v[18:19], 0, s[2:3]
	v_lshl_add_u64 v[18:19], s[0:1], 0, v[38:39]
	v_lshlrev_b64 v[22:23], 12, v[34:35]
	v_and_b32_e32 v28, 28, v28
	v_lshl_add_u64 v[18:19], v[18:19], 0, v[116:117]
	v_lshl_add_u64 v[24:25], s[36:37], 0, v[22:23]
	v_lshl_add_u64 v[22:23], s[52:53], 0, v[22:23]
	v_lshlrev_b32_e32 v34, 2, v28
	v_lshlrev_b32_e32 v28, 1, v28
	v_mov_b32_e32 v29, v1
	v_bfe_u32 v52, v0, 3, 3
	v_lshl_add_u64 v[26:27], v[20:21], 0, v[114:115]
	v_lshl_add_u64 v[24:25], v[24:25], 0, v[114:115]
	v_lshl_add_u64 v[22:23], v[22:23], 0, v[114:115]
	v_mov_b32_e32 v35, v1
	v_lshl_add_u64 v[30:31], v[18:19], 0, v[28:29]
	v_mul_u32_u24_e32 v0, 0x90, v52
	v_lshlrev_b32_e32 v36, 11, v52
	v_mov_b32_e32 v37, v1
	s_waitcnt lgkmcnt(0)
	v_lshl_add_u64 v[26:27], v[26:27], 0, v[34:35]
	v_lshl_add_u64 v[32:33], v[24:25], 0, v[34:35]
	v_lshl_add_u64 v[28:29], v[22:23], 0, v[34:35]
	v_add3_u32 v0, v151, v34, v0
	v_lshlrev_b32_e32 v34, 12, v52
	v_lshl_add_u64 v[36:37], v[30:31], 0, v[36:37]
	v_lshl_add_u64 v[42:43], v[32:33], 0, v[34:35]
	global_load_dwordx4 v[180:183], v[26:27], off
	v_mov_b32_e32 v212, v52
	v_lshlrev_b32_e32 v184, 11, v212
	v_mov_b32_e32 v185, v1
	v_lshl_add_u64 v[184:185], v[30:31], 0, v[184:185]
	global_load_dwordx2 v[184:185], v[184:185], off
	v_lshlrev_b32_e32 v192, 12, v212
	v_mov_b32_e32 v193, v1
	v_lshl_add_u64 v[192:193], v[32:33], 0, v[192:193]
	global_load_dwordx4 v[192:195], v[192:193], off
	v_or_b32_e32 v212, 8, v52
	v_lshlrev_b32_e32 v186, 11, v212
	v_mov_b32_e32 v187, v1
	v_lshl_add_u64 v[186:187], v[30:31], 0, v[186:187]
	global_load_dwordx2 v[186:187], v[186:187], off
	v_lshlrev_b32_e32 v200, 12, v212
	v_mov_b32_e32 v201, v1
	v_lshl_add_u64 v[200:201], v[32:33], 0, v[200:201]
	global_load_dwordx4 v[200:203], v[200:201], off
	v_or_b32_e32 v212, 16, v52
	v_lshlrev_b32_e32 v188, 11, v212
	v_mov_b32_e32 v189, v1
	v_lshl_add_u64 v[188:189], v[30:31], 0, v[188:189]
	global_load_dwordx2 v[188:189], v[188:189], off
	v_lshlrev_b32_e32 v204, 12, v212
	v_mov_b32_e32 v205, v1
	v_lshl_add_u64 v[204:205], v[32:33], 0, v[204:205]
	global_load_dwordx4 v[204:207], v[204:205], off
	v_or_b32_e32 v212, 24, v52
	v_lshlrev_b32_e32 v190, 11, v212
	v_mov_b32_e32 v191, v1
	v_lshl_add_u64 v[190:191], v[30:31], 0, v[190:191]
	global_load_dwordx2 v[190:191], v[190:191], off
	v_lshlrev_b32_e32 v208, 12, v212
	v_mov_b32_e32 v209, v1
	v_lshl_add_u64 v[208:209], v[32:33], 0, v[208:209]
	global_load_dwordx4 v[208:211], v[208:209], off
	s_waitcnt vmcnt(6)
	v_mov_b32_e32 v46, v184
	v_mov_b32_e32 v47, v185
	v_lshl_add_u64 v[48:49], v[28:29], 0, v[34:35]
	ds_read_b128 v[34:37], v0
	v_mov_b32_e32 v38, v180
	v_mov_b32_e32 v39, v181
	v_mov_b32_e32 v40, v182
	v_mov_b32_e32 v41, v183
	s_nop 0
	v_mov_b32_e32 v42, v192
	v_mov_b32_e32 v43, v193
	v_mov_b32_e32 v44, v194
	v_mov_b32_e32 v45, v195
	v_and_b32_e32 v51, 0xffff0000, v46
	v_lshlrev_b32_e32 v50, 16, v46
	v_pk_add_f32 v[42:43], v[42:43], v[50:51]
	s_waitcnt lgkmcnt(0)
	v_pk_fma_f32 v[34:35], v[34:35], v[38:39], v[42:43]
	v_and_b32_e32 v39, 0xffff0000, v47
	v_lshlrev_b32_e32 v38, 16, v47
	v_pk_add_f32 v[38:39], v[44:45], v[38:39]
	s_nop 0
	v_pk_fma_f32 v[36:37], v[36:37], v[40:41], v[38:39]
	global_store_dwordx4 v[48:49], v[34:37], off
	s_nop 1
	v_or_b32_e32 v36, 8, v52
	v_lshlrev_b32_e32 v34, 12, v36
	v_lshlrev_b32_e32 v36, 11, v36
	v_mov_b32_e32 v37, v1
	v_mov_b32_e32 v35, v1
	v_lshl_add_u64 v[36:37], v[30:31], 0, v[36:37]
	v_lshl_add_u64 v[42:43], v[32:33], 0, v[34:35]
	s_waitcnt vmcnt(5)
	v_mov_b32_e32 v46, v186
	v_mov_b32_e32 v47, v187
	v_lshl_add_u64 v[48:49], v[28:29], 0, v[34:35]
	ds_read_b128 v[34:37], v0 offset:1152
	v_mov_b32_e32 v38, v180
	v_mov_b32_e32 v39, v181
	v_mov_b32_e32 v40, v182
	v_mov_b32_e32 v41, v183
	s_nop 0
	v_mov_b32_e32 v42, v200
	v_mov_b32_e32 v43, v201
	v_mov_b32_e32 v44, v202
	v_mov_b32_e32 v45, v203
	v_and_b32_e32 v51, 0xffff0000, v46
	v_lshlrev_b32_e32 v50, 16, v46
	v_pk_add_f32 v[42:43], v[42:43], v[50:51]
	s_waitcnt lgkmcnt(0)
	v_pk_fma_f32 v[34:35], v[34:35], v[38:39], v[42:43]
	v_and_b32_e32 v39, 0xffff0000, v47
	v_lshlrev_b32_e32 v38, 16, v47
	v_pk_add_f32 v[38:39], v[44:45], v[38:39]
	s_nop 0
	v_pk_fma_f32 v[36:37], v[36:37], v[40:41], v[38:39]
	global_store_dwordx4 v[48:49], v[34:37], off
	s_nop 1
	v_or_b32_e32 v36, 16, v52
	v_lshlrev_b32_e32 v34, 12, v36
	v_lshlrev_b32_e32 v36, 11, v36
	v_mov_b32_e32 v37, v1
	v_mov_b32_e32 v35, v1
	v_lshl_add_u64 v[36:37], v[30:31], 0, v[36:37]
	v_lshl_add_u64 v[42:43], v[32:33], 0, v[34:35]
	s_waitcnt vmcnt(4)
	v_mov_b32_e32 v46, v188
	v_mov_b32_e32 v47, v189
	v_lshl_add_u64 v[48:49], v[28:29], 0, v[34:35]
	ds_read_b128 v[34:37], v0 offset:2304
	v_mov_b32_e32 v38, v180
	v_mov_b32_e32 v39, v181
	v_mov_b32_e32 v40, v182
	v_mov_b32_e32 v41, v183
	s_nop 0
	v_mov_b32_e32 v42, v204
	v_mov_b32_e32 v43, v205
	v_mov_b32_e32 v44, v206
	v_mov_b32_e32 v45, v207
	v_and_b32_e32 v51, 0xffff0000, v46
	v_lshlrev_b32_e32 v50, 16, v46
	v_pk_add_f32 v[42:43], v[42:43], v[50:51]
	s_waitcnt lgkmcnt(0)
	v_pk_fma_f32 v[34:35], v[34:35], v[38:39], v[42:43]
	v_and_b32_e32 v39, 0xffff0000, v47
	v_lshlrev_b32_e32 v38, 16, v47
	v_pk_add_f32 v[38:39], v[44:45], v[38:39]
	s_nop 0
	v_pk_fma_f32 v[36:37], v[36:37], v[40:41], v[38:39]
	v_or_b32_e32 v38, 24, v52
	global_store_dwordx4 v[48:49], v[34:37], off
	s_nop 1
	v_lshlrev_b32_e32 v34, 12, v38
	v_mov_b32_e32 v35, v1
	v_lshl_add_u64 v[36:37], v[32:33], 0, v[34:35]
	v_lshlrev_b32_e32 v32, 11, v38
	v_mov_b32_e32 v33, v1
	v_lshl_add_u64 v[30:31], v[30:31], 0, v[32:33]
	s_waitcnt vmcnt(3)
	v_mov_b32_e32 v40, v190
	v_mov_b32_e32 v41, v191
	v_lshl_add_u64 v[42:43], v[28:29], 0, v[34:35]
	ds_read_b128 v[28:31], v0 offset:3456
	v_mov_b32_e32 v32, v180
	v_mov_b32_e32 v33, v181
	v_mov_b32_e32 v34, v182
	v_mov_b32_e32 v35, v183
	s_nop 0
	v_mov_b32_e32 v36, v208
	v_mov_b32_e32 v37, v209
	v_mov_b32_e32 v38, v210
	v_mov_b32_e32 v39, v211
	v_and_b32_e32 v27, 0xffff0000, v40
	v_lshlrev_b32_e32 v26, 16, v40
	v_pk_add_f32 v[26:27], v[36:37], v[26:27]
	s_waitcnt lgkmcnt(0)
	v_pk_fma_f32 v[26:27], v[28:29], v[32:33], v[26:27]
	v_and_b32_e32 v29, 0xffff0000, v41
	v_lshlrev_b32_e32 v28, 16, v41
	v_pk_add_f32 v[28:29], v[38:39], v[28:29]
	s_nop 0
	v_pk_fma_f32 v[28:29], v[30:31], v[34:35], v[28:29]
	global_store_dwordx4 v[42:43], v[26:29], off
	v_mov_b32_e32 v0, v179
	s_nop 0
	v_and_b32_e32 v26, 31, v0
	v_bfe_u32 v27, v0, 5, 1
	v_mul_u32_u24_e32 v27, 0x240, v27
	v_lshlrev_b32_e32 v26, 2, v26
	v_add3_u32 v26, v151, v27, v26
	ds_write2_b32 v26, v2, v3 offset1:36
	ds_write2_b32 v26, v4, v5 offset0:72 offset1:108
	v_add_u32_e32 v2, 0x400, v26
	ds_write2_b32 v2, v6, v7 offset0:32 offset1:68
	ds_write2_b32 v2, v8, v9 offset0:104 offset1:140
	v_add_u32_e32 v2, 0x800, v26
	ds_write2_b32 v2, v10, v11 offset0:64 offset1:100
	ds_write2_b32 v2, v12, v13 offset0:136 offset1:172
	v_add_u32_e32 v2, 0xc00, v26
	ds_write2_b32 v2, v14, v15 offset0:96 offset1:132
	ds_write2_b32 v2, v16, v17 offset0:168 offset1:204
	v_lshlrev_b32_e32 v2, 2, v0
	v_and_b32_e32 v4, 28, v2
	v_lshlrev_b32_e32 v10, 2, v4
	v_lshlrev_b32_e32 v4, 1, v4
	v_mov_b32_e32 v5, v1
	v_bfe_u32 v28, v0, 3, 3
	v_mov_b32_e32 v11, v1
	v_lshl_add_u64 v[6:7], v[18:19], 0, v[4:5]
	v_mul_u32_u24_e32 v0, 0x90, v28
	v_lshlrev_b32_e32 v12, 11, v28
	v_mov_b32_e32 v13, v1
	s_waitcnt lgkmcnt(0)
	v_lshl_add_u64 v[2:3], v[20:21], 0, v[10:11]
	v_lshl_add_u64 v[8:9], v[24:25], 0, v[10:11]
	v_lshl_add_u64 v[4:5], v[22:23], 0, v[10:11]
	v_add3_u32 v0, v151, v10, v0
	v_lshlrev_b32_e32 v10, 12, v28
	v_lshl_add_u64 v[12:13], v[6:7], 0, v[12:13]
	v_lshl_add_u64 v[2:3], v[2:3], 0, v[98:99]
	v_lshl_add_u64 v[18:19], v[8:9], 0, v[10:11]
	global_load_dwordx4 v[180:183], v[2:3], off
	v_mov_b32_e32 v212, v28
	v_lshlrev_b32_e32 v184, 11, v212
	v_mov_b32_e32 v185, v1
	v_lshl_add_u64 v[184:185], v[6:7], 0, v[184:185]
	global_load_dwordx2 v[184:185], v[184:185], off offset:64
	v_lshlrev_b32_e32 v192, 12, v212
	v_mov_b32_e32 v193, v1
	v_lshl_add_u64 v[192:193], v[8:9], 0, v[192:193]
	global_load_dwordx4 v[192:195], v[192:193], off offset:128
	v_or_b32_e32 v212, 8, v28
	v_lshlrev_b32_e32 v186, 11, v212
	v_mov_b32_e32 v187, v1
	v_lshl_add_u64 v[186:187], v[6:7], 0, v[186:187]
	global_load_dwordx2 v[186:187], v[186:187], off offset:64
	v_lshlrev_b32_e32 v200, 12, v212
	v_mov_b32_e32 v201, v1
	v_lshl_add_u64 v[200:201], v[8:9], 0, v[200:201]
	global_load_dwordx4 v[200:203], v[200:201], off offset:128
	v_or_b32_e32 v212, 16, v28
	v_lshlrev_b32_e32 v188, 11, v212
	v_mov_b32_e32 v189, v1
	v_lshl_add_u64 v[188:189], v[6:7], 0, v[188:189]
	global_load_dwordx2 v[188:189], v[188:189], off offset:64
	v_lshlrev_b32_e32 v204, 12, v212
	v_mov_b32_e32 v205, v1
	v_lshl_add_u64 v[204:205], v[8:9], 0, v[204:205]
	global_load_dwordx4 v[204:207], v[204:205], off offset:128
	v_or_b32_e32 v212, 24, v28
	v_lshlrev_b32_e32 v190, 11, v212
	v_mov_b32_e32 v191, v1
	v_lshl_add_u64 v[190:191], v[6:7], 0, v[190:191]
	global_load_dwordx2 v[190:191], v[190:191], off offset:64
	v_lshlrev_b32_e32 v208, 12, v212
	v_mov_b32_e32 v209, v1
	v_lshl_add_u64 v[208:209], v[8:9], 0, v[208:209]
	global_load_dwordx4 v[208:211], v[208:209], off offset:128
	s_waitcnt vmcnt(6)
	v_mov_b32_e32 v22, v184
	v_mov_b32_e32 v23, v185
	v_lshl_add_u64 v[24:25], v[4:5], 0, v[10:11]
	ds_read_b128 v[10:13], v0
	v_mov_b32_e32 v14, v180
	v_mov_b32_e32 v15, v181
	v_mov_b32_e32 v16, v182
	v_mov_b32_e32 v17, v183
	s_nop 0
	v_mov_b32_e32 v18, v192
	v_mov_b32_e32 v19, v193
	v_mov_b32_e32 v20, v194
	v_mov_b32_e32 v21, v195
	v_and_b32_e32 v27, 0xffff0000, v22
	v_lshlrev_b32_e32 v26, 16, v22
	v_pk_add_f32 v[18:19], v[18:19], v[26:27]
	s_waitcnt lgkmcnt(0)
	v_pk_fma_f32 v[10:11], v[10:11], v[14:15], v[18:19]
	v_and_b32_e32 v15, 0xffff0000, v23
	v_lshlrev_b32_e32 v14, 16, v23
	v_pk_add_f32 v[14:15], v[20:21], v[14:15]
	s_nop 0
	v_pk_fma_f32 v[12:13], v[12:13], v[16:17], v[14:15]
	global_store_dwordx4 v[24:25], v[10:13], off offset:128
	s_nop 1
	v_or_b32_e32 v12, 8, v28
	v_lshlrev_b32_e32 v10, 12, v12
	v_lshlrev_b32_e32 v12, 11, v12
	v_mov_b32_e32 v13, v1
	v_mov_b32_e32 v11, v1
	v_lshl_add_u64 v[12:13], v[6:7], 0, v[12:13]
	v_lshl_add_u64 v[18:19], v[8:9], 0, v[10:11]
	s_waitcnt vmcnt(5)
	v_mov_b32_e32 v22, v186
	v_mov_b32_e32 v23, v187
	v_lshl_add_u64 v[24:25], v[4:5], 0, v[10:11]
	ds_read_b128 v[10:13], v0 offset:1152
	v_mov_b32_e32 v14, v180
	v_mov_b32_e32 v15, v181
	v_mov_b32_e32 v16, v182
	v_mov_b32_e32 v17, v183
	s_nop 0
	v_mov_b32_e32 v18, v200
	v_mov_b32_e32 v19, v201
	v_mov_b32_e32 v20, v202
	v_mov_b32_e32 v21, v203
	v_and_b32_e32 v27, 0xffff0000, v22
	v_lshlrev_b32_e32 v26, 16, v22
	v_pk_add_f32 v[18:19], v[18:19], v[26:27]
	s_waitcnt lgkmcnt(0)
	v_pk_fma_f32 v[10:11], v[10:11], v[14:15], v[18:19]
	v_and_b32_e32 v15, 0xffff0000, v23
	v_lshlrev_b32_e32 v14, 16, v23
	v_pk_add_f32 v[14:15], v[20:21], v[14:15]
	s_nop 0
	v_pk_fma_f32 v[12:13], v[12:13], v[16:17], v[14:15]
	global_store_dwordx4 v[24:25], v[10:13], off offset:128
	s_nop 1
	v_or_b32_e32 v12, 16, v28
	v_lshlrev_b32_e32 v10, 12, v12
	v_lshlrev_b32_e32 v12, 11, v12
	v_mov_b32_e32 v13, v1
	v_mov_b32_e32 v11, v1
	v_lshl_add_u64 v[12:13], v[6:7], 0, v[12:13]
	v_lshl_add_u64 v[18:19], v[8:9], 0, v[10:11]
	s_waitcnt vmcnt(4)
	v_mov_b32_e32 v22, v188
	v_mov_b32_e32 v23, v189
	v_lshl_add_u64 v[24:25], v[4:5], 0, v[10:11]
	ds_read_b128 v[10:13], v0 offset:2304
	v_mov_b32_e32 v14, v180
	v_mov_b32_e32 v15, v181
	v_mov_b32_e32 v16, v182
	v_mov_b32_e32 v17, v183
	s_nop 0
	v_mov_b32_e32 v18, v204
	v_mov_b32_e32 v19, v205
	v_mov_b32_e32 v20, v206
	v_mov_b32_e32 v21, v207
	v_and_b32_e32 v27, 0xffff0000, v22
	v_lshlrev_b32_e32 v26, 16, v22
	v_pk_add_f32 v[18:19], v[18:19], v[26:27]
	s_waitcnt lgkmcnt(0)
	v_pk_fma_f32 v[10:11], v[10:11], v[14:15], v[18:19]
	v_and_b32_e32 v15, 0xffff0000, v23
	v_lshlrev_b32_e32 v14, 16, v23
	v_pk_add_f32 v[14:15], v[20:21], v[14:15]
	s_nop 0
	v_pk_fma_f32 v[12:13], v[12:13], v[16:17], v[14:15]
	v_or_b32_e32 v14, 24, v28
	global_store_dwordx4 v[24:25], v[10:13], off offset:128
	s_nop 1
	v_lshlrev_b32_e32 v10, 12, v14
	v_mov_b32_e32 v11, v1
	v_lshl_add_u64 v[12:13], v[8:9], 0, v[10:11]
	v_lshlrev_b32_e32 v8, 11, v14
	v_mov_b32_e32 v9, v1
	v_lshl_add_u64 v[6:7], v[6:7], 0, v[8:9]
	s_waitcnt vmcnt(3)
	v_mov_b32_e32 v16, v190
	v_mov_b32_e32 v17, v191
	v_lshl_add_u64 v[18:19], v[4:5], 0, v[10:11]
	ds_read_b128 v[4:7], v0 offset:3456
	v_mov_b32_e32 v8, v180
	v_mov_b32_e32 v9, v181
	v_mov_b32_e32 v10, v182
	v_mov_b32_e32 v11, v183
	s_nop 0
	v_mov_b32_e32 v12, v208
	v_mov_b32_e32 v13, v209
	v_mov_b32_e32 v14, v210
	v_mov_b32_e32 v15, v211
	v_and_b32_e32 v3, 0xffff0000, v16
	v_lshlrev_b32_e32 v2, 16, v16
	v_pk_add_f32 v[2:3], v[12:13], v[2:3]
	s_waitcnt lgkmcnt(0)
	v_pk_fma_f32 v[2:3], v[4:5], v[8:9], v[2:3]
	v_and_b32_e32 v5, 0xffff0000, v17
	v_lshlrev_b32_e32 v4, 16, v17
	v_pk_add_f32 v[4:5], v[14:15], v[4:5]
	s_nop 0
	v_pk_fma_f32 v[4:5], v[6:7], v[10:11], v[4:5]
	global_store_dwordx4 v[18:19], v[2:5], off offset:128
	s_add_i32 s7, s7, s6
	s_cmpk_gt_i32 s7, 0x1ff
	v_readlane_b32 s64, v254, 55
	v_readlane_b32 s38, v254, 57
	v_readlane_b32 s42, v254, 59
	s_cselect_b64 s[0:1], -1, 0
	v_readlane_b32 s65, v254, 56
	v_readlane_b32 s39, v254, 58
	v_readlane_b32 s43, v254, 60
	s_mov_b32 s51, s27
	s_movk_i32 s37, 0x1000
	s_movk_i32 s36, 0x1ff
	s_mov_b32 s47, 0x7f800000
	s_mov_b32 s49, 0x20000
	s_mov_b32 s46, 0x4081e0d3
	s_mov_b32 s48, 0xc09de9e6
	s_mov_b64 s[44:45], 0x800
	s_branch .LBB0_21

.Lg295_np:
	s_add_u32 m0, s9, 0x8020
	s_add_u32 s14, s1, s2
	s_addc_u32 s15, s5, s3
	global_load_lds_dwordx4 v159, s[14:15]
	s_add_u32 m0, s9, 0xa020
	s_add_u32 s14, s14, 0x20000
	s_addc_u32 s15, s15, 0
	global_load_lds_dwordx4 v159, s[14:15]
	s_add_u32 m0, s9, 0xc020
	s_add_u32 s14, s14, 0x20000
	s_addc_u32 s15, s15, 0
	global_load_lds_dwordx4 v159, s[14:15]
	s_add_u32 m0, s9, 0xe020
	s_add_u32 s14, s14, 0x20000
	s_addc_u32 s15, s15, 0
	global_load_lds_dwordx4 v159, s[14:15]
	ds_read_b128 v[130:133], v177 offset:0
	ds_read_b128 v[164:167], v207 offset:0
	ds_read_b128 v[168:171], v207 offset:4096
	ds_read_b128 v[134:137], v177 offset:4096
	ds_read_b128 v[138:141], v177 offset:8192
	ds_read_b128 v[160:163], v177 offset:12288
.Lg295_loop:
	s_waitcnt lgkmcnt(4)
	v_mfma_f32_32x32x16_bf16 v[114:129], v[130:133], v[164:167], v[114:129]
	ds_read_b128 v[172:175], v204 offset:0
	s_waitcnt lgkmcnt(4)
	v_mfma_f32_32x32x16_bf16 v[98:113], v[130:133], v[168:171], v[98:113]
	ds_read_b128 v[192:195], v208 offset:0
	s_add_u32 m0, s9, 0x18020
	s_add_u32 s14, s7, s2
	s_addc_u32 s15, s8, s3
	global_load_lds_dwordx4 v159, s[14:15]
	s_waitcnt lgkmcnt(4)
	v_mfma_f32_32x32x16_bf16 v[82:97], v[134:137], v[164:167], v[82:97]
	ds_read_b128 v[200:203], v208 offset:4096
	v_mfma_f32_32x32x16_bf16 v[66:81], v[134:137], v[168:171], v[66:81]
	ds_read_b128 v[180:183], v204 offset:4096
	s_add_u32 m0, s9, 0x1a020
	s_add_u32 s14, s14, 0x20000
	s_addc_u32 s15, s15, 0
	global_load_lds_dwordx4 v159, s[14:15]
	s_waitcnt lgkmcnt(5)
	v_mfma_f32_32x32x16_bf16 v[50:65], v[138:141], v[164:167], v[50:65]
	ds_read_b128 v[184:187], v204 offset:8192
	v_mfma_f32_32x32x16_bf16 v[34:49], v[138:141], v[168:171], v[34:49]
	ds_read_b128 v[188:191], v204 offset:12288
	s_add_u32 m0, s9, 0x1c020
	s_add_u32 s14, s14, 0x20000
	s_addc_u32 s15, s15, 0
	global_load_lds_dwordx4 v159, s[14:15]
	s_waitcnt lgkmcnt(6)
	v_mfma_f32_32x32x16_bf16 v[18:33], v[160:163], v[164:167], v[18:33]
	v_mfma_f32_32x32x16_bf16 v[2:17], v[160:163], v[168:171], v[2:17]
	s_add_u32 m0, s9, 0x1e020
	s_add_u32 s14, s14, 0x20000
	s_addc_u32 s15, s15, 0
	global_load_lds_dwordx4 v159, s[14:15]
	s_add_u32 s2, s2, 0x80
	s_addc_u32 s3, s3, 0
	s_waitcnt lgkmcnt(4)
	v_mfma_f32_32x32x16_bf16 v[114:129], v[172:175], v[192:195], v[114:129]
	ds_read_b128 v[130:133], v205 offset:0
	s_waitcnt lgkmcnt(4)
	v_mfma_f32_32x32x16_bf16 v[98:113], v[172:175], v[200:203], v[98:113]
	ds_read_b128 v[164:167], v209 offset:0
	s_waitcnt lgkmcnt(4)
	v_mfma_f32_32x32x16_bf16 v[82:97], v[180:183], v[192:195], v[82:97]
	ds_read_b128 v[168:171], v209 offset:4096
	v_mfma_f32_32x32x16_bf16 v[66:81], v[180:183], v[200:203], v[66:81]
	ds_read_b128 v[134:137], v205 offset:4096
	s_waitcnt lgkmcnt(5)
	v_mfma_f32_32x32x16_bf16 v[50:65], v[184:187], v[192:195], v[50:65]
	ds_read_b128 v[138:141], v205 offset:8192
	v_mfma_f32_32x32x16_bf16 v[34:49], v[184:187], v[200:203], v[34:49]
	ds_read_b128 v[160:163], v205 offset:12288
	s_waitcnt lgkmcnt(6)
	v_mfma_f32_32x32x16_bf16 v[18:33], v[188:191], v[192:195], v[18:33]
	v_mfma_f32_32x32x16_bf16 v[2:17], v[188:191], v[200:203], v[2:17]
	s_waitcnt lgkmcnt(4)
	v_mfma_f32_32x32x16_bf16 v[114:129], v[130:133], v[164:167], v[114:129]
	ds_read_b128 v[172:175], v206 offset:0
	ds_read_b128 v[192:195], v210 offset:0
	s_waitcnt lgkmcnt(5)
	v_mfma_f32_32x32x16_bf16 v[98:113], v[130:133], v[168:171], v[98:113]
	ds_read_b128 v[200:203], v210 offset:4096
	ds_read_b128 v[180:183], v206 offset:4096
	s_waitcnt lgkmcnt(6)
	v_mfma_f32_32x32x16_bf16 v[82:97], v[134:137], v[164:167], v[82:97]
	ds_read_b128 v[184:187], v206 offset:8192
	ds_read_b128 v[188:191], v206 offset:12288
	v_mfma_f32_32x32x16_bf16 v[66:81], v[134:137], v[168:171], v[66:81]
	s_waitcnt lgkmcnt(7)
	v_mfma_f32_32x32x16_bf16 v[50:65], v[138:141], v[164:167], v[50:65]
	v_mfma_f32_32x32x16_bf16 v[34:49], v[138:141], v[168:171], v[34:49]
	s_waitcnt lgkmcnt(6)
	v_mfma_f32_32x32x16_bf16 v[18:33], v[160:163], v[164:167], v[18:33]
	v_mfma_f32_32x32x16_bf16 v[2:17], v[160:163], v[168:171], v[2:17]
	s_waitcnt vmcnt(0) lgkmcnt(0)
	s_barrier
	v_mfma_f32_32x32x16_bf16 v[114:129], v[172:175], v[192:195], v[114:129]
	ds_read_b128 v[130:133], v177 offset:32768
	v_mfma_f32_32x32x16_bf16 v[98:113], v[172:175], v[200:203], v[98:113]
	ds_read_b128 v[164:167], v207 offset:32768
	s_add_u32 m0, s9, 0x20
	s_add_u32 s14, s1, s2
	s_addc_u32 s15, s5, s3
	global_load_lds_dwordx4 v159, s[14:15]
	v_mfma_f32_32x32x16_bf16 v[82:97], v[180:183], v[192:195], v[82:97]
	ds_read_b128 v[168:171], v207 offset:36864
	v_mfma_f32_32x32x16_bf16 v[66:81], v[180:183], v[200:203], v[66:81]
	ds_read_b128 v[134:137], v177 offset:36864
	s_add_u32 m0, s9, 0x2020
	s_add_u32 s14, s14, 0x20000
	s_addc_u32 s15, s15, 0
	global_load_lds_dwordx4 v159, s[14:15]
	v_mfma_f32_32x32x16_bf16 v[50:65], v[184:187], v[192:195], v[50:65]
	ds_read_b128 v[138:141], v177 offset:40960
	v_mfma_f32_32x32x16_bf16 v[34:49], v[184:187], v[200:203], v[34:49]
	ds_read_b128 v[160:163], v177 offset:45056
	s_add_u32 m0, s9, 0x4020
	s_add_u32 s14, s14, 0x20000
	s_addc_u32 s15, s15, 0
	global_load_lds_dwordx4 v159, s[14:15]
	v_mfma_f32_32x32x16_bf16 v[18:33], v[188:191], v[192:195], v[18:33]
	v_mfma_f32_32x32x16_bf16 v[2:17], v[188:191], v[200:203], v[2:17]
	s_add_u32 m0, s9, 0x6020
	s_add_u32 s14, s14, 0x20000
	s_addc_u32 s15, s15, 0
	global_load_lds_dwordx4 v159, s[14:15]
	s_waitcnt lgkmcnt(4)
	v_mfma_f32_32x32x16_bf16 v[114:129], v[130:133], v[164:167], v[114:129]
	ds_read_b128 v[172:175], v204 offset:32768
	s_waitcnt lgkmcnt(4)
	v_mfma_f32_32x32x16_bf16 v[98:113], v[130:133], v[168:171], v[98:113]
	ds_read_b128 v[192:195], v208 offset:32768
	s_add_u32 m0, s9, 0x10020
	s_add_u32 s14, s7, s2
	s_addc_u32 s15, s8, s3
	global_load_lds_dwordx4 v159, s[14:15]
	s_waitcnt lgkmcnt(4)
	v_mfma_f32_32x32x16_bf16 v[82:97], v[134:137], v[164:167], v[82:97]
	ds_read_b128 v[200:203], v208 offset:36864
	v_mfma_f32_32x32x16_bf16 v[66:81], v[134:137], v[168:171], v[66:81]
	ds_read_b128 v[180:183], v204 offset:36864
	s_add_u32 m0, s9, 0x12020
	s_add_u32 s14, s14, 0x20000
	s_addc_u32 s15, s15, 0
	global_load_lds_dwordx4 v159, s[14:15]
	s_waitcnt lgkmcnt(5)
	v_mfma_f32_32x32x16_bf16 v[50:65], v[138:141], v[164:167], v[50:65]
	ds_read_b128 v[184:187], v204 offset:40960
	v_mfma_f32_32x32x16_bf16 v[34:49], v[138:141], v[168:171], v[34:49]
	ds_read_b128 v[188:191], v204 offset:45056
	s_add_u32 m0, s9, 0x14020
	s_add_u32 s14, s14, 0x20000
	s_addc_u32 s15, s15, 0
	global_load_lds_dwordx4 v159, s[14:15]
	s_waitcnt lgkmcnt(6)
	v_mfma_f32_32x32x16_bf16 v[18:33], v[160:163], v[164:167], v[18:33]
	v_mfma_f32_32x32x16_bf16 v[2:17], v[160:163], v[168:171], v[2:17]
	s_add_u32 m0, s9, 0x16020
	s_add_u32 s14, s14, 0x20000
	s_addc_u32 s15, s15, 0
	global_load_lds_dwordx4 v159, s[14:15]
	s_add_u32 s2, s2, 0x80
	s_addc_u32 s3, s3, 0
	s_waitcnt lgkmcnt(4)
	v_mfma_f32_32x32x16_bf16 v[114:129], v[172:175], v[192:195], v[114:129]
	ds_read_b128 v[130:133], v205 offset:32768
	s_waitcnt lgkmcnt(4)
	v_mfma_f32_32x32x16_bf16 v[98:113], v[172:175], v[200:203], v[98:113]
	ds_read_b128 v[164:167], v209 offset:32768
	s_waitcnt lgkmcnt(4)
	v_mfma_f32_32x32x16_bf16 v[82:97], v[180:183], v[192:195], v[82:97]
	ds_read_b128 v[168:171], v209 offset:36864
	v_mfma_f32_32x32x16_bf16 v[66:81], v[180:183], v[200:203], v[66:81]
	ds_read_b128 v[134:137], v205 offset:36864
	s_waitcnt lgkmcnt(5)
	v_mfma_f32_32x32x16_bf16 v[50:65], v[184:187], v[192:195], v[50:65]
	ds_read_b128 v[138:141], v205 offset:40960
	v_mfma_f32_32x32x16_bf16 v[34:49], v[184:187], v[200:203], v[34:49]
	ds_read_b128 v[160:163], v205 offset:45056
	s_waitcnt lgkmcnt(6)
	v_mfma_f32_32x32x16_bf16 v[18:33], v[188:191], v[192:195], v[18:33]
	v_mfma_f32_32x32x16_bf16 v[2:17], v[188:191], v[200:203], v[2:17]
	s_waitcnt lgkmcnt(4)
	v_mfma_f32_32x32x16_bf16 v[114:129], v[130:133], v[164:167], v[114:129]
	ds_read_b128 v[172:175], v206 offset:32768
	ds_read_b128 v[192:195], v210 offset:32768
	s_waitcnt lgkmcnt(5)
	v_mfma_f32_32x32x16_bf16 v[98:113], v[130:133], v[168:171], v[98:113]
	ds_read_b128 v[200:203], v210 offset:36864
	ds_read_b128 v[180:183], v206 offset:36864
	s_waitcnt lgkmcnt(6)
	v_mfma_f32_32x32x16_bf16 v[82:97], v[134:137], v[164:167], v[82:97]
	ds_read_b128 v[184:187], v206 offset:40960
	ds_read_b128 v[188:191], v206 offset:45056
	v_mfma_f32_32x32x16_bf16 v[66:81], v[134:137], v[168:171], v[66:81]
	s_waitcnt lgkmcnt(7)
	v_mfma_f32_32x32x16_bf16 v[50:65], v[138:141], v[164:167], v[50:65]
	v_mfma_f32_32x32x16_bf16 v[34:49], v[138:141], v[168:171], v[34:49]
	s_waitcnt lgkmcnt(6)
	v_mfma_f32_32x32x16_bf16 v[18:33], v[160:163], v[164:167], v[18:33]
	v_mfma_f32_32x32x16_bf16 v[2:17], v[160:163], v[168:171], v[2:17]
	s_waitcnt vmcnt(0) lgkmcnt(0)
	s_barrier
	v_mfma_f32_32x32x16_bf16 v[114:129], v[172:175], v[192:195], v[114:129]
	ds_read_b128 v[130:133], v177 offset:0
	v_mfma_f32_32x32x16_bf16 v[98:113], v[172:175], v[200:203], v[98:113]
	ds_read_b128 v[164:167], v207 offset:0
	s_add_u32 m0, s9, 0x8020
	s_add_u32 s14, s1, s2
	s_addc_u32 s15, s5, s3
	global_load_lds_dwordx4 v159, s[14:15]
	v_mfma_f32_32x32x16_bf16 v[82:97], v[180:183], v[192:195], v[82:97]
	ds_read_b128 v[168:171], v207 offset:4096
	v_mfma_f32_32x32x16_bf16 v[66:81], v[180:183], v[200:203], v[66:81]
	ds_read_b128 v[134:137], v177 offset:4096
	s_add_u32 m0, s9, 0xa020
	s_add_u32 s14, s14, 0x20000
	s_addc_u32 s15, s15, 0
	global_load_lds_dwordx4 v159, s[14:15]
	v_mfma_f32_32x32x16_bf16 v[50:65], v[184:187], v[192:195], v[50:65]
	ds_read_b128 v[138:141], v177 offset:8192
	v_mfma_f32_32x32x16_bf16 v[34:49], v[184:187], v[200:203], v[34:49]
	ds_read_b128 v[160:163], v177 offset:12288
	s_add_u32 m0, s9, 0xc020
	s_add_u32 s14, s14, 0x20000
	s_addc_u32 s15, s15, 0
	global_load_lds_dwordx4 v159, s[14:15]
	v_mfma_f32_32x32x16_bf16 v[18:33], v[188:191], v[192:195], v[18:33]
	v_mfma_f32_32x32x16_bf16 v[2:17], v[188:191], v[200:203], v[2:17]
	s_add_u32 m0, s9, 0xe020
	s_add_u32 s14, s14, 0x20000
	s_addc_u32 s15, s15, 0
	global_load_lds_dwordx4 v159, s[14:15]
	s_sub_u32 s6, s6, 1
	s_cmp_lg_u32 s6, 0
	s_cbranch_scc1 .Lg295_loop
	s_waitcnt lgkmcnt(4)
	v_mfma_f32_32x32x16_bf16 v[114:129], v[130:133], v[164:167], v[114:129]
	ds_read_b128 v[172:175], v204 offset:0
	s_waitcnt lgkmcnt(4)
	v_mfma_f32_32x32x16_bf16 v[98:113], v[130:133], v[168:171], v[98:113]
	ds_read_b128 v[192:195], v208 offset:0
	s_add_u32 m0, s9, 0x18020
	s_add_u32 s14, s7, s2
	s_addc_u32 s15, s8, s3
	global_load_lds_dwordx4 v159, s[14:15]
	s_waitcnt lgkmcnt(4)
	v_mfma_f32_32x32x16_bf16 v[82:97], v[134:137], v[164:167], v[82:97]
	ds_read_b128 v[200:203], v208 offset:4096
	v_mfma_f32_32x32x16_bf16 v[66:81], v[134:137], v[168:171], v[66:81]
	ds_read_b128 v[180:183], v204 offset:4096
	s_add_u32 m0, s9, 0x1a020
	s_add_u32 s14, s14, 0x20000
	s_addc_u32 s15, s15, 0
	global_load_lds_dwordx4 v159, s[14:15]
	s_waitcnt lgkmcnt(5)
	v_mfma_f32_32x32x16_bf16 v[50:65], v[138:141], v[164:167], v[50:65]
	ds_read_b128 v[184:187], v204 offset:8192
	v_mfma_f32_32x32x16_bf16 v[34:49], v[138:141], v[168:171], v[34:49]
	ds_read_b128 v[188:191], v204 offset:12288
	s_add_u32 m0, s9, 0x1c020
	s_add_u32 s14, s14, 0x20000
	s_addc_u32 s15, s15, 0
	global_load_lds_dwordx4 v159, s[14:15]
	s_waitcnt lgkmcnt(6)
	v_mfma_f32_32x32x16_bf16 v[18:33], v[160:163], v[164:167], v[18:33]
	v_mfma_f32_32x32x16_bf16 v[2:17], v[160:163], v[168:171], v[2:17]
	s_add_u32 m0, s9, 0x1e020
	s_add_u32 s14, s14, 0x20000
	s_addc_u32 s15, s15, 0
	global_load_lds_dwordx4 v159, s[14:15]
	s_add_u32 s2, s2, 0x80
	s_addc_u32 s3, s3, 0
	s_waitcnt lgkmcnt(4)
	v_mfma_f32_32x32x16_bf16 v[114:129], v[172:175], v[192:195], v[114:129]
	ds_read_b128 v[130:133], v205 offset:0
	s_waitcnt lgkmcnt(4)
	v_mfma_f32_32x32x16_bf16 v[98:113], v[172:175], v[200:203], v[98:113]
	ds_read_b128 v[164:167], v209 offset:0
	s_waitcnt lgkmcnt(4)
	v_mfma_f32_32x32x16_bf16 v[82:97], v[180:183], v[192:195], v[82:97]
	ds_read_b128 v[168:171], v209 offset:4096
	v_mfma_f32_32x32x16_bf16 v[66:81], v[180:183], v[200:203], v[66:81]
	ds_read_b128 v[134:137], v205 offset:4096
	s_waitcnt lgkmcnt(5)
	v_mfma_f32_32x32x16_bf16 v[50:65], v[184:187], v[192:195], v[50:65]
	ds_read_b128 v[138:141], v205 offset:8192
	v_mfma_f32_32x32x16_bf16 v[34:49], v[184:187], v[200:203], v[34:49]
	ds_read_b128 v[160:163], v205 offset:12288
	s_waitcnt lgkmcnt(6)
	v_mfma_f32_32x32x16_bf16 v[18:33], v[188:191], v[192:195], v[18:33]
	v_mfma_f32_32x32x16_bf16 v[2:17], v[188:191], v[200:203], v[2:17]
	s_waitcnt lgkmcnt(4)
	v_mfma_f32_32x32x16_bf16 v[114:129], v[130:133], v[164:167], v[114:129]
	ds_read_b128 v[172:175], v206 offset:0
	ds_read_b128 v[192:195], v210 offset:0
	s_waitcnt lgkmcnt(5)
	v_mfma_f32_32x32x16_bf16 v[98:113], v[130:133], v[168:171], v[98:113]
	ds_read_b128 v[200:203], v210 offset:4096
	ds_read_b128 v[180:183], v206 offset:4096
	s_waitcnt lgkmcnt(6)
	v_mfma_f32_32x32x16_bf16 v[82:97], v[134:137], v[164:167], v[82:97]
	ds_read_b128 v[184:187], v206 offset:8192
	ds_read_b128 v[188:191], v206 offset:12288
	v_mfma_f32_32x32x16_bf16 v[66:81], v[134:137], v[168:171], v[66:81]
	s_waitcnt lgkmcnt(7)
	v_mfma_f32_32x32x16_bf16 v[50:65], v[138:141], v[164:167], v[50:65]
	v_mfma_f32_32x32x16_bf16 v[34:49], v[138:141], v[168:171], v[34:49]
	s_waitcnt lgkmcnt(6)
	v_mfma_f32_32x32x16_bf16 v[18:33], v[160:163], v[164:167], v[18:33]
	v_mfma_f32_32x32x16_bf16 v[2:17], v[160:163], v[168:171], v[2:17]
	s_waitcnt vmcnt(0) lgkmcnt(0)
	s_barrier
	v_mfma_f32_32x32x16_bf16 v[114:129], v[172:175], v[192:195], v[114:129]
	ds_read_b128 v[130:133], v177 offset:32768
	v_mfma_f32_32x32x16_bf16 v[98:113], v[172:175], v[200:203], v[98:113]
	ds_read_b128 v[164:167], v207 offset:32768
	v_mfma_f32_32x32x16_bf16 v[82:97], v[180:183], v[192:195], v[82:97]
	ds_read_b128 v[168:171], v207 offset:36864
	v_mfma_f32_32x32x16_bf16 v[66:81], v[180:183], v[200:203], v[66:81]
	ds_read_b128 v[134:137], v177 offset:36864
	v_mfma_f32_32x32x16_bf16 v[50:65], v[184:187], v[192:195], v[50:65]
	ds_read_b128 v[138:141], v177 offset:40960
	v_mfma_f32_32x32x16_bf16 v[34:49], v[184:187], v[200:203], v[34:49]
	ds_read_b128 v[160:163], v177 offset:45056
	v_mfma_f32_32x32x16_bf16 v[18:33], v[188:191], v[192:195], v[18:33]
	v_mfma_f32_32x32x16_bf16 v[2:17], v[188:191], v[200:203], v[2:17]
	s_waitcnt lgkmcnt(4)
	v_mfma_f32_32x32x16_bf16 v[114:129], v[130:133], v[164:167], v[114:129]
	ds_read_b128 v[172:175], v204 offset:32768
	s_waitcnt lgkmcnt(4)
	v_mfma_f32_32x32x16_bf16 v[98:113], v[130:133], v[168:171], v[98:113]
	ds_read_b128 v[192:195], v208 offset:32768
	s_waitcnt lgkmcnt(4)
	v_mfma_f32_32x32x16_bf16 v[82:97], v[134:137], v[164:167], v[82:97]
	ds_read_b128 v[200:203], v208 offset:36864
	v_mfma_f32_32x32x16_bf16 v[66:81], v[134:137], v[168:171], v[66:81]
	ds_read_b128 v[180:183], v204 offset:36864
	s_waitcnt lgkmcnt(5)
	v_mfma_f32_32x32x16_bf16 v[50:65], v[138:141], v[164:167], v[50:65]
	ds_read_b128 v[184:187], v204 offset:40960
	v_mfma_f32_32x32x16_bf16 v[34:49], v[138:141], v[168:171], v[34:49]
	ds_read_b128 v[188:191], v204 offset:45056
	s_waitcnt lgkmcnt(6)
	v_mfma_f32_32x32x16_bf16 v[18:33], v[160:163], v[164:167], v[18:33]
	v_mfma_f32_32x32x16_bf16 v[2:17], v[160:163], v[168:171], v[2:17]
	s_waitcnt lgkmcnt(4)
	v_mfma_f32_32x32x16_bf16 v[114:129], v[172:175], v[192:195], v[114:129]
	ds_read_b128 v[130:133], v205 offset:32768
	s_waitcnt lgkmcnt(4)
	v_mfma_f32_32x32x16_bf16 v[98:113], v[172:175], v[200:203], v[98:113]
	ds_read_b128 v[164:167], v209 offset:32768
	s_waitcnt lgkmcnt(4)
	v_mfma_f32_32x32x16_bf16 v[82:97], v[180:183], v[192:195], v[82:97]
	ds_read_b128 v[168:171], v209 offset:36864
	v_mfma_f32_32x32x16_bf16 v[66:81], v[180:183], v[200:203], v[66:81]
	ds_read_b128 v[134:137], v205 offset:36864
	s_waitcnt lgkmcnt(5)
	v_mfma_f32_32x32x16_bf16 v[50:65], v[184:187], v[192:195], v[50:65]
	ds_read_b128 v[138:141], v205 offset:40960
	v_mfma_f32_32x32x16_bf16 v[34:49], v[184:187], v[200:203], v[34:49]
	ds_read_b128 v[160:163], v205 offset:45056
	s_waitcnt lgkmcnt(6)
	v_mfma_f32_32x32x16_bf16 v[18:33], v[188:191], v[192:195], v[18:33]
	v_mfma_f32_32x32x16_bf16 v[2:17], v[188:191], v[200:203], v[2:17]
	s_waitcnt lgkmcnt(4)
	v_mfma_f32_32x32x16_bf16 v[114:129], v[130:133], v[164:167], v[114:129]
	ds_read_b128 v[172:175], v206 offset:32768
	ds_read_b128 v[192:195], v210 offset:32768
	s_waitcnt lgkmcnt(5)
	v_mfma_f32_32x32x16_bf16 v[98:113], v[130:133], v[168:171], v[98:113]
	ds_read_b128 v[200:203], v210 offset:36864
	ds_read_b128 v[180:183], v206 offset:36864
	s_waitcnt lgkmcnt(6)
	v_mfma_f32_32x32x16_bf16 v[82:97], v[134:137], v[164:167], v[82:97]
	ds_read_b128 v[184:187], v206 offset:40960
	ds_read_b128 v[188:191], v206 offset:45056
	v_mfma_f32_32x32x16_bf16 v[66:81], v[134:137], v[168:171], v[66:81]
	s_waitcnt lgkmcnt(7)
	v_mfma_f32_32x32x16_bf16 v[50:65], v[138:141], v[164:167], v[50:65]
	v_mfma_f32_32x32x16_bf16 v[34:49], v[138:141], v[168:171], v[34:49]
	s_waitcnt lgkmcnt(6)
	v_mfma_f32_32x32x16_bf16 v[18:33], v[160:163], v[164:167], v[18:33]
	v_mfma_f32_32x32x16_bf16 v[2:17], v[160:163], v[168:171], v[2:17]
	s_waitcnt vmcnt(0) lgkmcnt(0)
	s_barrier
	v_mfma_f32_32x32x16_bf16 v[114:129], v[172:175], v[192:195], v[114:129]
	v_mfma_f32_32x32x16_bf16 v[98:113], v[172:175], v[200:203], v[98:113]
	v_mfma_f32_32x32x16_bf16 v[82:97], v[180:183], v[192:195], v[82:97]
	v_mfma_f32_32x32x16_bf16 v[66:81], v[180:183], v[200:203], v[66:81]
	v_mfma_f32_32x32x16_bf16 v[50:65], v[184:187], v[192:195], v[50:65]
	v_mfma_f32_32x32x16_bf16 v[34:49], v[184:187], v[200:203], v[34:49]
	v_mfma_f32_32x32x16_bf16 v[18:33], v[188:191], v[192:195], v[18:33]
	v_mfma_f32_32x32x16_bf16 v[2:17], v[188:191], v[200:203], v[2:17]
	s_setprio 0
	v_add_u32_e32 v159, s0, v153
	s_mov_b32 s0, 0x7e07e07f
	v_mul_hi_i32 v0, v159, s0
	v_lshrrev_b32_e32 v133, 31, v0
	v_ashrrev_i32_e32 v0, 13, v0
	v_add_u32_e32 v134, v0, v133
	v_mul_i32_i24_e32 v0, 0x4100, v134
	v_sub_u32_e32 v136, v159, v0
	s_movk_i32 s0, 0x100
	v_cmp_gt_i32_e64 s[56:57], s0, v136
	v_ashrrev_i32_e32 v137, 31, v136
	s_mov_b32 s0, 0xfff00000
	s_waitcnt vmcnt(0)
	v_ashrrev_i32_e32 v130, 7, v159
	v_lshlrev_b64 v[136:137], 12, v[136:137]
	s_mov_b32 s1, -1
	v_or_b32_e32 v132, s4, v154
	v_ashrrev_i32_e32 v131, 31, v130
	v_ashrrev_i32_e32 v135, 31, v134
	v_lshl_add_u64 v[136:137], v[136:137], 0, s[0:1]
	s_movk_i32 s0, 0x1840
	v_lshlrev_b64 v[130:131], 14, v[130:131]
	v_lshlrev_b64 v[134:135], 26, v[134:135]
	v_mov_b32_e32 v161, v179
	v_cmp_gt_i32_e64 s[54:55], s0, v132
	s_barrier
	s_and_saveexec_b64 s[2:3], s[54:55]
	s_cbranch_execz .LBB0_371
	s_movk_i32 s0, 0x7ff
	v_cmp_lt_i32_e32 vcc, s0, v132
	s_xor_b64 s[0:1], s[56:57], -1
	s_or_b64 s[0:1], vcc, s[0:1]
	s_and_b64 exec, exec, s[0:1]
	s_cbranch_execz .LBB0_371
	v_bfe_u32 v0, v161, 5, 1
	v_mul_u32_u24_e32 v0, 0x90, v0
	v_lshlrev_b32_e32 v133, 2, v161
	v_lshlrev_b32_e32 v0, 2, v0
	v_and_b32_e32 v133, 0x7c, v133
	v_add3_u32 v138, v155, v0, v133
	v_add3_u32 v0, v155, v133, v0
	ds_write_b32 v138, v114
	v_add_u32_e32 v114, 0x100, v0
	ds_write2_b32 v114, v117, v118 offset0:44 offset1:224
	v_add_u32_e32 v114, 0x400, v0
	ds_write2_b32 v114, v119, v120 offset0:68 offset1:104
	v_add_u32_e32 v114, 0x600, v0
	ds_write2_b32 v114, v121, v122 offset0:12 offset1:192
	v_add_u32_e32 v114, 0x800, v0
	ds_write2_b32 v114, v123, v124 offset0:100 offset1:136
	v_add_u32_e32 v114, 0xa00, v0
	ds_write2_b32 v114, v125, v126 offset0:44 offset1:224
	v_add_u32_e32 v114, 0xc00, v0
	ds_write2_b32 v0, v115, v116 offset0:36 offset1:72
	ds_write2_b32 v114, v127, v128 offset0:132 offset1:168
	ds_write_b32 v0, v129 offset:3888
	s_waitcnt lgkmcnt(0)
	v_and_b32_e32 v160, 63, v161
	s_and_saveexec_b64 s[0:1], vcc
	s_xor_b64 s[6:7], exec, s[0:1]
	s_cbranch_execz .LBB0_369
	s_cmpk_gt_u32 s4, 0x17ff
	s_mov_b64 s[0:1], -1
	s_cbranch_scc0 .LBB0_365
	v_readlane_b32 s16, v251, 2
	v_lshlrev_b32_e32 v116, 3, v161
	v_add_u32_e32 v0, 0xffffe800, v132
	v_readlane_b32 s17, v251, 3
	v_and_b32_e32 v116, 24, v116
	v_lshlrev_b32_e32 v140, 2, v116
	v_lshl_add_u64 v[114:115], v[0:1], 2, s[16:17]
	v_mov_b32_e32 v141, v1
	v_lshl_add_u64 v[138:139], v[114:115], 0, v[140:141]
	global_load_dwordx4 v[122:125], v[138:139], off
	global_load_dwordx4 v[114:117], v[138:139], off offset:16
	v_add_u32_e32 v162, v155, v140
	v_lshrrev_b32_e32 v133, 2, v160
	s_movk_i32 s0, 0x90
	v_mad_u32_u24 v118, v133, s0, v162
	ds_read_b128 v[126:129], v118
	ds_read_b128 v[118:121], v118 offset:16
	s_mov_b32 s0, 0xbfb8aa3b
	v_readlane_b32 s18, v251, 4
	v_readlane_b32 s19, v251, 5
	v_readlane_b32 s20, v251, 6
	v_readlane_b32 s21, v251, 7
	v_readlane_b32 s22, v251, 8
	v_readlane_b32 s23, v251, 9
	v_readlane_b32 s24, v251, 10
	v_readlane_b32 s25, v251, 11
	v_readlane_b32 s26, v251, 12
	v_readlane_b32 s27, v251, 13
	v_readlane_b32 s28, v251, 14
	v_readlane_b32 s29, v251, 15
	v_readlane_b32 s30, v251, 16
	v_readlane_b32 s31, v251, 17
	s_waitcnt vmcnt(1) lgkmcnt(1)
	v_add_f32_e32 v122, v126, v122
	v_mul_f32_e64 v126, |v122|, s0
	v_exp_f32_e32 v141, v126
	s_mov_b32 s0, 0x3c23d70a
	v_cmp_ngt_f32_e32 vcc, s0, v141
	s_and_saveexec_b64 s[0:1], vcc
	s_xor_b64 s[8:9], exec, s[0:1]
	s_cbranch_execz .LBB0_302
	v_add_f32_e32 v126, 1.0, v141
	s_mov_b32 s0, 0x800000
	v_cmp_gt_f32_e32 vcc, s0, v126
	s_mov_b32 s0, 0x3f317217
	s_nop 0
	v_cndmask_b32_e64 v141, 0, 32, vcc
	v_ldexp_f32 v126, v126, v141
	v_log_f32_e32 v126, v126
	s_nop 0
	v_mul_f32_e32 v141, 0x3f317217, v126
	v_fma_f32 v141, v126, s0, -v141
	v_fmac_f32_e32 v141, 0x3377d1cf, v126
	v_fmac_f32_e32 v141, 0x3f317217, v126
	v_cmp_lt_f32_e64 s[0:1], |v126|, s47
	s_nop 1
	v_cndmask_b32_e64 v126, v126, v141, s[0:1]
	v_cndmask_b32_e32 v141, 0, v238, vcc
	v_sub_f32_e32 v126, v126, v141

.Lg910_np:
	s_add_u32 m0, s14, 0x8020
	s_add_u32 s12, s1, s4
	s_addc_u32 s13, s3, s5
	global_load_lds_dwordx4 v149, s[12:13]
	s_add_u32 m0, s14, 0xa020
	s_add_u32 s12, s12, 0x20000
	s_addc_u32 s13, s13, 0
	global_load_lds_dwordx4 v149, s[12:13]
	s_add_u32 m0, s14, 0xc020
	s_add_u32 s12, s12, 0x20000
	s_addc_u32 s13, s13, 0
	global_load_lds_dwordx4 v149, s[12:13]
	s_add_u32 m0, s14, 0xe020
	s_add_u32 s12, s12, 0x20000
	s_addc_u32 s13, s13, 0
	global_load_lds_dwordx4 v149, s[12:13]
	ds_read_b128 v[150:153], v205 offset:0
	ds_read_b128 v[166:169], v209 offset:0
	ds_read_b128 v[170:173], v209 offset:4096
	ds_read_b128 v[154:157], v205 offset:4096
	ds_read_b128 v[158:161], v205 offset:8192
	ds_read_b128 v[162:165], v205 offset:12288
.Lg910_loop:
	s_waitcnt lgkmcnt(4)
	v_mfma_f32_32x32x16_bf16 v[114:129], v[150:153], v[166:169], v[114:129]
	ds_read_b128 v[174:177], v206 offset:0
	s_waitcnt lgkmcnt(4)
	v_mfma_f32_32x32x16_bf16 v[98:113], v[150:153], v[170:173], v[98:113]
	ds_read_b128 v[192:195], v210 offset:0
	s_add_u32 m0, s14, 0x18020
	s_add_u32 s12, s10, s4
	s_addc_u32 s13, s11, s5
	global_load_lds_dwordx4 v149, s[12:13]
	s_waitcnt lgkmcnt(4)
	v_mfma_f32_32x32x16_bf16 v[82:97], v[154:157], v[166:169], v[82:97]
	ds_read_b128 v[200:203], v210 offset:4096
	v_mfma_f32_32x32x16_bf16 v[66:81], v[154:157], v[170:173], v[66:81]
	ds_read_b128 v[180:183], v206 offset:4096
	s_add_u32 m0, s14, 0x1a020
	s_add_u32 s12, s12, 0x20000
	s_addc_u32 s13, s13, 0
	global_load_lds_dwordx4 v149, s[12:13]
	s_waitcnt lgkmcnt(5)
	v_mfma_f32_32x32x16_bf16 v[50:65], v[158:161], v[166:169], v[50:65]
	ds_read_b128 v[184:187], v206 offset:8192
	v_mfma_f32_32x32x16_bf16 v[34:49], v[158:161], v[170:173], v[34:49]
	ds_read_b128 v[188:191], v206 offset:12288
	s_add_u32 m0, s14, 0x1c020
	s_add_u32 s12, s12, 0x20000
	s_addc_u32 s13, s13, 0
	global_load_lds_dwordx4 v149, s[12:13]
	s_waitcnt lgkmcnt(6)
	v_mfma_f32_32x32x16_bf16 v[18:33], v[162:165], v[166:169], v[18:33]
	v_mfma_f32_32x32x16_bf16 v[2:17], v[162:165], v[170:173], v[2:17]
	s_add_u32 m0, s14, 0x1e020
	s_add_u32 s12, s12, 0x20000
	s_addc_u32 s13, s13, 0
	global_load_lds_dwordx4 v149, s[12:13]
	s_add_u32 s4, s4, 0x80
	s_addc_u32 s5, s5, 0
	s_waitcnt lgkmcnt(4)
	v_mfma_f32_32x32x16_bf16 v[114:129], v[174:177], v[192:195], v[114:129]
	ds_read_b128 v[150:153], v207 offset:0
	s_waitcnt lgkmcnt(4)
	v_mfma_f32_32x32x16_bf16 v[98:113], v[174:177], v[200:203], v[98:113]
	ds_read_b128 v[166:169], v211 offset:0
	s_waitcnt lgkmcnt(4)
	v_mfma_f32_32x32x16_bf16 v[82:97], v[180:183], v[192:195], v[82:97]
	ds_read_b128 v[170:173], v211 offset:4096
	v_mfma_f32_32x32x16_bf16 v[66:81], v[180:183], v[200:203], v[66:81]
	ds_read_b128 v[154:157], v207 offset:4096
	s_waitcnt lgkmcnt(5)
	v_mfma_f32_32x32x16_bf16 v[50:65], v[184:187], v[192:195], v[50:65]
	ds_read_b128 v[158:161], v207 offset:8192
	v_mfma_f32_32x32x16_bf16 v[34:49], v[184:187], v[200:203], v[34:49]
	ds_read_b128 v[162:165], v207 offset:12288
	s_waitcnt lgkmcnt(6)
	v_mfma_f32_32x32x16_bf16 v[18:33], v[188:191], v[192:195], v[18:33]
	v_mfma_f32_32x32x16_bf16 v[2:17], v[188:191], v[200:203], v[2:17]
	s_waitcnt lgkmcnt(4)
	v_mfma_f32_32x32x16_bf16 v[114:129], v[150:153], v[166:169], v[114:129]
	ds_read_b128 v[174:177], v208 offset:0
	ds_read_b128 v[192:195], v212 offset:0
	s_waitcnt lgkmcnt(5)
	v_mfma_f32_32x32x16_bf16 v[98:113], v[150:153], v[170:173], v[98:113]
	ds_read_b128 v[200:203], v212 offset:4096
	ds_read_b128 v[180:183], v208 offset:4096
	s_waitcnt lgkmcnt(6)
	v_mfma_f32_32x32x16_bf16 v[82:97], v[154:157], v[166:169], v[82:97]
	ds_read_b128 v[184:187], v208 offset:8192
	ds_read_b128 v[188:191], v208 offset:12288
	v_mfma_f32_32x32x16_bf16 v[66:81], v[154:157], v[170:173], v[66:81]
	s_waitcnt lgkmcnt(7)
	v_mfma_f32_32x32x16_bf16 v[50:65], v[158:161], v[166:169], v[50:65]
	v_mfma_f32_32x32x16_bf16 v[34:49], v[158:161], v[170:173], v[34:49]
	s_waitcnt lgkmcnt(6)
	v_mfma_f32_32x32x16_bf16 v[18:33], v[162:165], v[166:169], v[18:33]
	v_mfma_f32_32x32x16_bf16 v[2:17], v[162:165], v[170:173], v[2:17]
	s_waitcnt vmcnt(0) lgkmcnt(0)
	s_barrier
	v_mfma_f32_32x32x16_bf16 v[114:129], v[174:177], v[192:195], v[114:129]
	ds_read_b128 v[150:153], v205 offset:32768
	v_mfma_f32_32x32x16_bf16 v[98:113], v[174:177], v[200:203], v[98:113]
	ds_read_b128 v[166:169], v209 offset:32768
	s_add_u32 m0, s14, 0x20
	s_add_u32 s12, s1, s4
	s_addc_u32 s13, s3, s5
	global_load_lds_dwordx4 v149, s[12:13]
	v_mfma_f32_32x32x16_bf16 v[82:97], v[180:183], v[192:195], v[82:97]
	ds_read_b128 v[170:173], v209 offset:36864
	v_mfma_f32_32x32x16_bf16 v[66:81], v[180:183], v[200:203], v[66:81]
	ds_read_b128 v[154:157], v205 offset:36864
	s_add_u32 m0, s14, 0x2020
	s_add_u32 s12, s12, 0x20000
	s_addc_u32 s13, s13, 0
	global_load_lds_dwordx4 v149, s[12:13]
	v_mfma_f32_32x32x16_bf16 v[50:65], v[184:187], v[192:195], v[50:65]
	ds_read_b128 v[158:161], v205 offset:40960
	v_mfma_f32_32x32x16_bf16 v[34:49], v[184:187], v[200:203], v[34:49]
	ds_read_b128 v[162:165], v205 offset:45056
	s_add_u32 m0, s14, 0x4020
	s_add_u32 s12, s12, 0x20000
	s_addc_u32 s13, s13, 0
	global_load_lds_dwordx4 v149, s[12:13]
	v_mfma_f32_32x32x16_bf16 v[18:33], v[188:191], v[192:195], v[18:33]
	v_mfma_f32_32x32x16_bf16 v[2:17], v[188:191], v[200:203], v[2:17]
	s_add_u32 m0, s14, 0x6020
	s_add_u32 s12, s12, 0x20000
	s_addc_u32 s13, s13, 0
	global_load_lds_dwordx4 v149, s[12:13]
	s_waitcnt lgkmcnt(4)
	v_mfma_f32_32x32x16_bf16 v[114:129], v[150:153], v[166:169], v[114:129]
	ds_read_b128 v[174:177], v206 offset:32768
	s_waitcnt lgkmcnt(4)
	v_mfma_f32_32x32x16_bf16 v[98:113], v[150:153], v[170:173], v[98:113]
	ds_read_b128 v[192:195], v210 offset:32768
	s_add_u32 m0, s14, 0x10020
	s_add_u32 s12, s10, s4
	s_addc_u32 s13, s11, s5
	global_load_lds_dwordx4 v149, s[12:13]
	s_waitcnt lgkmcnt(4)
	v_mfma_f32_32x32x16_bf16 v[82:97], v[154:157], v[166:169], v[82:97]
	ds_read_b128 v[200:203], v210 offset:36864
	v_mfma_f32_32x32x16_bf16 v[66:81], v[154:157], v[170:173], v[66:81]
	ds_read_b128 v[180:183], v206 offset:36864
	s_add_u32 m0, s14, 0x12020
	s_add_u32 s12, s12, 0x20000
	s_addc_u32 s13, s13, 0
	global_load_lds_dwordx4 v149, s[12:13]
	s_waitcnt lgkmcnt(5)
	v_mfma_f32_32x32x16_bf16 v[50:65], v[158:161], v[166:169], v[50:65]
	ds_read_b128 v[184:187], v206 offset:40960
	v_mfma_f32_32x32x16_bf16 v[34:49], v[158:161], v[170:173], v[34:49]
	ds_read_b128 v[188:191], v206 offset:45056
	s_add_u32 m0, s14, 0x14020
	s_add_u32 s12, s12, 0x20000
	s_addc_u32 s13, s13, 0
	global_load_lds_dwordx4 v149, s[12:13]
	s_waitcnt lgkmcnt(6)
	v_mfma_f32_32x32x16_bf16 v[18:33], v[162:165], v[166:169], v[18:33]
	v_mfma_f32_32x32x16_bf16 v[2:17], v[162:165], v[170:173], v[2:17]
	s_add_u32 m0, s14, 0x16020
	s_add_u32 s12, s12, 0x20000
	s_addc_u32 s13, s13, 0
	global_load_lds_dwordx4 v149, s[12:13]
	s_add_u32 s4, s4, 0x80
	s_addc_u32 s5, s5, 0
	s_waitcnt lgkmcnt(4)
	v_mfma_f32_32x32x16_bf16 v[114:129], v[174:177], v[192:195], v[114:129]
	ds_read_b128 v[150:153], v207 offset:32768
	s_waitcnt lgkmcnt(4)
	v_mfma_f32_32x32x16_bf16 v[98:113], v[174:177], v[200:203], v[98:113]
	ds_read_b128 v[166:169], v211 offset:32768
	s_waitcnt lgkmcnt(4)
	v_mfma_f32_32x32x16_bf16 v[82:97], v[180:183], v[192:195], v[82:97]
	ds_read_b128 v[170:173], v211 offset:36864
	v_mfma_f32_32x32x16_bf16 v[66:81], v[180:183], v[200:203], v[66:81]
	ds_read_b128 v[154:157], v207 offset:36864
	s_waitcnt lgkmcnt(5)
	v_mfma_f32_32x32x16_bf16 v[50:65], v[184:187], v[192:195], v[50:65]
	ds_read_b128 v[158:161], v207 offset:40960
	v_mfma_f32_32x32x16_bf16 v[34:49], v[184:187], v[200:203], v[34:49]
	ds_read_b128 v[162:165], v207 offset:45056
	s_waitcnt lgkmcnt(6)
	v_mfma_f32_32x32x16_bf16 v[18:33], v[188:191], v[192:195], v[18:33]
	v_mfma_f32_32x32x16_bf16 v[2:17], v[188:191], v[200:203], v[2:17]
	s_waitcnt lgkmcnt(4)
	v_mfma_f32_32x32x16_bf16 v[114:129], v[150:153], v[166:169], v[114:129]
	ds_read_b128 v[174:177], v208 offset:32768
	ds_read_b128 v[192:195], v212 offset:32768
	s_waitcnt lgkmcnt(5)
	v_mfma_f32_32x32x16_bf16 v[98:113], v[150:153], v[170:173], v[98:113]
	ds_read_b128 v[200:203], v212 offset:36864
	ds_read_b128 v[180:183], v208 offset:36864
	s_waitcnt lgkmcnt(6)
	v_mfma_f32_32x32x16_bf16 v[82:97], v[154:157], v[166:169], v[82:97]
	ds_read_b128 v[184:187], v208 offset:40960
	ds_read_b128 v[188:191], v208 offset:45056
	v_mfma_f32_32x32x16_bf16 v[66:81], v[154:157], v[170:173], v[66:81]
	s_waitcnt lgkmcnt(7)
	v_mfma_f32_32x32x16_bf16 v[50:65], v[158:161], v[166:169], v[50:65]
	v_mfma_f32_32x32x16_bf16 v[34:49], v[158:161], v[170:173], v[34:49]
	s_waitcnt lgkmcnt(6)
	v_mfma_f32_32x32x16_bf16 v[18:33], v[162:165], v[166:169], v[18:33]
	v_mfma_f32_32x32x16_bf16 v[2:17], v[162:165], v[170:173], v[2:17]
	s_waitcnt vmcnt(0) lgkmcnt(0)
	s_barrier
	v_mfma_f32_32x32x16_bf16 v[114:129], v[174:177], v[192:195], v[114:129]
	ds_read_b128 v[150:153], v205 offset:0
	v_mfma_f32_32x32x16_bf16 v[98:113], v[174:177], v[200:203], v[98:113]
	ds_read_b128 v[166:169], v209 offset:0
	s_add_u32 m0, s14, 0x8020
	s_add_u32 s12, s1, s4
	s_addc_u32 s13, s3, s5
	global_load_lds_dwordx4 v149, s[12:13]
	v_mfma_f32_32x32x16_bf16 v[82:97], v[180:183], v[192:195], v[82:97]
	ds_read_b128 v[170:173], v209 offset:4096
	v_mfma_f32_32x32x16_bf16 v[66:81], v[180:183], v[200:203], v[66:81]
	ds_read_b128 v[154:157], v205 offset:4096
	s_add_u32 m0, s14, 0xa020
	s_add_u32 s12, s12, 0x20000
	s_addc_u32 s13, s13, 0
	global_load_lds_dwordx4 v149, s[12:13]
	v_mfma_f32_32x32x16_bf16 v[50:65], v[184:187], v[192:195], v[50:65]
	ds_read_b128 v[158:161], v205 offset:8192
	v_mfma_f32_32x32x16_bf16 v[34:49], v[184:187], v[200:203], v[34:49]
	ds_read_b128 v[162:165], v205 offset:12288
	s_add_u32 m0, s14, 0xc020
	s_add_u32 s12, s12, 0x20000
	s_addc_u32 s13, s13, 0
	global_load_lds_dwordx4 v149, s[12:13]
	v_mfma_f32_32x32x16_bf16 v[18:33], v[188:191], v[192:195], v[18:33]
	v_mfma_f32_32x32x16_bf16 v[2:17], v[188:191], v[200:203], v[2:17]
	s_add_u32 m0, s14, 0xe020
	s_add_u32 s12, s12, 0x20000
	s_addc_u32 s13, s13, 0
	global_load_lds_dwordx4 v149, s[12:13]
	s_sub_u32 s9, s9, 1
	s_cmp_lg_u32 s9, 0
	s_cbranch_scc1 .Lg910_loop
	s_waitcnt lgkmcnt(4)
	v_mfma_f32_32x32x16_bf16 v[114:129], v[150:153], v[166:169], v[114:129]
	ds_read_b128 v[174:177], v206 offset:0
	s_waitcnt lgkmcnt(4)
	v_mfma_f32_32x32x16_bf16 v[98:113], v[150:153], v[170:173], v[98:113]
	ds_read_b128 v[192:195], v210 offset:0
	s_add_u32 m0, s14, 0x18020
	s_add_u32 s12, s10, s4
	s_addc_u32 s13, s11, s5
	global_load_lds_dwordx4 v149, s[12:13]
	s_waitcnt lgkmcnt(4)
	v_mfma_f32_32x32x16_bf16 v[82:97], v[154:157], v[166:169], v[82:97]
	ds_read_b128 v[200:203], v210 offset:4096
	v_mfma_f32_32x32x16_bf16 v[66:81], v[154:157], v[170:173], v[66:81]
	ds_read_b128 v[180:183], v206 offset:4096
	s_add_u32 m0, s14, 0x1a020
	s_add_u32 s12, s12, 0x20000
	s_addc_u32 s13, s13, 0
	global_load_lds_dwordx4 v149, s[12:13]
	s_waitcnt lgkmcnt(5)
	v_mfma_f32_32x32x16_bf16 v[50:65], v[158:161], v[166:169], v[50:65]
	ds_read_b128 v[184:187], v206 offset:8192
	v_mfma_f32_32x32x16_bf16 v[34:49], v[158:161], v[170:173], v[34:49]
	ds_read_b128 v[188:191], v206 offset:12288
	s_add_u32 m0, s14, 0x1c020
	s_add_u32 s12, s12, 0x20000
	s_addc_u32 s13, s13, 0
	global_load_lds_dwordx4 v149, s[12:13]
	s_waitcnt lgkmcnt(6)
	v_mfma_f32_32x32x16_bf16 v[18:33], v[162:165], v[166:169], v[18:33]
	v_mfma_f32_32x32x16_bf16 v[2:17], v[162:165], v[170:173], v[2:17]
	s_add_u32 m0, s14, 0x1e020
	s_add_u32 s12, s12, 0x20000
	s_addc_u32 s13, s13, 0
	global_load_lds_dwordx4 v149, s[12:13]
	s_add_u32 s4, s4, 0x80
	s_addc_u32 s5, s5, 0
	s_waitcnt lgkmcnt(4)
	v_mfma_f32_32x32x16_bf16 v[114:129], v[174:177], v[192:195], v[114:129]
	ds_read_b128 v[150:153], v207 offset:0
	s_waitcnt lgkmcnt(4)
	v_mfma_f32_32x32x16_bf16 v[98:113], v[174:177], v[200:203], v[98:113]
	ds_read_b128 v[166:169], v211 offset:0
	s_waitcnt lgkmcnt(4)
	v_mfma_f32_32x32x16_bf16 v[82:97], v[180:183], v[192:195], v[82:97]
	ds_read_b128 v[170:173], v211 offset:4096
	v_mfma_f32_32x32x16_bf16 v[66:81], v[180:183], v[200:203], v[66:81]
	ds_read_b128 v[154:157], v207 offset:4096
	s_waitcnt lgkmcnt(5)
	v_mfma_f32_32x32x16_bf16 v[50:65], v[184:187], v[192:195], v[50:65]
	ds_read_b128 v[158:161], v207 offset:8192
	v_mfma_f32_32x32x16_bf16 v[34:49], v[184:187], v[200:203], v[34:49]
	ds_read_b128 v[162:165], v207 offset:12288
	s_waitcnt lgkmcnt(6)
	v_mfma_f32_32x32x16_bf16 v[18:33], v[188:191], v[192:195], v[18:33]
	v_mfma_f32_32x32x16_bf16 v[2:17], v[188:191], v[200:203], v[2:17]
	s_waitcnt lgkmcnt(4)
	v_mfma_f32_32x32x16_bf16 v[114:129], v[150:153], v[166:169], v[114:129]
	ds_read_b128 v[174:177], v208 offset:0
	ds_read_b128 v[192:195], v212 offset:0
	s_waitcnt lgkmcnt(5)
	v_mfma_f32_32x32x16_bf16 v[98:113], v[150:153], v[170:173], v[98:113]
	ds_read_b128 v[200:203], v212 offset:4096
	ds_read_b128 v[180:183], v208 offset:4096
	s_waitcnt lgkmcnt(6)
	v_mfma_f32_32x32x16_bf16 v[82:97], v[154:157], v[166:169], v[82:97]
	ds_read_b128 v[184:187], v208 offset:8192
	ds_read_b128 v[188:191], v208 offset:12288
	v_mfma_f32_32x32x16_bf16 v[66:81], v[154:157], v[170:173], v[66:81]
	s_waitcnt lgkmcnt(7)
	v_mfma_f32_32x32x16_bf16 v[50:65], v[158:161], v[166:169], v[50:65]
	v_mfma_f32_32x32x16_bf16 v[34:49], v[158:161], v[170:173], v[34:49]
	s_waitcnt lgkmcnt(6)
	v_mfma_f32_32x32x16_bf16 v[18:33], v[162:165], v[166:169], v[18:33]
	v_mfma_f32_32x32x16_bf16 v[2:17], v[162:165], v[170:173], v[2:17]
	s_waitcnt vmcnt(0) lgkmcnt(0)
	s_barrier
	v_mfma_f32_32x32x16_bf16 v[114:129], v[174:177], v[192:195], v[114:129]
	ds_read_b128 v[150:153], v205 offset:32768
	v_mfma_f32_32x32x16_bf16 v[98:113], v[174:177], v[200:203], v[98:113]
	ds_read_b128 v[166:169], v209 offset:32768
	v_mfma_f32_32x32x16_bf16 v[82:97], v[180:183], v[192:195], v[82:97]
	ds_read_b128 v[170:173], v209 offset:36864
	v_mfma_f32_32x32x16_bf16 v[66:81], v[180:183], v[200:203], v[66:81]
	ds_read_b128 v[154:157], v205 offset:36864
	v_mfma_f32_32x32x16_bf16 v[50:65], v[184:187], v[192:195], v[50:65]
	ds_read_b128 v[158:161], v205 offset:40960
	v_mfma_f32_32x32x16_bf16 v[34:49], v[184:187], v[200:203], v[34:49]
	ds_read_b128 v[162:165], v205 offset:45056
	v_mfma_f32_32x32x16_bf16 v[18:33], v[188:191], v[192:195], v[18:33]
	v_mfma_f32_32x32x16_bf16 v[2:17], v[188:191], v[200:203], v[2:17]
	s_waitcnt lgkmcnt(4)
	v_mfma_f32_32x32x16_bf16 v[114:129], v[150:153], v[166:169], v[114:129]
	ds_read_b128 v[174:177], v206 offset:32768
	s_waitcnt lgkmcnt(4)
	v_mfma_f32_32x32x16_bf16 v[98:113], v[150:153], v[170:173], v[98:113]
	ds_read_b128 v[192:195], v210 offset:32768
	s_waitcnt lgkmcnt(4)
	v_mfma_f32_32x32x16_bf16 v[82:97], v[154:157], v[166:169], v[82:97]
	ds_read_b128 v[200:203], v210 offset:36864
	v_mfma_f32_32x32x16_bf16 v[66:81], v[154:157], v[170:173], v[66:81]
	ds_read_b128 v[180:183], v206 offset:36864
	s_waitcnt lgkmcnt(5)
	v_mfma_f32_32x32x16_bf16 v[50:65], v[158:161], v[166:169], v[50:65]
	ds_read_b128 v[184:187], v206 offset:40960
	v_mfma_f32_32x32x16_bf16 v[34:49], v[158:161], v[170:173], v[34:49]
	ds_read_b128 v[188:191], v206 offset:45056
	s_waitcnt lgkmcnt(6)
	v_mfma_f32_32x32x16_bf16 v[18:33], v[162:165], v[166:169], v[18:33]
	v_mfma_f32_32x32x16_bf16 v[2:17], v[162:165], v[170:173], v[2:17]
	s_waitcnt lgkmcnt(4)
	v_mfma_f32_32x32x16_bf16 v[114:129], v[174:177], v[192:195], v[114:129]
	ds_read_b128 v[150:153], v207 offset:32768
	s_waitcnt lgkmcnt(4)
	v_mfma_f32_32x32x16_bf16 v[98:113], v[174:177], v[200:203], v[98:113]
	ds_read_b128 v[166:169], v211 offset:32768
	s_waitcnt lgkmcnt(4)
	v_mfma_f32_32x32x16_bf16 v[82:97], v[180:183], v[192:195], v[82:97]
	ds_read_b128 v[170:173], v211 offset:36864
	v_mfma_f32_32x32x16_bf16 v[66:81], v[180:183], v[200:203], v[66:81]
	ds_read_b128 v[154:157], v207 offset:36864
	s_waitcnt lgkmcnt(5)
	v_mfma_f32_32x32x16_bf16 v[50:65], v[184:187], v[192:195], v[50:65]
	ds_read_b128 v[158:161], v207 offset:40960
	v_mfma_f32_32x32x16_bf16 v[34:49], v[184:187], v[200:203], v[34:49]
	ds_read_b128 v[162:165], v207 offset:45056
	s_waitcnt lgkmcnt(6)
	v_mfma_f32_32x32x16_bf16 v[18:33], v[188:191], v[192:195], v[18:33]
	v_mfma_f32_32x32x16_bf16 v[2:17], v[188:191], v[200:203], v[2:17]
	s_waitcnt lgkmcnt(4)
	v_mfma_f32_32x32x16_bf16 v[114:129], v[150:153], v[166:169], v[114:129]
	ds_read_b128 v[174:177], v208 offset:32768
	ds_read_b128 v[192:195], v212 offset:32768
	s_waitcnt lgkmcnt(5)
	v_mfma_f32_32x32x16_bf16 v[98:113], v[150:153], v[170:173], v[98:113]
	ds_read_b128 v[200:203], v212 offset:36864
	ds_read_b128 v[180:183], v208 offset:36864
	s_waitcnt lgkmcnt(6)
	v_mfma_f32_32x32x16_bf16 v[82:97], v[154:157], v[166:169], v[82:97]
	ds_read_b128 v[184:187], v208 offset:40960
	ds_read_b128 v[188:191], v208 offset:45056
	v_mfma_f32_32x32x16_bf16 v[66:81], v[154:157], v[170:173], v[66:81]
	s_waitcnt lgkmcnt(7)
	v_mfma_f32_32x32x16_bf16 v[50:65], v[158:161], v[166:169], v[50:65]
	v_mfma_f32_32x32x16_bf16 v[34:49], v[158:161], v[170:173], v[34:49]
	s_waitcnt lgkmcnt(6)
	v_mfma_f32_32x32x16_bf16 v[18:33], v[162:165], v[166:169], v[18:33]
	v_mfma_f32_32x32x16_bf16 v[2:17], v[162:165], v[170:173], v[2:17]
	s_waitcnt vmcnt(0) lgkmcnt(0)
	s_barrier
	v_mfma_f32_32x32x16_bf16 v[114:129], v[174:177], v[192:195], v[114:129]
	v_mfma_f32_32x32x16_bf16 v[98:113], v[174:177], v[200:203], v[98:113]
	v_mfma_f32_32x32x16_bf16 v[82:97], v[180:183], v[192:195], v[82:97]
	v_mfma_f32_32x32x16_bf16 v[66:81], v[180:183], v[200:203], v[66:81]
	v_mfma_f32_32x32x16_bf16 v[50:65], v[184:187], v[192:195], v[50:65]
	v_mfma_f32_32x32x16_bf16 v[34:49], v[184:187], v[200:203], v[34:49]
	v_mfma_f32_32x32x16_bf16 v[18:33], v[188:191], v[192:195], v[18:33]
	v_mfma_f32_32x32x16_bf16 v[2:17], v[188:191], v[200:203], v[2:17]
	s_setprio 0
	v_add_u32_e32 v149, s0, v143
	v_or_b32_e32 v130, s2, v144
	s_mov_b32 s2, 0x7e07e07f
	v_mul_hi_i32 v0, v149, s2
	v_lshrrev_b32_e32 v131, 31, v0
	v_ashrrev_i32_e32 v0, 13, v0
	v_add_u32_e32 v0, v0, v131
	v_mul_i32_i24_e32 v131, 0x4100, v0
	v_sub_u32_e32 v131, v149, v131
	s_movk_i32 s3, 0xff
	v_mul_i32_i24_e32 v0, 0xc00, v0
	v_cmp_lt_i32_e32 vcc, s3, v131
	v_mov_b32_e32 v162, 0x1800
	v_mov_b32_e32 v152, v179
	s_waitcnt vmcnt(0)
	s_barrier
	v_cndmask_b32_e32 v150, v162, v0, vcc
	v_readlane_b32 s12, v251, 2
	v_and_b32_e32 v0, 31, v152
	v_bfe_u32 v131, v152, 5, 1
	v_mul_u32_u24_e32 v131, 0x240, v131
	v_lshlrev_b32_e32 v0, 2, v0
	v_add3_u32 v0, v145, v131, v0
	ds_write2_b32 v0, v114, v115 offset1:36
	ds_write2_b32 v0, v116, v117 offset0:72 offset1:108
	v_add_u32_e32 v114, 0x400, v0
	v_ashrrev_i32_e32 v151, 31, v150
	ds_write2_b32 v114, v118, v119 offset0:32 offset1:68
	ds_write2_b32 v114, v120, v121 offset0:104 offset1:140
	v_add_u32_e32 v114, 0x800, v0
	v_add_u32_e32 v0, 0xc00, v0
	v_readlane_b32 s26, v251, 16
	v_readlane_b32 s27, v251, 17
	ds_write2_b32 v114, v122, v123 offset0:64 offset1:100
	ds_write2_b32 v114, v124, v125 offset0:136 offset1:172
	ds_write2_b32 v0, v126, v127 offset0:96 offset1:132
	ds_write2_b32 v0, v128, v129 offset0:168 offset1:204
	v_lshl_add_u64 v[114:115], v[150:151], 2, s[26:27]
	s_mov_b64 s[4:5], 0x1b02000
	v_ashrrev_i32_e32 v131, 31, v130
	v_readlane_b32 s0, v251, 26
	v_lshlrev_b32_e32 v0, 3, v152
	v_lshl_add_u64 v[118:119], v[114:115], 0, s[4:5]
	v_lshlrev_b64 v[116:117], 2, v[130:131]
	v_readlane_b32 s1, v251, 27
	v_and_b32_e32 v122, 24, v0
	v_lshl_add_u64 v[120:121], v[118:119], 0, v[116:117]
	v_lshl_add_u64 v[114:115], v[130:131], 1, s[0:1]
	v_lshlrev_b32_e32 v0, 2, v122
	v_bfe_u32 v131, v152, 2, 4
	v_lshl_add_u64 v[158:159], v[120:121], 0, v[0:1]
	v_lshlrev_b32_e32 v120, 1, v122
	v_mul_u32_u24_e32 v122, 0x90, v131
	s_waitcnt lgkmcnt(0)
	v_add3_u32 v0, v145, v0, v122
	ds_read_b128 v[122:125], v0
	ds_read_b128 v[126:129], v0 offset:16
	global_load_dwordx4 v[150:153], v[158:159], off offset:16
	global_load_dwordx4 v[154:157], v[158:159], off
	v_or_b32_e32 v160, v131, v149
	v_mov_b32_e32 v121, v1
	v_ashrrev_i32_e32 v161, 31, v160
	v_lshl_add_u64 v[120:121], v[114:115], 0, v[120:121]
	v_readlane_b32 s13, v251, 3
	v_readlane_b32 s14, v251, 4
	v_readlane_b32 s15, v251, 5
	v_readlane_b32 s16, v251, 6
	v_readlane_b32 s17, v251, 7
	v_readlane_b32 s18, v251, 8
	v_readlane_b32 s19, v251, 9
	v_readlane_b32 s20, v251, 10
	v_readlane_b32 s21, v251, 11
	v_readlane_b32 s22, v251, 12
	v_readlane_b32 s23, v251, 13
	v_readlane_b32 s24, v251, 14
	v_readlane_b32 s25, v251, 15
	s_waitcnt vmcnt(1) lgkmcnt(0)
	v_pk_mul_f32 v[126:127], v[126:127], v[150:151]
	s_waitcnt vmcnt(0)
	v_pk_mul_f32 v[122:123], v[122:123], v[154:155]
	v_pk_mul_f32 v[124:125], v[124:125], v[156:157]
	v_pk_mul_f32 v[128:129], v[128:129], v[152:153]
	v_cvt_pk_bf16_f32 v122, v122, v123
	v_cvt_pk_bf16_f32 v123, v124, v125
	v_cvt_pk_bf16_f32 v124, v126, v127
	v_lshlrev_b64 v[126:127], 11, v[160:161]
	v_cvt_pk_bf16_f32 v125, v128, v129
	v_lshl_add_u64 v[126:127], v[120:121], 0, v[126:127]
	global_store_dwordx4 v[126:127], v[122:125], off
	ds_read_b128 v[122:125], v0 offset:2304
	ds_read_b128 v[126:129], v0 offset:2320
	global_load_dwordx4 v[150:153], v[158:159], off offset:16
	global_load_dwordx4 v[154:157], v[158:159], off
	s_waitcnt vmcnt(1) lgkmcnt(0)
	v_pk_mul_f32 v[126:127], v[126:127], v[150:151]
	s_waitcnt vmcnt(0)
	v_pk_mul_f32 v[122:123], v[122:123], v[154:155]
	v_pk_mul_f32 v[124:125], v[124:125], v[156:157]
	v_cvt_pk_bf16_f32 v122, v122, v123
	v_cvt_pk_bf16_f32 v123, v124, v125
	v_cvt_pk_bf16_f32 v124, v126, v127
	v_or_b32_e32 v126, 16, v160
	v_ashrrev_i32_e32 v127, 31, v126
	v_pk_mul_f32 v[128:129], v[128:129], v[152:153]
	v_lshlrev_b64 v[126:127], 11, v[126:127]
	v_cvt_pk_bf16_f32 v125, v128, v129
	v_lshl_add_u64 v[120:121], v[120:121], 0, v[126:127]
	global_store_dwordx4 v[120:121], v[122:125], off
	v_mov_b32_e32 v120, v179
	v_or_b32_e32 v126, 32, v130
	v_and_b32_e32 v0, 31, v120
	v_bfe_u32 v121, v120, 5, 1
	v_mul_u32_u24_e32 v121, 0x240, v121
	v_lshlrev_b32_e32 v0, 2, v0
	v_add3_u32 v0, v145, v121, v0
	ds_write2_b32 v0, v98, v99 offset1:36
	ds_write2_b32 v0, v100, v101 offset0:72 offset1:108
	v_add_u32_e32 v98, 0x400, v0
	ds_write2_b32 v98, v102, v103 offset0:32 offset1:68
	ds_write2_b32 v98, v104, v105 offset0:104 offset1:140
	v_add_u32_e32 v98, 0x800, v0
	v_add_u32_e32 v0, 0xc00, v0
	ds_write2_b32 v98, v106, v107 offset0:64 offset1:100
	ds_write2_b32 v98, v108, v109 offset0:136 offset1:172
	ds_write2_b32 v0, v110, v111 offset0:96 offset1:132
	ds_write2_b32 v0, v112, v113 offset0:168 offset1:204
	v_lshlrev_b32_e32 v0, 3, v120
	v_and_b32_e32 v102, 24, v0
	v_ashrrev_i32_e32 v127, 31, v126
	v_lshlrev_b32_e32 v0, 2, v102
	v_lshl_add_u64 v[98:99], v[118:119], 0, v[0:1]
	v_lshlrev_b64 v[100:101], 2, v[126:127]
	v_lshl_add_u64 v[112:113], v[98:99], 0, v[100:101]
	v_lshlrev_b32_e32 v98, 1, v102
	v_mov_b32_e32 v99, v1
	v_bfe_u32 v128, v120, 2, 4
	v_lshl_add_u64 v[102:103], s[0:1], 0, v[98:99]
	v_mul_u32_u24_e32 v98, 0x90, v128
	s_waitcnt lgkmcnt(0)
	v_add3_u32 v0, v145, v0, v98
	ds_read_b128 v[104:107], v0
	ds_read_b128 v[108:111], v0 offset:16
	global_load_dwordx4 v[118:121], v[112:113], off offset:16
	global_load_dwordx4 v[122:125], v[112:113], off
	v_or_b32_e32 v128, v128, v149
	v_ashrrev_i32_e32 v129, 31, v128
	s_waitcnt vmcnt(1) lgkmcnt(0)
	v_pk_mul_f32 v[108:109], v[108:109], v[118:119]
	s_waitcnt vmcnt(0)
	v_pk_mul_f32 v[98:99], v[104:105], v[122:123]
	v_pk_mul_f32 v[106:107], v[106:107], v[124:125]
	v_cvt_pk_bf16_f32 v104, v98, v99
	v_lshlrev_b64 v[98:99], 11, v[128:129]
	v_pk_mul_f32 v[110:111], v[110:111], v[120:121]
	v_cvt_pk_bf16_f32 v105, v106, v107
	v_cvt_pk_bf16_f32 v106, v108, v109
	v_lshl_add_u64 v[108:109], v[102:103], 0, v[98:99]
	v_lshlrev_b64 v[98:99], 1, v[126:127]
	v_cvt_pk_bf16_f32 v107, v110, v111
	v_lshl_add_u64 v[108:109], v[108:109], 0, v[98:99]
	global_store_dwordx4 v[108:109], v[104:107], off
	ds_read_b128 v[104:107], v0 offset:2304
	ds_read_b128 v[108:111], v0 offset:2320
	global_load_dwordx4 v[118:121], v[112:113], off offset:16
	global_load_dwordx4 v[122:125], v[112:113], off
	s_waitcnt vmcnt(1) lgkmcnt(0)
	v_pk_mul_f32 v[108:109], v[108:109], v[118:119]
	s_waitcnt vmcnt(0)
	v_pk_mul_f32 v[104:105], v[104:105], v[122:123]
	v_pk_mul_f32 v[106:107], v[106:107], v[124:125]
	v_cvt_pk_bf16_f32 v104, v104, v105
	v_cvt_pk_bf16_f32 v105, v106, v107
	v_cvt_pk_bf16_f32 v106, v108, v109
	v_or_b32_e32 v108, 16, v128
	v_ashrrev_i32_e32 v109, 31, v108
	v_lshlrev_b64 v[108:109], 11, v[108:109]
	v_pk_mul_f32 v[110:111], v[110:111], v[120:121]
	v_lshl_add_u64 v[102:103], v[102:103], 0, v[108:109]
	v_cvt_pk_bf16_f32 v107, v110, v111
	v_lshl_add_u64 v[102:103], v[102:103], 0, v[98:99]
	global_store_dwordx4 v[102:103], v[104:107], off
	v_or_b32_e32 v110, 32, v149
	v_mul_hi_i32 v0, v110, s2
	v_lshrrev_b32_e32 v102, 31, v0
	v_ashrrev_i32_e32 v0, 13, v0
	v_add_u32_e32 v0, v0, v102
	v_mul_i32_i24_e32 v102, 0x4100, v0
	v_sub_u32_e32 v102, v110, v102
	v_mul_i32_i24_e32 v0, 0xc00, v0
	v_cmp_lt_i32_e32 vcc, s3, v102
	v_mov_b32_e32 v104, v179
	s_nop 0
	v_cndmask_b32_e32 v102, v162, v0, vcc
	v_and_b32_e32 v0, 31, v104
	v_bfe_u32 v105, v104, 5, 1
	v_mul_u32_u24_e32 v105, 0x240, v105
	v_lshlrev_b32_e32 v0, 2, v0
	v_add3_u32 v0, v145, v105, v0
	ds_write2_b32 v0, v82, v83 offset1:36
	ds_write2_b32 v0, v84, v85 offset0:72 offset1:108
	v_add_u32_e32 v82, 0x400, v0
	v_ashrrev_i32_e32 v103, 31, v102
	ds_write2_b32 v82, v86, v87 offset0:32 offset1:68
	ds_write2_b32 v82, v88, v89 offset0:104 offset1:140
	v_add_u32_e32 v82, 0x800, v0
	v_add_u32_e32 v0, 0xc00, v0
	ds_write2_b32 v82, v90, v91 offset0:64 offset1:100
	ds_write2_b32 v82, v92, v93 offset0:136 offset1:172
	ds_write2_b32 v0, v94, v95 offset0:96 offset1:132
	ds_write2_b32 v0, v96, v97 offset0:168 offset1:204
	v_lshl_add_u64 v[82:83], v[102:103], 2, s[26:27]
	v_lshlrev_b32_e32 v0, 3, v104
	v_lshl_add_u64 v[82:83], v[82:83], 0, s[4:5]
	v_and_b32_e32 v86, 24, v0
	v_lshl_add_u64 v[84:85], v[82:83], 0, v[116:117]
	v_lshlrev_b32_e32 v0, 2, v86
	v_bfe_u32 v108, v104, 2, 4
	v_lshl_add_u64 v[106:107], v[84:85], 0, v[0:1]
	v_lshlrev_b32_e32 v84, 1, v86
	v_mul_u32_u24_e32 v86, 0x90, v108
	s_waitcnt lgkmcnt(0)
	v_add3_u32 v0, v145, v0, v86
	ds_read_b128 v[86:89], v0
	ds_read_b128 v[90:93], v0 offset:16
	global_load_dwordx4 v[94:97], v[106:107], off offset:16
	global_load_dwordx4 v[102:105], v[106:107], off
	v_or_b32_e32 v108, v108, v110
	v_mov_b32_e32 v85, v1
	v_ashrrev_i32_e32 v109, 31, v108
	v_lshl_add_u64 v[84:85], v[114:115], 0, v[84:85]
	s_waitcnt vmcnt(1) lgkmcnt(0)
	v_pk_mul_f32 v[90:91], v[90:91], v[94:95]
	s_waitcnt vmcnt(0)
	v_pk_mul_f32 v[86:87], v[86:87], v[102:103]
	v_pk_mul_f32 v[88:89], v[88:89], v[104:105]
	v_pk_mul_f32 v[92:93], v[92:93], v[96:97]
	v_cvt_pk_bf16_f32 v86, v86, v87
	v_cvt_pk_bf16_f32 v87, v88, v89
	v_cvt_pk_bf16_f32 v88, v90, v91
	v_lshlrev_b64 v[90:91], 11, v[108:109]
	v_cvt_pk_bf16_f32 v89, v92, v93
	v_lshl_add_u64 v[90:91], v[84:85], 0, v[90:91]
	global_store_dwordx4 v[90:91], v[86:89], off
	ds_read_b128 v[86:89], v0 offset:2304
	ds_read_b128 v[90:93], v0 offset:2320
	global_load_dwordx4 v[94:97], v[106:107], off offset:16
	global_load_dwordx4 v[102:105], v[106:107], off
	s_waitcnt vmcnt(1) lgkmcnt(0)
	v_pk_mul_f32 v[90:91], v[90:91], v[94:95]
	s_waitcnt vmcnt(0)
	v_pk_mul_f32 v[86:87], v[86:87], v[102:103]
	v_pk_mul_f32 v[88:89], v[88:89], v[104:105]
	v_cvt_pk_bf16_f32 v86, v86, v87
	v_cvt_pk_bf16_f32 v87, v88, v89
	v_cvt_pk_bf16_f32 v88, v90, v91
	v_or_b32_e32 v90, 16, v108
	v_ashrrev_i32_e32 v91, 31, v90
	v_pk_mul_f32 v[92:93], v[92:93], v[96:97]
	v_lshlrev_b64 v[90:91], 11, v[90:91]
	v_cvt_pk_bf16_f32 v89, v92, v93
	v_lshl_add_u64 v[84:85], v[84:85], 0, v[90:91]
	global_store_dwordx4 v[84:85], v[86:89], off
	s_nop 1
	v_mov_b32_e32 v86, v179
	s_nop 0
	v_and_b32_e32 v0, 31, v86
	v_bfe_u32 v84, v86, 5, 1
	v_mul_u32_u24_e32 v84, 0x240, v84
	v_lshlrev_b32_e32 v0, 2, v0
	v_add3_u32 v0, v145, v84, v0
	ds_write2_b32 v0, v66, v67 offset1:36
	ds_write2_b32 v0, v68, v69 offset0:72 offset1:108
	v_add_u32_e32 v66, 0x400, v0
	ds_write2_b32 v66, v70, v71 offset0:32 offset1:68
	ds_write2_b32 v66, v72, v73 offset0:104 offset1:140
	v_add_u32_e32 v66, 0x800, v0
	v_add_u32_e32 v0, 0xc00, v0
	ds_write2_b32 v66, v74, v75 offset0:64 offset1:100
	ds_write2_b32 v66, v76, v77 offset0:136 offset1:172
	ds_write2_b32 v0, v78, v79 offset0:96 offset1:132
	ds_write2_b32 v0, v80, v81 offset0:168 offset1:204
	v_lshlrev_b32_e32 v0, 3, v86
	v_and_b32_e32 v68, 24, v0
	v_lshlrev_b32_e32 v0, 2, v68
	v_lshl_add_u64 v[66:67], v[82:83], 0, v[0:1]
	v_bfe_u32 v86, v86, 2, 4
	v_lshl_add_u64 v[84:85], v[66:67], 0, v[100:101]
	v_lshlrev_b32_e32 v66, 1, v68
	v_mul_u32_u24_e32 v68, 0x90, v86
	s_waitcnt lgkmcnt(0)
	v_add3_u32 v0, v145, v0, v68
	ds_read_b128 v[68:71], v0
	ds_read_b128 v[72:75], v0 offset:16
	global_load_dwordx4 v[76:79], v[84:85], off offset:16
	global_load_dwordx4 v[80:83], v[84:85], off
	v_or_b32_e32 v86, v86, v110
	v_mov_b32_e32 v67, v1
	v_ashrrev_i32_e32 v87, 31, v86
	v_lshl_add_u64 v[66:67], s[0:1], 0, v[66:67]
	s_waitcnt vmcnt(1) lgkmcnt(0)
	v_pk_mul_f32 v[72:73], v[72:73], v[76:77]
	s_waitcnt vmcnt(0)
	v_pk_mul_f32 v[68:69], v[68:69], v[80:81]
	v_pk_mul_f32 v[70:71], v[70:71], v[82:83]
	v_cvt_pk_bf16_f32 v68, v68, v69
	v_cvt_pk_bf16_f32 v69, v70, v71
	v_cvt_pk_bf16_f32 v70, v72, v73
	v_lshlrev_b64 v[72:73], 11, v[86:87]
	v_pk_mul_f32 v[74:75], v[74:75], v[78:79]
	v_lshl_add_u64 v[72:73], v[66:67], 0, v[72:73]
	v_cvt_pk_bf16_f32 v71, v74, v75
	v_lshl_add_u64 v[72:73], v[72:73], 0, v[98:99]
	global_store_dwordx4 v[72:73], v[68:71], off
	ds_read_b128 v[68:71], v0 offset:2304
	ds_read_b128 v[72:75], v0 offset:2320
	global_load_dwordx4 v[76:79], v[84:85], off offset:16
	global_load_dwordx4 v[80:83], v[84:85], off
	s_waitcnt vmcnt(1) lgkmcnt(0)
	v_pk_mul_f32 v[72:73], v[72:73], v[76:77]
	s_waitcnt vmcnt(0)
	v_pk_mul_f32 v[68:69], v[68:69], v[80:81]
	v_pk_mul_f32 v[70:71], v[70:71], v[82:83]
	v_cvt_pk_bf16_f32 v68, v68, v69
	v_cvt_pk_bf16_f32 v69, v70, v71
	v_cvt_pk_bf16_f32 v70, v72, v73
	v_or_b32_e32 v72, 16, v86
	v_ashrrev_i32_e32 v73, 31, v72
	v_lshlrev_b64 v[72:73], 11, v[72:73]
	v_pk_mul_f32 v[74:75], v[74:75], v[78:79]
	v_lshl_add_u64 v[66:67], v[66:67], 0, v[72:73]
	v_cvt_pk_bf16_f32 v71, v74, v75
	v_lshl_add_u64 v[66:67], v[66:67], 0, v[98:99]
	global_store_dwordx4 v[66:67], v[68:71], off
	v_or_b32_e32 v74, 64, v149
	v_mul_hi_i32 v0, v74, s2
	v_lshrrev_b32_e32 v66, 31, v0
	v_ashrrev_i32_e32 v0, 13, v0
	v_add_u32_e32 v0, v0, v66
	v_mul_i32_i24_e32 v66, 0x4100, v0
	v_sub_u32_e32 v66, v74, v66
	v_mul_i32_i24_e32 v0, 0xc00, v0
	v_cmp_lt_i32_e32 vcc, s3, v66
	v_mov_b32_e32 v68, v179
	s_nop 0
	v_cndmask_b32_e32 v66, v162, v0, vcc
	v_and_b32_e32 v0, 31, v68
	v_bfe_u32 v69, v68, 5, 1
	v_mul_u32_u24_e32 v69, 0x240, v69
	v_lshlrev_b32_e32 v0, 2, v0
	v_add3_u32 v0, v145, v69, v0
	ds_write2_b32 v0, v50, v51 offset1:36
	ds_write2_b32 v0, v52, v53 offset0:72 offset1:108
	v_add_u32_e32 v50, 0x400, v0
	v_ashrrev_i32_e32 v67, 31, v66
	ds_write2_b32 v50, v54, v55 offset0:32 offset1:68
	ds_write2_b32 v50, v56, v57 offset0:104 offset1:140
	v_add_u32_e32 v50, 0x800, v0
	v_add_u32_e32 v0, 0xc00, v0
	ds_write2_b32 v50, v58, v59 offset0:64 offset1:100
	ds_write2_b32 v50, v60, v61 offset0:136 offset1:172
	ds_write2_b32 v0, v62, v63 offset0:96 offset1:132
	ds_write2_b32 v0, v64, v65 offset0:168 offset1:204
	v_lshl_add_u64 v[50:51], v[66:67], 2, s[26:27]
	v_lshlrev_b32_e32 v0, 3, v68
	v_lshl_add_u64 v[50:51], v[50:51], 0, s[4:5]
	v_and_b32_e32 v54, 24, v0
	v_lshl_add_u64 v[52:53], v[50:51], 0, v[116:117]
	v_lshlrev_b32_e32 v0, 2, v54
	v_bfe_u32 v72, v68, 2, 4
	v_lshl_add_u64 v[70:71], v[52:53], 0, v[0:1]
	v_lshlrev_b32_e32 v52, 1, v54
	v_mul_u32_u24_e32 v54, 0x90, v72
	s_waitcnt lgkmcnt(0)
	v_add3_u32 v0, v145, v0, v54
	ds_read_b128 v[54:57], v0
	ds_read_b128 v[58:61], v0 offset:16
	global_load_dwordx4 v[62:65], v[70:71], off offset:16
	global_load_dwordx4 v[66:69], v[70:71], off
	v_or_b32_e32 v72, v72, v74
	v_mov_b32_e32 v53, v1
	v_ashrrev_i32_e32 v73, 31, v72
	v_lshl_add_u64 v[52:53], v[114:115], 0, v[52:53]
	s_waitcnt vmcnt(1) lgkmcnt(0)
	v_pk_mul_f32 v[58:59], v[58:59], v[62:63]
	s_waitcnt vmcnt(0)
	v_pk_mul_f32 v[54:55], v[54:55], v[66:67]
	v_pk_mul_f32 v[56:57], v[56:57], v[68:69]
	v_pk_mul_f32 v[60:61], v[60:61], v[64:65]
	v_cvt_pk_bf16_f32 v54, v54, v55
	v_cvt_pk_bf16_f32 v55, v56, v57
	v_cvt_pk_bf16_f32 v56, v58, v59
	v_lshlrev_b64 v[58:59], 11, v[72:73]
	v_cvt_pk_bf16_f32 v57, v60, v61
	v_lshl_add_u64 v[58:59], v[52:53], 0, v[58:59]
	global_store_dwordx4 v[58:59], v[54:57], off
	ds_read_b128 v[54:57], v0 offset:2304
	ds_read_b128 v[58:61], v0 offset:2320
	global_load_dwordx4 v[62:65], v[70:71], off offset:16
	global_load_dwordx4 v[66:69], v[70:71], off
	s_waitcnt vmcnt(1) lgkmcnt(0)
	v_pk_mul_f32 v[58:59], v[58:59], v[62:63]
	s_waitcnt vmcnt(0)
	v_pk_mul_f32 v[54:55], v[54:55], v[66:67]
	v_pk_mul_f32 v[56:57], v[56:57], v[68:69]
	v_cvt_pk_bf16_f32 v54, v54, v55
	v_cvt_pk_bf16_f32 v55, v56, v57
	v_cvt_pk_bf16_f32 v56, v58, v59
	v_or_b32_e32 v58, 16, v72
	v_ashrrev_i32_e32 v59, 31, v58
	v_pk_mul_f32 v[60:61], v[60:61], v[64:65]
	v_lshlrev_b64 v[58:59], 11, v[58:59]
	v_cvt_pk_bf16_f32 v57, v60, v61
	v_lshl_add_u64 v[52:53], v[52:53], 0, v[58:59]
	global_store_dwordx4 v[52:53], v[54:57], off
	s_nop 1
	v_mov_b32_e32 v54, v179
	s_nop 0
	v_and_b32_e32 v0, 31, v54
	v_bfe_u32 v52, v54, 5, 1
	v_mul_u32_u24_e32 v52, 0x240, v52
	v_lshlrev_b32_e32 v0, 2, v0
	v_add3_u32 v0, v145, v52, v0
	ds_write2_b32 v0, v34, v35 offset1:36
	ds_write2_b32 v0, v36, v37 offset0:72 offset1:108
	v_add_u32_e32 v34, 0x400, v0
	ds_write2_b32 v34, v38, v39 offset0:32 offset1:68
	ds_write2_b32 v34, v40, v41 offset0:104 offset1:140
	v_add_u32_e32 v34, 0x800, v0
	v_add_u32_e32 v0, 0xc00, v0
	ds_write2_b32 v34, v42, v43 offset0:64 offset1:100
	ds_write2_b32 v34, v44, v45 offset0:136 offset1:172
	ds_write2_b32 v0, v46, v47 offset0:96 offset1:132
	ds_write2_b32 v0, v48, v49 offset0:168 offset1:204
	v_lshlrev_b32_e32 v0, 3, v54
	v_and_b32_e32 v36, 24, v0
	v_lshlrev_b32_e32 v0, 2, v36
	v_lshl_add_u64 v[34:35], v[50:51], 0, v[0:1]
	v_bfe_u32 v54, v54, 2, 4
	v_lshl_add_u64 v[52:53], v[34:35], 0, v[100:101]
	v_lshlrev_b32_e32 v34, 1, v36
	v_mul_u32_u24_e32 v36, 0x90, v54
	s_waitcnt lgkmcnt(0)
	v_add3_u32 v0, v145, v0, v36
	ds_read_b128 v[36:39], v0
	ds_read_b128 v[40:43], v0 offset:16
	global_load_dwordx4 v[44:47], v[52:53], off offset:16
	global_load_dwordx4 v[48:51], v[52:53], off
	v_or_b32_e32 v54, v54, v74
	v_mov_b32_e32 v35, v1
	v_ashrrev_i32_e32 v55, 31, v54
	v_lshl_add_u64 v[34:35], s[0:1], 0, v[34:35]
	s_waitcnt vmcnt(1) lgkmcnt(0)
	v_pk_mul_f32 v[40:41], v[40:41], v[44:45]
	s_waitcnt vmcnt(0)
	v_pk_mul_f32 v[36:37], v[36:37], v[48:49]
	v_pk_mul_f32 v[38:39], v[38:39], v[50:51]
	v_cvt_pk_bf16_f32 v36, v36, v37
	v_cvt_pk_bf16_f32 v37, v38, v39
	v_cvt_pk_bf16_f32 v38, v40, v41
	v_lshlrev_b64 v[40:41], 11, v[54:55]
	v_pk_mul_f32 v[42:43], v[42:43], v[46:47]
	v_lshl_add_u64 v[40:41], v[34:35], 0, v[40:41]
	v_cvt_pk_bf16_f32 v39, v42, v43
	v_lshl_add_u64 v[40:41], v[40:41], 0, v[98:99]
	global_store_dwordx4 v[40:41], v[36:39], off
	ds_read_b128 v[36:39], v0 offset:2304
	ds_read_b128 v[40:43], v0 offset:2320
	global_load_dwordx4 v[44:47], v[52:53], off offset:16
	global_load_dwordx4 v[48:51], v[52:53], off
	s_waitcnt vmcnt(1) lgkmcnt(0)
	v_pk_mul_f32 v[40:41], v[40:41], v[44:45]
	s_waitcnt vmcnt(0)
	v_pk_mul_f32 v[36:37], v[36:37], v[48:49]
	v_pk_mul_f32 v[38:39], v[38:39], v[50:51]
	v_cvt_pk_bf16_f32 v36, v36, v37
	v_cvt_pk_bf16_f32 v37, v38, v39
	v_cvt_pk_bf16_f32 v38, v40, v41
	v_or_b32_e32 v40, 16, v54
	v_ashrrev_i32_e32 v41, 31, v40
	v_lshlrev_b64 v[40:41], 11, v[40:41]
	v_pk_mul_f32 v[42:43], v[42:43], v[46:47]
	v_lshl_add_u64 v[34:35], v[34:35], 0, v[40:41]
	v_cvt_pk_bf16_f32 v39, v42, v43
	v_lshl_add_u64 v[34:35], v[34:35], 0, v[98:99]
	global_store_dwordx4 v[34:35], v[36:39], off
	v_or_b32_e32 v42, 0x60, v149
	v_mul_hi_i32 v0, v42, s2
	v_lshrrev_b32_e32 v34, 31, v0
	v_ashrrev_i32_e32 v0, 13, v0
	v_add_u32_e32 v0, v0, v34
	v_mul_i32_i24_e32 v34, 0x4100, v0
	v_sub_u32_e32 v34, v42, v34
	v_mul_i32_i24_e32 v0, 0xc00, v0
	v_cmp_lt_i32_e32 vcc, s3, v34
	v_mov_b32_e32 v36, v179
	s_nop 0
	v_cndmask_b32_e32 v34, v162, v0, vcc
	v_and_b32_e32 v0, 31, v36
	v_bfe_u32 v37, v36, 5, 1
	v_mul_u32_u24_e32 v37, 0x240, v37
	v_lshlrev_b32_e32 v0, 2, v0
	v_add3_u32 v0, v145, v37, v0
	ds_write2_b32 v0, v18, v19 offset1:36
	ds_write2_b32 v0, v20, v21 offset0:72 offset1:108
	v_add_u32_e32 v18, 0x400, v0
	v_ashrrev_i32_e32 v35, 31, v34
	ds_write2_b32 v18, v22, v23 offset0:32 offset1:68
	ds_write2_b32 v18, v24, v25 offset0:104 offset1:140
	v_add_u32_e32 v18, 0x800, v0
	v_add_u32_e32 v0, 0xc00, v0
	ds_write2_b32 v18, v26, v27 offset0:64 offset1:100
	ds_write2_b32 v18, v28, v29 offset0:136 offset1:172
	ds_write2_b32 v0, v30, v31 offset0:96 offset1:132
	ds_write2_b32 v0, v32, v33 offset0:168 offset1:204
	v_lshl_add_u64 v[18:19], v[34:35], 2, s[26:27]
	v_lshlrev_b32_e32 v0, 3, v36
	v_lshl_add_u64 v[18:19], v[18:19], 0, s[4:5]
	v_and_b32_e32 v22, 24, v0
	v_lshl_add_u64 v[20:21], v[18:19], 0, v[116:117]
	v_lshlrev_b32_e32 v0, 2, v22
	v_bfe_u32 v40, v36, 2, 4
	v_lshl_add_u64 v[38:39], v[20:21], 0, v[0:1]
	v_lshlrev_b32_e32 v20, 1, v22
	v_mul_u32_u24_e32 v22, 0x90, v40
	s_waitcnt lgkmcnt(0)
	v_add3_u32 v0, v145, v0, v22
	ds_read_b128 v[22:25], v0
	ds_read_b128 v[26:29], v0 offset:16
	global_load_dwordx4 v[30:33], v[38:39], off offset:16
	global_load_dwordx4 v[34:37], v[38:39], off
	v_or_b32_e32 v40, v40, v42
	v_mov_b32_e32 v21, v1
	v_ashrrev_i32_e32 v41, 31, v40
	v_lshl_add_u64 v[20:21], v[114:115], 0, v[20:21]
	s_waitcnt vmcnt(1) lgkmcnt(0)
	v_pk_mul_f32 v[26:27], v[26:27], v[30:31]
	s_waitcnt vmcnt(0)
	v_pk_mul_f32 v[22:23], v[22:23], v[34:35]
	v_pk_mul_f32 v[24:25], v[24:25], v[36:37]
	v_pk_mul_f32 v[28:29], v[28:29], v[32:33]
	v_cvt_pk_bf16_f32 v22, v22, v23
	v_cvt_pk_bf16_f32 v23, v24, v25
	v_cvt_pk_bf16_f32 v24, v26, v27
	v_lshlrev_b64 v[26:27], 11, v[40:41]
	v_cvt_pk_bf16_f32 v25, v28, v29
	v_lshl_add_u64 v[26:27], v[20:21], 0, v[26:27]
	global_store_dwordx4 v[26:27], v[22:25], off
	ds_read_b128 v[22:25], v0 offset:2304
	ds_read_b128 v[26:29], v0 offset:2320
	global_load_dwordx4 v[30:33], v[38:39], off offset:16
	global_load_dwordx4 v[34:37], v[38:39], off
	s_waitcnt vmcnt(1) lgkmcnt(0)
	v_pk_mul_f32 v[26:27], v[26:27], v[30:31]
	s_waitcnt vmcnt(0)
	v_pk_mul_f32 v[22:23], v[22:23], v[34:35]
	v_pk_mul_f32 v[24:25], v[24:25], v[36:37]
	v_cvt_pk_bf16_f32 v22, v22, v23
	v_cvt_pk_bf16_f32 v23, v24, v25
	v_cvt_pk_bf16_f32 v24, v26, v27
	v_or_b32_e32 v26, 16, v40
	v_ashrrev_i32_e32 v27, 31, v26
	v_pk_mul_f32 v[28:29], v[28:29], v[32:33]
	v_lshlrev_b64 v[26:27], 11, v[26:27]
	v_cvt_pk_bf16_f32 v25, v28, v29
	v_lshl_add_u64 v[20:21], v[20:21], 0, v[26:27]
	global_store_dwordx4 v[20:21], v[22:25], off
	s_nop 1
	v_mov_b32_e32 v22, v179
	s_nop 0
	v_and_b32_e32 v0, 31, v22
	v_bfe_u32 v20, v22, 5, 1
	v_mul_u32_u24_e32 v20, 0x240, v20
	v_lshlrev_b32_e32 v0, 2, v0
	v_add3_u32 v0, v145, v20, v0
	ds_write2_b32 v0, v2, v3 offset1:36
	ds_write2_b32 v0, v4, v5 offset0:72 offset1:108
	v_add_u32_e32 v2, 0x400, v0
	ds_write2_b32 v2, v6, v7 offset0:32 offset1:68
	ds_write2_b32 v2, v8, v9 offset0:104 offset1:140
	v_add_u32_e32 v2, 0x800, v0
	v_add_u32_e32 v0, 0xc00, v0
	ds_write2_b32 v2, v10, v11 offset0:64 offset1:100
	ds_write2_b32 v2, v12, v13 offset0:136 offset1:172
	ds_write2_b32 v0, v14, v15 offset0:96 offset1:132
	ds_write2_b32 v0, v16, v17 offset0:168 offset1:204
	v_lshlrev_b32_e32 v0, 3, v22
	v_and_b32_e32 v4, 24, v0
	v_lshlrev_b32_e32 v0, 2, v4
	v_lshl_add_u64 v[2:3], v[18:19], 0, v[0:1]
	v_bfe_u32 v22, v22, 2, 4
	v_lshl_add_u64 v[20:21], v[2:3], 0, v[100:101]
	v_lshlrev_b32_e32 v2, 1, v4
	v_mul_u32_u24_e32 v4, 0x90, v22
	s_waitcnt lgkmcnt(0)
	v_add3_u32 v0, v145, v0, v4
	ds_read_b128 v[4:7], v0
	ds_read_b128 v[8:11], v0 offset:16
	global_load_dwordx4 v[12:15], v[20:21], off offset:16
	global_load_dwordx4 v[16:19], v[20:21], off
	v_or_b32_e32 v22, v22, v42
	v_mov_b32_e32 v3, v1
	v_ashrrev_i32_e32 v23, 31, v22
	v_lshl_add_u64 v[2:3], s[0:1], 0, v[2:3]
	s_waitcnt vmcnt(1) lgkmcnt(0)
	v_pk_mul_f32 v[8:9], v[8:9], v[12:13]
	s_waitcnt vmcnt(0)
	v_pk_mul_f32 v[4:5], v[4:5], v[16:17]
	v_pk_mul_f32 v[6:7], v[6:7], v[18:19]
	v_cvt_pk_bf16_f32 v4, v4, v5
	v_cvt_pk_bf16_f32 v5, v6, v7
	v_cvt_pk_bf16_f32 v6, v8, v9
	v_lshlrev_b64 v[8:9], 11, v[22:23]
	v_pk_mul_f32 v[10:11], v[10:11], v[14:15]
	v_lshl_add_u64 v[8:9], v[2:3], 0, v[8:9]
	v_cvt_pk_bf16_f32 v7, v10, v11
	v_lshl_add_u64 v[8:9], v[8:9], 0, v[98:99]
	global_store_dwordx4 v[8:9], v[4:7], off
	ds_read_b128 v[4:7], v0 offset:2304
	ds_read_b128 v[8:11], v0 offset:2320
	global_load_dwordx4 v[12:15], v[20:21], off offset:16
	global_load_dwordx4 v[16:19], v[20:21], off
	s_waitcnt vmcnt(1) lgkmcnt(0)
	v_pk_mul_f32 v[8:9], v[8:9], v[12:13]
	s_waitcnt vmcnt(0)
	v_pk_mul_f32 v[4:5], v[4:5], v[16:17]
	v_pk_mul_f32 v[6:7], v[6:7], v[18:19]
	v_cvt_pk_bf16_f32 v4, v4, v5
	v_cvt_pk_bf16_f32 v5, v6, v7
	v_cvt_pk_bf16_f32 v6, v8, v9
	v_or_b32_e32 v8, 16, v22
	v_ashrrev_i32_e32 v9, 31, v8
	v_lshlrev_b64 v[8:9], 11, v[8:9]
	v_pk_mul_f32 v[10:11], v[10:11], v[14:15]
	v_lshl_add_u64 v[2:3], v[2:3], 0, v[8:9]
	v_cvt_pk_bf16_f32 v7, v10, v11
	v_lshl_add_u64 v[2:3], v[2:3], 0, v[98:99]
	global_store_dwordx4 v[2:3], v[4:7], off
	s_add_i32 s7, s7, s6
	s_cmpk_gt_i32 s7, 0x207
	s_cselect_b64 s[0:1], -1, 0
	s_branch .LBB0_907

.Lg1122_np:
	s_add_u32 m0, s15, 0x8020
	s_add_u32 s10, s1, s2
	s_addc_u32 s11, s7, s3
	global_load_lds_dwordx4 v142, s[10:11]
	s_add_u32 m0, s15, 0xa020
	s_add_u32 s10, s10, 0x20000
	s_addc_u32 s11, s11, 0
	global_load_lds_dwordx4 v142, s[10:11]
	s_add_u32 m0, s15, 0xc020
	s_add_u32 s10, s10, 0x20000
	s_addc_u32 s11, s11, 0
	global_load_lds_dwordx4 v142, s[10:11]
	s_add_u32 m0, s15, 0xe020
	s_add_u32 s10, s10, 0x20000
	s_addc_u32 s11, s11, 0
	global_load_lds_dwordx4 v142, s[10:11]
	ds_read_b128 v[130:133], v156 offset:0
	ds_read_b128 v[148:151], v195 offset:0
	ds_read_b128 v[152:155], v195 offset:4096
	ds_read_b128 v[134:137], v156 offset:4096
	ds_read_b128 v[138:141], v156 offset:8192
	ds_read_b128 v[144:147], v156 offset:12288
.Lg1122_loop:
	s_waitcnt lgkmcnt(4)
	v_mfma_f32_32x32x16_bf16 v[114:129], v[130:133], v[148:151], v[114:129]
	ds_read_b128 v[180:183], v157 offset:0
	s_waitcnt lgkmcnt(4)
	v_mfma_f32_32x32x16_bf16 v[98:113], v[130:133], v[152:155], v[98:113]
	ds_read_b128 v[226:229], v200 offset:0
	s_add_u32 m0, s15, 0x18020
	s_add_u32 s10, s8, s2
	s_addc_u32 s11, s9, s3
	global_load_lds_dwordx4 v142, s[10:11]
	s_waitcnt lgkmcnt(4)
	v_mfma_f32_32x32x16_bf16 v[82:97], v[134:137], v[148:151], v[82:97]
	ds_read_b128 v[230:233], v200 offset:4096
	v_mfma_f32_32x32x16_bf16 v[66:81], v[134:137], v[152:155], v[66:81]
	ds_read_b128 v[184:187], v157 offset:4096
	s_add_u32 m0, s15, 0x1a020
	s_add_u32 s10, s10, 0x20000
	s_addc_u32 s11, s11, 0
	global_load_lds_dwordx4 v142, s[10:11]
	s_waitcnt lgkmcnt(5)
	v_mfma_f32_32x32x16_bf16 v[50:65], v[138:141], v[148:151], v[50:65]
	ds_read_b128 v[188:191], v157 offset:8192
	v_mfma_f32_32x32x16_bf16 v[34:49], v[138:141], v[152:155], v[34:49]
	ds_read_b128 v[222:225], v157 offset:12288
	s_add_u32 m0, s15, 0x1c020
	s_add_u32 s10, s10, 0x20000
	s_addc_u32 s11, s11, 0
	global_load_lds_dwordx4 v142, s[10:11]
	s_waitcnt lgkmcnt(6)
	v_mfma_f32_32x32x16_bf16 v[18:33], v[144:147], v[148:151], v[18:33]
	v_mfma_f32_32x32x16_bf16 v[2:17], v[144:147], v[152:155], v[2:17]
	s_add_u32 m0, s15, 0x1e020
	s_add_u32 s10, s10, 0x20000
	s_addc_u32 s11, s11, 0
	global_load_lds_dwordx4 v142, s[10:11]
	s_add_u32 s2, s2, 0x80
	s_addc_u32 s3, s3, 0
	s_waitcnt lgkmcnt(4)
	v_mfma_f32_32x32x16_bf16 v[114:129], v[180:183], v[226:229], v[114:129]
	ds_read_b128 v[130:133], v193 offset:0
	s_waitcnt lgkmcnt(4)
	v_mfma_f32_32x32x16_bf16 v[98:113], v[180:183], v[230:233], v[98:113]
	ds_read_b128 v[148:151], v201 offset:0
	s_waitcnt lgkmcnt(4)
	v_mfma_f32_32x32x16_bf16 v[82:97], v[184:187], v[226:229], v[82:97]
	ds_read_b128 v[152:155], v201 offset:4096
	v_mfma_f32_32x32x16_bf16 v[66:81], v[184:187], v[230:233], v[66:81]
	ds_read_b128 v[134:137], v193 offset:4096
	s_waitcnt lgkmcnt(5)
	v_mfma_f32_32x32x16_bf16 v[50:65], v[188:191], v[226:229], v[50:65]
	ds_read_b128 v[138:141], v193 offset:8192
	v_mfma_f32_32x32x16_bf16 v[34:49], v[188:191], v[230:233], v[34:49]
	ds_read_b128 v[144:147], v193 offset:12288
	s_waitcnt lgkmcnt(6)
	v_mfma_f32_32x32x16_bf16 v[18:33], v[222:225], v[226:229], v[18:33]
	v_mfma_f32_32x32x16_bf16 v[2:17], v[222:225], v[230:233], v[2:17]
	s_waitcnt lgkmcnt(4)
	v_mfma_f32_32x32x16_bf16 v[114:129], v[130:133], v[148:151], v[114:129]
	ds_read_b128 v[180:183], v194 offset:0
	ds_read_b128 v[226:229], v202 offset:0
	s_waitcnt lgkmcnt(5)
	v_mfma_f32_32x32x16_bf16 v[98:113], v[130:133], v[152:155], v[98:113]
	ds_read_b128 v[230:233], v202 offset:4096
	ds_read_b128 v[184:187], v194 offset:4096
	s_waitcnt lgkmcnt(6)
	v_mfma_f32_32x32x16_bf16 v[82:97], v[134:137], v[148:151], v[82:97]
	ds_read_b128 v[188:191], v194 offset:8192
	ds_read_b128 v[222:225], v194 offset:12288
	v_mfma_f32_32x32x16_bf16 v[66:81], v[134:137], v[152:155], v[66:81]
	s_waitcnt lgkmcnt(7)
	v_mfma_f32_32x32x16_bf16 v[50:65], v[138:141], v[148:151], v[50:65]
	v_mfma_f32_32x32x16_bf16 v[34:49], v[138:141], v[152:155], v[34:49]
	s_waitcnt lgkmcnt(6)
	v_mfma_f32_32x32x16_bf16 v[18:33], v[144:147], v[148:151], v[18:33]
	v_mfma_f32_32x32x16_bf16 v[2:17], v[144:147], v[152:155], v[2:17]
	s_waitcnt vmcnt(0) lgkmcnt(0)
	s_barrier
	v_mfma_f32_32x32x16_bf16 v[114:129], v[180:183], v[226:229], v[114:129]
	ds_read_b128 v[130:133], v156 offset:32768
	v_mfma_f32_32x32x16_bf16 v[98:113], v[180:183], v[230:233], v[98:113]
	ds_read_b128 v[148:151], v195 offset:32768
	s_add_u32 m0, s15, 0x20
	s_add_u32 s10, s1, s2
	s_addc_u32 s11, s7, s3
	global_load_lds_dwordx4 v142, s[10:11]
	v_mfma_f32_32x32x16_bf16 v[82:97], v[184:187], v[226:229], v[82:97]
	ds_read_b128 v[152:155], v195 offset:36864
	v_mfma_f32_32x32x16_bf16 v[66:81], v[184:187], v[230:233], v[66:81]
	ds_read_b128 v[134:137], v156 offset:36864
	s_add_u32 m0, s15, 0x2020
	s_add_u32 s10, s10, 0x20000
	s_addc_u32 s11, s11, 0
	global_load_lds_dwordx4 v142, s[10:11]
	v_mfma_f32_32x32x16_bf16 v[50:65], v[188:191], v[226:229], v[50:65]
	ds_read_b128 v[138:141], v156 offset:40960
	v_mfma_f32_32x32x16_bf16 v[34:49], v[188:191], v[230:233], v[34:49]
	ds_read_b128 v[144:147], v156 offset:45056
	s_add_u32 m0, s15, 0x4020
	s_add_u32 s10, s10, 0x20000
	s_addc_u32 s11, s11, 0
	global_load_lds_dwordx4 v142, s[10:11]
	v_mfma_f32_32x32x16_bf16 v[18:33], v[222:225], v[226:229], v[18:33]
	v_mfma_f32_32x32x16_bf16 v[2:17], v[222:225], v[230:233], v[2:17]
	s_add_u32 m0, s15, 0x6020
	s_add_u32 s10, s10, 0x20000
	s_addc_u32 s11, s11, 0
	global_load_lds_dwordx4 v142, s[10:11]
	s_waitcnt lgkmcnt(4)
	v_mfma_f32_32x32x16_bf16 v[114:129], v[130:133], v[148:151], v[114:129]
	ds_read_b128 v[180:183], v157 offset:32768
	s_waitcnt lgkmcnt(4)
	v_mfma_f32_32x32x16_bf16 v[98:113], v[130:133], v[152:155], v[98:113]
	ds_read_b128 v[226:229], v200 offset:32768
	s_add_u32 m0, s15, 0x10020
	s_add_u32 s10, s8, s2
	s_addc_u32 s11, s9, s3
	global_load_lds_dwordx4 v142, s[10:11]
	s_waitcnt lgkmcnt(4)
	v_mfma_f32_32x32x16_bf16 v[82:97], v[134:137], v[148:151], v[82:97]
	ds_read_b128 v[230:233], v200 offset:36864
	v_mfma_f32_32x32x16_bf16 v[66:81], v[134:137], v[152:155], v[66:81]
	ds_read_b128 v[184:187], v157 offset:36864
	s_add_u32 m0, s15, 0x12020
	s_add_u32 s10, s10, 0x20000
	s_addc_u32 s11, s11, 0
	global_load_lds_dwordx4 v142, s[10:11]
	s_waitcnt lgkmcnt(5)
	v_mfma_f32_32x32x16_bf16 v[50:65], v[138:141], v[148:151], v[50:65]
	ds_read_b128 v[188:191], v157 offset:40960
	v_mfma_f32_32x32x16_bf16 v[34:49], v[138:141], v[152:155], v[34:49]
	ds_read_b128 v[222:225], v157 offset:45056
	s_add_u32 m0, s15, 0x14020
	s_add_u32 s10, s10, 0x20000
	s_addc_u32 s11, s11, 0
	global_load_lds_dwordx4 v142, s[10:11]
	s_waitcnt lgkmcnt(6)
	v_mfma_f32_32x32x16_bf16 v[18:33], v[144:147], v[148:151], v[18:33]
	v_mfma_f32_32x32x16_bf16 v[2:17], v[144:147], v[152:155], v[2:17]
	s_add_u32 m0, s15, 0x16020
	s_add_u32 s10, s10, 0x20000
	s_addc_u32 s11, s11, 0
	global_load_lds_dwordx4 v142, s[10:11]
	s_add_u32 s2, s2, 0x80
	s_addc_u32 s3, s3, 0
	s_waitcnt lgkmcnt(4)
	v_mfma_f32_32x32x16_bf16 v[114:129], v[180:183], v[226:229], v[114:129]
	ds_read_b128 v[130:133], v193 offset:32768
	s_waitcnt lgkmcnt(4)
	v_mfma_f32_32x32x16_bf16 v[98:113], v[180:183], v[230:233], v[98:113]
	ds_read_b128 v[148:151], v201 offset:32768
	s_waitcnt lgkmcnt(4)
	v_mfma_f32_32x32x16_bf16 v[82:97], v[184:187], v[226:229], v[82:97]
	ds_read_b128 v[152:155], v201 offset:36864
	v_mfma_f32_32x32x16_bf16 v[66:81], v[184:187], v[230:233], v[66:81]
	ds_read_b128 v[134:137], v193 offset:36864
	s_waitcnt lgkmcnt(5)
	v_mfma_f32_32x32x16_bf16 v[50:65], v[188:191], v[226:229], v[50:65]
	ds_read_b128 v[138:141], v193 offset:40960
	v_mfma_f32_32x32x16_bf16 v[34:49], v[188:191], v[230:233], v[34:49]
	ds_read_b128 v[144:147], v193 offset:45056
	s_waitcnt lgkmcnt(6)
	v_mfma_f32_32x32x16_bf16 v[18:33], v[222:225], v[226:229], v[18:33]
	v_mfma_f32_32x32x16_bf16 v[2:17], v[222:225], v[230:233], v[2:17]
	s_waitcnt lgkmcnt(4)
	v_mfma_f32_32x32x16_bf16 v[114:129], v[130:133], v[148:151], v[114:129]
	ds_read_b128 v[180:183], v194 offset:32768
	ds_read_b128 v[226:229], v202 offset:32768
	s_waitcnt lgkmcnt(5)
	v_mfma_f32_32x32x16_bf16 v[98:113], v[130:133], v[152:155], v[98:113]
	ds_read_b128 v[230:233], v202 offset:36864
	ds_read_b128 v[184:187], v194 offset:36864
	s_waitcnt lgkmcnt(6)
	v_mfma_f32_32x32x16_bf16 v[82:97], v[134:137], v[148:151], v[82:97]
	ds_read_b128 v[188:191], v194 offset:40960
	ds_read_b128 v[222:225], v194 offset:45056
	v_mfma_f32_32x32x16_bf16 v[66:81], v[134:137], v[152:155], v[66:81]
	s_waitcnt lgkmcnt(7)
	v_mfma_f32_32x32x16_bf16 v[50:65], v[138:141], v[148:151], v[50:65]
	v_mfma_f32_32x32x16_bf16 v[34:49], v[138:141], v[152:155], v[34:49]
	s_waitcnt lgkmcnt(6)
	v_mfma_f32_32x32x16_bf16 v[18:33], v[144:147], v[148:151], v[18:33]
	v_mfma_f32_32x32x16_bf16 v[2:17], v[144:147], v[152:155], v[2:17]
	s_waitcnt vmcnt(0) lgkmcnt(0)
	s_barrier
	v_mfma_f32_32x32x16_bf16 v[114:129], v[180:183], v[226:229], v[114:129]
	ds_read_b128 v[130:133], v156 offset:0
	v_mfma_f32_32x32x16_bf16 v[98:113], v[180:183], v[230:233], v[98:113]
	ds_read_b128 v[148:151], v195 offset:0
	s_add_u32 m0, s15, 0x8020
	s_add_u32 s10, s1, s2
	s_addc_u32 s11, s7, s3
	global_load_lds_dwordx4 v142, s[10:11]
	v_mfma_f32_32x32x16_bf16 v[82:97], v[184:187], v[226:229], v[82:97]
	ds_read_b128 v[152:155], v195 offset:4096
	v_mfma_f32_32x32x16_bf16 v[66:81], v[184:187], v[230:233], v[66:81]
	ds_read_b128 v[134:137], v156 offset:4096
	s_add_u32 m0, s15, 0xa020
	s_add_u32 s10, s10, 0x20000
	s_addc_u32 s11, s11, 0
	global_load_lds_dwordx4 v142, s[10:11]
	v_mfma_f32_32x32x16_bf16 v[50:65], v[188:191], v[226:229], v[50:65]
	ds_read_b128 v[138:141], v156 offset:8192
	v_mfma_f32_32x32x16_bf16 v[34:49], v[188:191], v[230:233], v[34:49]
	ds_read_b128 v[144:147], v156 offset:12288
	s_add_u32 m0, s15, 0xc020
	s_add_u32 s10, s10, 0x20000
	s_addc_u32 s11, s11, 0
	global_load_lds_dwordx4 v142, s[10:11]
	v_mfma_f32_32x32x16_bf16 v[18:33], v[222:225], v[226:229], v[18:33]
	v_mfma_f32_32x32x16_bf16 v[2:17], v[222:225], v[230:233], v[2:17]
	s_add_u32 m0, s15, 0xe020
	s_add_u32 s10, s10, 0x20000
	s_addc_u32 s11, s11, 0
	global_load_lds_dwordx4 v142, s[10:11]
	s_sub_u32 s5, s5, 1
	s_cmp_lg_u32 s5, 0
	s_cbranch_scc1 .Lg1122_loop
	s_waitcnt lgkmcnt(4)
	v_mfma_f32_32x32x16_bf16 v[114:129], v[130:133], v[148:151], v[114:129]
	ds_read_b128 v[180:183], v157 offset:0
	s_waitcnt lgkmcnt(4)
	v_mfma_f32_32x32x16_bf16 v[98:113], v[130:133], v[152:155], v[98:113]
	ds_read_b128 v[226:229], v200 offset:0
	s_add_u32 m0, s15, 0x18020
	s_add_u32 s10, s8, s2
	s_addc_u32 s11, s9, s3
	global_load_lds_dwordx4 v142, s[10:11]
	s_waitcnt lgkmcnt(4)
	v_mfma_f32_32x32x16_bf16 v[82:97], v[134:137], v[148:151], v[82:97]
	ds_read_b128 v[230:233], v200 offset:4096
	v_mfma_f32_32x32x16_bf16 v[66:81], v[134:137], v[152:155], v[66:81]
	ds_read_b128 v[184:187], v157 offset:4096
	s_add_u32 m0, s15, 0x1a020
	s_add_u32 s10, s10, 0x20000
	s_addc_u32 s11, s11, 0
	global_load_lds_dwordx4 v142, s[10:11]
	s_waitcnt lgkmcnt(5)
	v_mfma_f32_32x32x16_bf16 v[50:65], v[138:141], v[148:151], v[50:65]
	ds_read_b128 v[188:191], v157 offset:8192
	v_mfma_f32_32x32x16_bf16 v[34:49], v[138:141], v[152:155], v[34:49]
	ds_read_b128 v[222:225], v157 offset:12288
	s_add_u32 m0, s15, 0x1c020
	s_add_u32 s10, s10, 0x20000
	s_addc_u32 s11, s11, 0
	global_load_lds_dwordx4 v142, s[10:11]
	s_waitcnt lgkmcnt(6)
	v_mfma_f32_32x32x16_bf16 v[18:33], v[144:147], v[148:151], v[18:33]
	v_mfma_f32_32x32x16_bf16 v[2:17], v[144:147], v[152:155], v[2:17]
	s_add_u32 m0, s15, 0x1e020
	s_add_u32 s10, s10, 0x20000
	s_addc_u32 s11, s11, 0
	global_load_lds_dwordx4 v142, s[10:11]
	s_add_u32 s2, s2, 0x80
	s_addc_u32 s3, s3, 0
	s_waitcnt lgkmcnt(4)
	v_mfma_f32_32x32x16_bf16 v[114:129], v[180:183], v[226:229], v[114:129]
	ds_read_b128 v[130:133], v193 offset:0
	s_waitcnt lgkmcnt(4)
	v_mfma_f32_32x32x16_bf16 v[98:113], v[180:183], v[230:233], v[98:113]
	ds_read_b128 v[148:151], v201 offset:0
	s_waitcnt lgkmcnt(4)
	v_mfma_f32_32x32x16_bf16 v[82:97], v[184:187], v[226:229], v[82:97]
	ds_read_b128 v[152:155], v201 offset:4096
	v_mfma_f32_32x32x16_bf16 v[66:81], v[184:187], v[230:233], v[66:81]
	ds_read_b128 v[134:137], v193 offset:4096
	s_waitcnt lgkmcnt(5)
	v_mfma_f32_32x32x16_bf16 v[50:65], v[188:191], v[226:229], v[50:65]
	ds_read_b128 v[138:141], v193 offset:8192
	v_mfma_f32_32x32x16_bf16 v[34:49], v[188:191], v[230:233], v[34:49]
	ds_read_b128 v[144:147], v193 offset:12288
	s_waitcnt lgkmcnt(6)
	v_mfma_f32_32x32x16_bf16 v[18:33], v[222:225], v[226:229], v[18:33]
	v_mfma_f32_32x32x16_bf16 v[2:17], v[222:225], v[230:233], v[2:17]
	s_waitcnt lgkmcnt(4)
	v_mfma_f32_32x32x16_bf16 v[114:129], v[130:133], v[148:151], v[114:129]
	ds_read_b128 v[180:183], v194 offset:0
	ds_read_b128 v[226:229], v202 offset:0
	s_waitcnt lgkmcnt(5)
	v_mfma_f32_32x32x16_bf16 v[98:113], v[130:133], v[152:155], v[98:113]
	ds_read_b128 v[230:233], v202 offset:4096
	ds_read_b128 v[184:187], v194 offset:4096
	s_waitcnt lgkmcnt(6)
	v_mfma_f32_32x32x16_bf16 v[82:97], v[134:137], v[148:151], v[82:97]
	ds_read_b128 v[188:191], v194 offset:8192
	ds_read_b128 v[222:225], v194 offset:12288
	v_mfma_f32_32x32x16_bf16 v[66:81], v[134:137], v[152:155], v[66:81]
	s_waitcnt lgkmcnt(7)
	v_mfma_f32_32x32x16_bf16 v[50:65], v[138:141], v[148:151], v[50:65]
	v_mfma_f32_32x32x16_bf16 v[34:49], v[138:141], v[152:155], v[34:49]
	s_waitcnt lgkmcnt(6)
	v_mfma_f32_32x32x16_bf16 v[18:33], v[144:147], v[148:151], v[18:33]
	v_mfma_f32_32x32x16_bf16 v[2:17], v[144:147], v[152:155], v[2:17]
	s_waitcnt vmcnt(0) lgkmcnt(0)
	s_barrier
	v_mfma_f32_32x32x16_bf16 v[114:129], v[180:183], v[226:229], v[114:129]
	ds_read_b128 v[130:133], v156 offset:32768
	v_mfma_f32_32x32x16_bf16 v[98:113], v[180:183], v[230:233], v[98:113]
	ds_read_b128 v[148:151], v195 offset:32768
	v_mfma_f32_32x32x16_bf16 v[82:97], v[184:187], v[226:229], v[82:97]
	ds_read_b128 v[152:155], v195 offset:36864
	v_mfma_f32_32x32x16_bf16 v[66:81], v[184:187], v[230:233], v[66:81]
	ds_read_b128 v[134:137], v156 offset:36864
	v_mfma_f32_32x32x16_bf16 v[50:65], v[188:191], v[226:229], v[50:65]
	ds_read_b128 v[138:141], v156 offset:40960
	v_mfma_f32_32x32x16_bf16 v[34:49], v[188:191], v[230:233], v[34:49]
	ds_read_b128 v[144:147], v156 offset:45056
	v_mfma_f32_32x32x16_bf16 v[18:33], v[222:225], v[226:229], v[18:33]
	v_mfma_f32_32x32x16_bf16 v[2:17], v[222:225], v[230:233], v[2:17]
	s_waitcnt lgkmcnt(4)
	v_mfma_f32_32x32x16_bf16 v[114:129], v[130:133], v[148:151], v[114:129]
	ds_read_b128 v[180:183], v157 offset:32768
	s_waitcnt lgkmcnt(4)
	v_mfma_f32_32x32x16_bf16 v[98:113], v[130:133], v[152:155], v[98:113]
	ds_read_b128 v[226:229], v200 offset:32768
	s_waitcnt lgkmcnt(4)
	v_mfma_f32_32x32x16_bf16 v[82:97], v[134:137], v[148:151], v[82:97]
	ds_read_b128 v[230:233], v200 offset:36864
	v_mfma_f32_32x32x16_bf16 v[66:81], v[134:137], v[152:155], v[66:81]
	ds_read_b128 v[184:187], v157 offset:36864
	s_waitcnt lgkmcnt(5)
	v_mfma_f32_32x32x16_bf16 v[50:65], v[138:141], v[148:151], v[50:65]
	ds_read_b128 v[188:191], v157 offset:40960
	v_mfma_f32_32x32x16_bf16 v[34:49], v[138:141], v[152:155], v[34:49]
	ds_read_b128 v[222:225], v157 offset:45056
	s_waitcnt lgkmcnt(6)
	v_mfma_f32_32x32x16_bf16 v[18:33], v[144:147], v[148:151], v[18:33]
	v_mfma_f32_32x32x16_bf16 v[2:17], v[144:147], v[152:155], v[2:17]
	s_waitcnt lgkmcnt(4)
	v_mfma_f32_32x32x16_bf16 v[114:129], v[180:183], v[226:229], v[114:129]
	ds_read_b128 v[130:133], v193 offset:32768
	s_waitcnt lgkmcnt(4)
	v_mfma_f32_32x32x16_bf16 v[98:113], v[180:183], v[230:233], v[98:113]
	ds_read_b128 v[148:151], v201 offset:32768
	s_waitcnt lgkmcnt(4)
	v_mfma_f32_32x32x16_bf16 v[82:97], v[184:187], v[226:229], v[82:97]
	ds_read_b128 v[152:155], v201 offset:36864
	v_mfma_f32_32x32x16_bf16 v[66:81], v[184:187], v[230:233], v[66:81]
	ds_read_b128 v[134:137], v193 offset:36864
	s_waitcnt lgkmcnt(5)
	v_mfma_f32_32x32x16_bf16 v[50:65], v[188:191], v[226:229], v[50:65]
	ds_read_b128 v[138:141], v193 offset:40960
	v_mfma_f32_32x32x16_bf16 v[34:49], v[188:191], v[230:233], v[34:49]
	ds_read_b128 v[144:147], v193 offset:45056
	s_waitcnt lgkmcnt(6)
	v_mfma_f32_32x32x16_bf16 v[18:33], v[222:225], v[226:229], v[18:33]
	v_mfma_f32_32x32x16_bf16 v[2:17], v[222:225], v[230:233], v[2:17]
	s_waitcnt lgkmcnt(4)
	v_mfma_f32_32x32x16_bf16 v[114:129], v[130:133], v[148:151], v[114:129]
	ds_read_b128 v[180:183], v194 offset:32768
	ds_read_b128 v[226:229], v202 offset:32768
	s_waitcnt lgkmcnt(5)
	v_mfma_f32_32x32x16_bf16 v[98:113], v[130:133], v[152:155], v[98:113]
	ds_read_b128 v[230:233], v202 offset:36864
	ds_read_b128 v[184:187], v194 offset:36864
	s_waitcnt lgkmcnt(6)
	v_mfma_f32_32x32x16_bf16 v[82:97], v[134:137], v[148:151], v[82:97]
	ds_read_b128 v[188:191], v194 offset:40960
	ds_read_b128 v[222:225], v194 offset:45056
	v_mfma_f32_32x32x16_bf16 v[66:81], v[134:137], v[152:155], v[66:81]
	s_waitcnt lgkmcnt(7)
	v_mfma_f32_32x32x16_bf16 v[50:65], v[138:141], v[148:151], v[50:65]
	v_mfma_f32_32x32x16_bf16 v[34:49], v[138:141], v[152:155], v[34:49]
	s_waitcnt lgkmcnt(6)
	v_mfma_f32_32x32x16_bf16 v[18:33], v[144:147], v[148:151], v[18:33]
	v_mfma_f32_32x32x16_bf16 v[2:17], v[144:147], v[152:155], v[2:17]
	s_waitcnt vmcnt(0) lgkmcnt(0)
	s_barrier
	v_mfma_f32_32x32x16_bf16 v[114:129], v[180:183], v[226:229], v[114:129]
	v_mfma_f32_32x32x16_bf16 v[98:113], v[180:183], v[230:233], v[98:113]
	v_mfma_f32_32x32x16_bf16 v[82:97], v[184:187], v[226:229], v[82:97]
	v_mfma_f32_32x32x16_bf16 v[66:81], v[184:187], v[230:233], v[66:81]
	v_mfma_f32_32x32x16_bf16 v[50:65], v[188:191], v[226:229], v[50:65]
	v_mfma_f32_32x32x16_bf16 v[34:49], v[188:191], v[230:233], v[34:49]
	v_mfma_f32_32x32x16_bf16 v[18:33], v[222:225], v[226:229], v[18:33]
	v_mfma_f32_32x32x16_bf16 v[2:17], v[222:225], v[230:233], v[2:17]
	s_setprio 0
	v_add_u32_e32 v180, s0, v168
	s_and_b32 s0, s4, 0x7ffffe
	s_mov_b32 s4, 0x7e07e07f
	v_mul_hi_i32 v0, v180, s4
	v_lshrrev_b32_e32 v130, 31, v0
	v_ashrrev_i32_e32 v0, 13, v0
	s_cmp_eq_u32 s0, 12
	v_add_u32_e32 v182, v0, v130
	s_waitcnt vmcnt(0)
	s_cselect_b64 s[2:3], -1, 0
	s_cmp_lg_u32 s0, 12
	v_mul_i32_i24_e32 v0, 0x4100, v182
	v_or_b32_e32 v138, s6, v169
	s_movk_i32 s4, 0x5ff
	s_cselect_b64 s[0:1], -1, 0
	v_sub_u32_e32 v140, v180, v0
	v_mov_b32_e32 v184, v179
	v_cmp_lt_i32_e64 s[52:53], s4, v138
	s_barrier
	v_lshl_or_b32 v181, v182, 3, v171
	v_ashrrev_i32_e32 v141, 31, v140
	s_and_b64 s[10:11], s[0:1], s[52:53]
	v_and_b32_e32 v183, 63, v184
	v_and_b32_e32 v0, 31, v184
	v_bfe_u32 v133, v184, 5, 1
	s_and_saveexec_b64 s[0:1], s[10:11]
	s_xor_b64 s[8:9], exec, s[0:1]
	s_cbranch_execz .LBB0_1136
	s_add_i32 s4, s6, 0xfffff200
	v_mul_u32_u24_e32 v130, 0x90, v133
	s_mov_b64 s[0:1], -1
	s_cmp_gt_u32 s4, 0xfffff9ff
	v_lshlrev_b32_e32 v139, 2, v0
	v_lshlrev_b32_e32 v185, 2, v130
	s_cbranch_scc0 .LBB0_1134
	v_add3_u32 v0, v170, v185, v139
	ds_write_b32 v0, v114
	v_add3_u32 v0, v170, v139, v185
	v_add_u32_e32 v130, 0x100, v0
	ds_write2_b32 v130, v117, v118 offset0:44 offset1:224
	v_add_u32_e32 v130, 0x400, v0
	ds_write2_b32 v130, v119, v120 offset0:68 offset1:104
	v_add_u32_e32 v130, 0x600, v0
	ds_write2_b32 v130, v121, v122 offset0:12 offset1:192
	v_add_u32_e32 v130, 0x800, v0
	ds_write2_b32 v130, v123, v124 offset0:100 offset1:136
	v_add_u32_e32 v130, 0xa00, v0
	ds_write2_b32 v130, v125, v126 offset0:44 offset1:224
	v_add_u32_e32 v130, 0xc00, v0
	s_cmpk_lt_u32 s6, 0xa00
	ds_write2_b32 v0, v115, v116 offset0:36 offset1:72
	ds_write2_b32 v130, v127, v128 offset0:132 offset1:168
	ds_write_b32 v0, v129 offset:3888
	s_cselect_b64 s[0:1], -1, 0
	v_mov_b32_e32 v0, 0x3e38aa3b
	v_cndmask_b32_e64 v142, 1.0, v0, s[0:1]
	v_lshlrev_b32_e32 v0, 3, v184
	v_lshrrev_b32_e32 v188, 2, v183
	s_movk_i32 s4, 0x90
	v_and_b32_e32 v187, 24, v0
	v_mad_u32_u24 v147, v188, s4, v170
	s_waitcnt lgkmcnt(0)
	v_lshl_add_u32 v130, v187, 2, v147
	ds_read_b128 v[134:137], v130
	ds_read_b128 v[130:133], v130 offset:16
	v_and_b32_e32 v144, 2, v184
	v_or_b32_e32 v150, v188, v140
	s_movk_i32 s4, 0x100
	v_cmp_eq_u32_e32 vcc, 0, v144
	v_cmp_gt_i32_e64 s[4:5], s4, v150
	s_and_saveexec_b64 s[16:17], s[4:5]
	s_xor_b64 s[4:5], exec, s[16:17]
	s_cbranch_execz .LBB0_1127
	s_waitcnt lgkmcnt(1)
	v_pk_mul_f32 v[152:153], v[142:143], v[134:135] op_sel_hi:[0,1]
	v_pk_mul_f32 v[154:155], v[142:143], v[136:137] op_sel_hi:[0,1]
	s_waitcnt lgkmcnt(0)
	v_pk_mul_f32 v[156:157], v[142:143], v[130:131] op_sel_hi:[0,1]
	v_mul_f32_e32 v145, v142, v132
